# v040 plus adaLN GEMV fully unrolled with a 60-load ring (15 iterations in flight instead of 8)
# speedup vs baseline: 1.0063x; 1.0055x over previous
.LBB0_16:
	s_mul_hi_i32 s6, s18, 0x2aaaaaab
	s_lshr_b32 s7, s6, 31
	s_ashr_i32 s19, s6, 4
	s_add_i32 s19, s19, s7
	s_mul_i32 s6, s19, 0x60
	s_sub_i32 s6, s18, s6
	s_lshl_b32 s22, s6, 6
	s_ashr_i32 s23, s22, 31
	s_mul_i32 s21, s19, 0x3000000
	s_lshl_b64 s[6:7], s[22:23], 2
	s_mul_hi_i32 s20, s19, 0x3000000
	s_add_u32 s6, s21, s6
	s_addc_u32 s7, s20, s7
	v_mov_b32_e32 v8, 0
	v_lshl_add_u64 v[10:11], v[6:7], 0, s[6:7]
	s_mov_b32 s20, 0
	v_mov_b32_e32 v12, 0
	v_mov_b32_e32 v13, v8
	v_mov_b32_e32 v14, 0
	v_mov_b32_e32 v15, v8
	v_mov_b32_e32 v16, 0
	v_mov_b32_e32 v17, v8
	v_mov_b32_e32 v18, 0
	v_mov_b32_e32 v19, v8
	s_add_u32 s24, s70, s6
	s_addc_u32 s25, s71, s7
	s_add_u32 s26, s24, 0x12000
	v_subrev_u32_e32 v200, s26, v10
	global_load_dword v78, v200, s[24:25]
	s_add_u32 s24, s24, 0x6000
	s_addc_u32 s25, s25, 0
	global_load_dword v80, v200, s[24:25]
	s_add_u32 s24, s24, 0x6000
	s_addc_u32 s25, s25, 0
	global_load_dword v82, v200, s[24:25]
	s_add_u32 s24, s24, 0x6000
	s_addc_u32 s25, s25, 0
	global_load_dword v84, v200, s[24:25]
	s_add_u32 s24, s24, 0x6000
	s_addc_u32 s25, s25, 0
	global_load_dword v86, v200, s[24:25]
	s_add_u32 s24, s24, 0x6000
	s_addc_u32 s25, s25, 0
	global_load_dword v88, v200, s[24:25]
	s_add_u32 s24, s24, 0x6000
	s_addc_u32 s25, s25, 0
	global_load_dword v90, v200, s[24:25]
	s_add_u32 s24, s24, 0x6000
	s_addc_u32 s25, s25, 0
	global_load_dword v92, v200, s[24:25]
	s_add_u32 s24, s24, 0x6000
	s_addc_u32 s25, s25, 0
	global_load_dword v94, v200, s[24:25]
	s_add_u32 s24, s24, 0x6000
	s_addc_u32 s25, s25, 0
	global_load_dword v96, v200, s[24:25]
	s_add_u32 s24, s24, 0x6000
	s_addc_u32 s25, s25, 0
	global_load_dword v98, v200, s[24:25]
	s_add_u32 s24, s24, 0x6000
	s_addc_u32 s25, s25, 0
	global_load_dword v100, v200, s[24:25]
	s_add_u32 s24, s24, 0x6000
	s_addc_u32 s25, s25, 0
	global_load_dword v102, v200, s[24:25]
	s_add_u32 s24, s24, 0x6000
	s_addc_u32 s25, s25, 0
	global_load_dword v104, v200, s[24:25]
	s_add_u32 s24, s24, 0x6000
	s_addc_u32 s25, s25, 0
	global_load_dword v106, v200, s[24:25]
	s_add_u32 s24, s24, 0x6000
	s_addc_u32 s25, s25, 0
	global_load_dword v108, v200, s[24:25]
	s_add_u32 s24, s24, 0x6000
	s_addc_u32 s25, s25, 0
	global_load_dword v110, v200, s[24:25]
	s_add_u32 s24, s24, 0x6000
	s_addc_u32 s25, s25, 0
	global_load_dword v112, v200, s[24:25]
	s_add_u32 s24, s24, 0x6000
	s_addc_u32 s25, s25, 0
	global_load_dword v114, v200, s[24:25]
	s_add_u32 s24, s24, 0x6000
	s_addc_u32 s25, s25, 0
	global_load_dword v116, v200, s[24:25]
	s_add_u32 s24, s24, 0x6000
	s_addc_u32 s25, s25, 0
	global_load_dword v118, v200, s[24:25]
	s_add_u32 s24, s24, 0x6000
	s_addc_u32 s25, s25, 0
	global_load_dword v120, v200, s[24:25]
	s_add_u32 s24, s24, 0x6000
	s_addc_u32 s25, s25, 0
	global_load_dword v122, v200, s[24:25]
	s_add_u32 s24, s24, 0x6000
	s_addc_u32 s25, s25, 0
	global_load_dword v124, v200, s[24:25]
	s_add_u32 s24, s24, 0x6000
	s_addc_u32 s25, s25, 0
	global_load_dword v126, v200, s[24:25]
	s_add_u32 s24, s24, 0x6000
	s_addc_u32 s25, s25, 0
	global_load_dword v128, v200, s[24:25]
	s_add_u32 s24, s24, 0x6000
	s_addc_u32 s25, s25, 0
	global_load_dword v130, v200, s[24:25]
	s_add_u32 s24, s24, 0x6000
	s_addc_u32 s25, s25, 0
	global_load_dword v132, v200, s[24:25]
	s_add_u32 s24, s24, 0x6000
	s_addc_u32 s25, s25, 0
	global_load_dword v134, v200, s[24:25]
	s_add_u32 s24, s24, 0x6000
	s_addc_u32 s25, s25, 0
	global_load_dword v136, v200, s[24:25]
	s_add_u32 s24, s24, 0x6000
	s_addc_u32 s25, s25, 0
	global_load_dword v138, v200, s[24:25]
	s_add_u32 s24, s24, 0x6000
	s_addc_u32 s25, s25, 0
	global_load_dword v140, v200, s[24:25]
	s_add_u32 s24, s24, 0x6000
	s_addc_u32 s25, s25, 0
	global_load_dword v142, v200, s[24:25]
	s_add_u32 s24, s24, 0x6000
	s_addc_u32 s25, s25, 0
	global_load_dword v144, v200, s[24:25]
	s_add_u32 s24, s24, 0x6000
	s_addc_u32 s25, s25, 0
	global_load_dword v146, v200, s[24:25]
	s_add_u32 s24, s24, 0x6000
	s_addc_u32 s25, s25, 0
	global_load_dword v148, v200, s[24:25]
	s_add_u32 s24, s24, 0x6000
	s_addc_u32 s25, s25, 0
	global_load_dword v150, v200, s[24:25]
	s_add_u32 s24, s24, 0x6000
	s_addc_u32 s25, s25, 0
	global_load_dword v152, v200, s[24:25]
	s_add_u32 s24, s24, 0x6000
	s_addc_u32 s25, s25, 0
	global_load_dword v154, v200, s[24:25]
	s_add_u32 s24, s24, 0x6000
	s_addc_u32 s25, s25, 0
	global_load_dword v156, v200, s[24:25]
	s_add_u32 s24, s24, 0x6000
	s_addc_u32 s25, s25, 0
	global_load_dword v158, v200, s[24:25]
	s_add_u32 s24, s24, 0x6000
	s_addc_u32 s25, s25, 0
	global_load_dword v160, v200, s[24:25]
	s_add_u32 s24, s24, 0x6000
	s_addc_u32 s25, s25, 0
	global_load_dword v162, v200, s[24:25]
	s_add_u32 s24, s24, 0x6000
	s_addc_u32 s25, s25, 0
	global_load_dword v164, v200, s[24:25]
	s_add_u32 s24, s24, 0x6000
	s_addc_u32 s25, s25, 0
	global_load_dword v166, v200, s[24:25]
	s_add_u32 s24, s24, 0x6000
	s_addc_u32 s25, s25, 0
	global_load_dword v168, v200, s[24:25]
	s_add_u32 s24, s24, 0x6000
	s_addc_u32 s25, s25, 0
	global_load_dword v170, v200, s[24:25]
	s_add_u32 s24, s24, 0x6000
	s_addc_u32 s25, s25, 0
	global_load_dword v172, v200, s[24:25]
	s_add_u32 s24, s24, 0x6000
	s_addc_u32 s25, s25, 0
	global_load_dword v174, v200, s[24:25]
	s_add_u32 s24, s24, 0x6000
	s_addc_u32 s25, s25, 0
	global_load_dword v176, v200, s[24:25]
	s_add_u32 s24, s24, 0x6000
	s_addc_u32 s25, s25, 0
	global_load_dword v178, v200, s[24:25]
	s_add_u32 s24, s24, 0x6000
	s_addc_u32 s25, s25, 0
	global_load_dword v180, v200, s[24:25]
	s_add_u32 s24, s24, 0x6000
	s_addc_u32 s25, s25, 0
	global_load_dword v182, v200, s[24:25]
	s_add_u32 s24, s24, 0x6000
	s_addc_u32 s25, s25, 0
	global_load_dword v184, v200, s[24:25]
	s_add_u32 s24, s24, 0x6000
	s_addc_u32 s25, s25, 0
	global_load_dword v186, v200, s[24:25]
	s_add_u32 s24, s24, 0x6000
	s_addc_u32 s25, s25, 0
	global_load_dword v188, v200, s[24:25]
	s_add_u32 s24, s24, 0x6000
	s_addc_u32 s25, s25, 0
	global_load_dword v190, v200, s[24:25]
	s_add_u32 s24, s24, 0x6000
	s_addc_u32 s25, s25, 0
	global_load_dword v192, v200, s[24:25]
	s_add_u32 s24, s24, 0x6000
	s_addc_u32 s25, s25, 0
	global_load_dword v194, v200, s[24:25]
	s_add_u32 s24, s24, 0x6000
	s_addc_u32 s25, s25, 0
	global_load_dword v196, v200, s[24:25]
	s_add_u32 s24, s24, 0x6000
	s_addc_u32 s25, s25, 0
	s_waitcnt vmcnt(56)
	v_add_u32_e32 v25, s20, v23
	ds_read_b128 v[26:29], v25
	ds_read_b128 v[30:33], v25 offset:8192
	ds_read_b128 v[34:37], v25 offset:16384
	ds_read_b128 v[38:41], v25 offset:24576
	ds_read_b128 v[42:45], v25 offset:32768
	ds_read_b128 v[46:49], v25 offset:40960
	ds_read_b128 v[50:53], v25 offset:49152
	ds_read_b128 v[54:57], v25 offset:57344
	v_add_u32_e32 v25, 0x10000, v25
	ds_read_b128 v[58:61], v25
	s_waitcnt lgkmcnt(6)
	v_mov_b32_e32 v70, v34
	v_mov_b32_e32 v71, v30
	v_mov_b32_e32 v72, v26
	s_waitcnt lgkmcnt(5)
	v_mov_b32_e32 v73, v38
	s_waitcnt lgkmcnt(4)
	v_mov_b32_e32 v74, v42
	s_waitcnt lgkmcnt(3)
	v_mov_b32_e32 v75, v46
	s_waitcnt lgkmcnt(2)
	v_mov_b32_e32 v76, v50
	s_waitcnt lgkmcnt(1)
	v_mov_b32_e32 v77, v54
	v_mov_b32_e32 v30, v35
	v_mov_b32_e32 v38, v27
	v_mov_b32_e32 v46, v43
	v_mov_b32_e32 v54, v51
	v_mov_b32_e32 v26, v36
	v_mov_b32_e32 v27, v32
	v_mov_b32_e32 v34, v28
	v_mov_b32_e32 v35, v40
	v_mov_b32_e32 v42, v44
	v_mov_b32_e32 v43, v48
	v_mov_b32_e32 v50, v52
	v_mov_b32_e32 v51, v56
	s_add_i32 s20, s20, 16
	v_mov_b32_e32 v32, v37
	v_mov_b32_e32 v40, v29
	v_mov_b32_e32 v48, v45
	v_mov_b32_e32 v56, v53
	v_pk_fma_f32 v[12:13], v[78:79], v[70:71], v[12:13] op_sel_hi:[0,1,1]
	v_pk_fma_f32 v[14:15], v[78:79], v[72:73], v[14:15] op_sel_hi:[0,1,1]
	v_pk_fma_f32 v[16:17], v[78:79], v[74:75], v[16:17] op_sel_hi:[0,1,1]
	v_pk_fma_f32 v[18:19], v[78:79], v[76:77], v[18:19] op_sel_hi:[0,1,1]
	s_waitcnt lgkmcnt(0)
	v_fmac_f32_e32 v8, v78, v58
	v_pk_fma_f32 v[12:13], v[80:81], v[30:31], v[12:13] op_sel_hi:[0,1,1]
	v_pk_fma_f32 v[14:15], v[80:81], v[38:39], v[14:15] op_sel_hi:[0,1,1]
	v_pk_fma_f32 v[16:17], v[80:81], v[46:47], v[16:17] op_sel_hi:[0,1,1]
	v_pk_fma_f32 v[18:19], v[80:81], v[54:55], v[18:19] op_sel_hi:[0,1,1]
	v_fmac_f32_e32 v8, v80, v59
	v_pk_fma_f32 v[12:13], v[82:83], v[26:27], v[12:13] op_sel_hi:[0,1,1]
	v_pk_fma_f32 v[14:15], v[82:83], v[34:35], v[14:15] op_sel_hi:[0,1,1]
	v_pk_fma_f32 v[16:17], v[82:83], v[42:43], v[16:17] op_sel_hi:[0,1,1]
	v_pk_fma_f32 v[18:19], v[82:83], v[50:51], v[18:19] op_sel_hi:[0,1,1]
	v_fmac_f32_e32 v8, v82, v60
	v_pk_fma_f32 v[12:13], v[84:85], v[32:33], v[12:13] op_sel_hi:[0,1,1]
	v_pk_fma_f32 v[14:15], v[84:85], v[40:41], v[14:15] op_sel_hi:[0,1,1]
	v_pk_fma_f32 v[16:17], v[84:85], v[48:49], v[16:17] op_sel_hi:[0,1,1]
	v_pk_fma_f32 v[18:19], v[84:85], v[56:57], v[18:19] op_sel_hi:[0,1,1]
	v_fmac_f32_e32 v8, v84, v61
	global_load_dword v78, v200, s[24:25]
	s_add_u32 s24, s24, 0x6000
	s_addc_u32 s25, s25, 0
	global_load_dword v80, v200, s[24:25]
	s_add_u32 s24, s24, 0x6000
	s_addc_u32 s25, s25, 0
	global_load_dword v82, v200, s[24:25]
	s_add_u32 s24, s24, 0x6000
	s_addc_u32 s25, s25, 0
	global_load_dword v84, v200, s[24:25]
	s_add_u32 s24, s24, 0x6000
	s_addc_u32 s25, s25, 0
	s_waitcnt vmcnt(56)
	v_add_u32_e32 v25, s20, v23
	ds_read_b128 v[26:29], v25
	ds_read_b128 v[30:33], v25 offset:8192
	ds_read_b128 v[34:37], v25 offset:16384
	ds_read_b128 v[38:41], v25 offset:24576
	ds_read_b128 v[42:45], v25 offset:32768
	ds_read_b128 v[46:49], v25 offset:40960
	ds_read_b128 v[50:53], v25 offset:49152
	ds_read_b128 v[54:57], v25 offset:57344
	v_add_u32_e32 v25, 0x10000, v25
	ds_read_b128 v[58:61], v25
	s_waitcnt lgkmcnt(6)
	v_mov_b32_e32 v70, v34
	v_mov_b32_e32 v71, v30
	v_mov_b32_e32 v72, v26
	s_waitcnt lgkmcnt(5)
	v_mov_b32_e32 v73, v38
	s_waitcnt lgkmcnt(4)
	v_mov_b32_e32 v74, v42
	s_waitcnt lgkmcnt(3)
	v_mov_b32_e32 v75, v46
	s_waitcnt lgkmcnt(2)
	v_mov_b32_e32 v76, v50
	s_waitcnt lgkmcnt(1)
	v_mov_b32_e32 v77, v54
	v_mov_b32_e32 v30, v35
	v_mov_b32_e32 v38, v27
	v_mov_b32_e32 v46, v43
	v_mov_b32_e32 v54, v51
	v_mov_b32_e32 v26, v36
	v_mov_b32_e32 v27, v32
	v_mov_b32_e32 v34, v28
	v_mov_b32_e32 v35, v40
	v_mov_b32_e32 v42, v44
	v_mov_b32_e32 v43, v48
	v_mov_b32_e32 v50, v52
	v_mov_b32_e32 v51, v56
	s_add_i32 s20, s20, 16
	v_mov_b32_e32 v32, v37
	v_mov_b32_e32 v40, v29
	v_mov_b32_e32 v48, v45
	v_mov_b32_e32 v56, v53
	v_pk_fma_f32 v[12:13], v[86:87], v[70:71], v[12:13] op_sel_hi:[0,1,1]
	v_pk_fma_f32 v[14:15], v[86:87], v[72:73], v[14:15] op_sel_hi:[0,1,1]
	v_pk_fma_f32 v[16:17], v[86:87], v[74:75], v[16:17] op_sel_hi:[0,1,1]
	v_pk_fma_f32 v[18:19], v[86:87], v[76:77], v[18:19] op_sel_hi:[0,1,1]
	s_waitcnt lgkmcnt(0)
	v_fmac_f32_e32 v8, v86, v58
	v_pk_fma_f32 v[12:13], v[88:89], v[30:31], v[12:13] op_sel_hi:[0,1,1]
	v_pk_fma_f32 v[14:15], v[88:89], v[38:39], v[14:15] op_sel_hi:[0,1,1]
	v_pk_fma_f32 v[16:17], v[88:89], v[46:47], v[16:17] op_sel_hi:[0,1,1]
	v_pk_fma_f32 v[18:19], v[88:89], v[54:55], v[18:19] op_sel_hi:[0,1,1]
	v_fmac_f32_e32 v8, v88, v59
	v_pk_fma_f32 v[12:13], v[90:91], v[26:27], v[12:13] op_sel_hi:[0,1,1]
	v_pk_fma_f32 v[14:15], v[90:91], v[34:35], v[14:15] op_sel_hi:[0,1,1]
	v_pk_fma_f32 v[16:17], v[90:91], v[42:43], v[16:17] op_sel_hi:[0,1,1]
	v_pk_fma_f32 v[18:19], v[90:91], v[50:51], v[18:19] op_sel_hi:[0,1,1]
	v_fmac_f32_e32 v8, v90, v60
	v_pk_fma_f32 v[12:13], v[92:93], v[32:33], v[12:13] op_sel_hi:[0,1,1]
	v_pk_fma_f32 v[14:15], v[92:93], v[40:41], v[14:15] op_sel_hi:[0,1,1]
	v_pk_fma_f32 v[16:17], v[92:93], v[48:49], v[16:17] op_sel_hi:[0,1,1]
	v_pk_fma_f32 v[18:19], v[92:93], v[56:57], v[18:19] op_sel_hi:[0,1,1]
	v_fmac_f32_e32 v8, v92, v61
	global_load_dword v86, v200, s[24:25]
	s_add_u32 s24, s24, 0x6000
	s_addc_u32 s25, s25, 0
	global_load_dword v88, v200, s[24:25]
	s_add_u32 s24, s24, 0x6000
	s_addc_u32 s25, s25, 0
	global_load_dword v90, v200, s[24:25]
	s_add_u32 s24, s24, 0x6000
	s_addc_u32 s25, s25, 0
	global_load_dword v92, v200, s[24:25]
	s_add_u32 s24, s24, 0x6000
	s_addc_u32 s25, s25, 0
	s_waitcnt vmcnt(56)
	v_add_u32_e32 v25, s20, v23
	ds_read_b128 v[26:29], v25
	ds_read_b128 v[30:33], v25 offset:8192
	ds_read_b128 v[34:37], v25 offset:16384
	ds_read_b128 v[38:41], v25 offset:24576
	ds_read_b128 v[42:45], v25 offset:32768
	ds_read_b128 v[46:49], v25 offset:40960
	ds_read_b128 v[50:53], v25 offset:49152
	ds_read_b128 v[54:57], v25 offset:57344
	v_add_u32_e32 v25, 0x10000, v25
	ds_read_b128 v[58:61], v25
	s_waitcnt lgkmcnt(6)
	v_mov_b32_e32 v70, v34
	v_mov_b32_e32 v71, v30
	v_mov_b32_e32 v72, v26
	s_waitcnt lgkmcnt(5)
	v_mov_b32_e32 v73, v38
	s_waitcnt lgkmcnt(4)
	v_mov_b32_e32 v74, v42
	s_waitcnt lgkmcnt(3)
	v_mov_b32_e32 v75, v46
	s_waitcnt lgkmcnt(2)
	v_mov_b32_e32 v76, v50
	s_waitcnt lgkmcnt(1)
	v_mov_b32_e32 v77, v54
	v_mov_b32_e32 v30, v35
	v_mov_b32_e32 v38, v27
	v_mov_b32_e32 v46, v43
	v_mov_b32_e32 v54, v51
	v_mov_b32_e32 v26, v36
	v_mov_b32_e32 v27, v32
	v_mov_b32_e32 v34, v28
	v_mov_b32_e32 v35, v40
	v_mov_b32_e32 v42, v44
	v_mov_b32_e32 v43, v48
	v_mov_b32_e32 v50, v52
	v_mov_b32_e32 v51, v56
	s_add_i32 s20, s20, 16
	v_mov_b32_e32 v32, v37
	v_mov_b32_e32 v40, v29
	v_mov_b32_e32 v48, v45
	v_mov_b32_e32 v56, v53
	v_pk_fma_f32 v[12:13], v[94:95], v[70:71], v[12:13] op_sel_hi:[0,1,1]
	v_pk_fma_f32 v[14:15], v[94:95], v[72:73], v[14:15] op_sel_hi:[0,1,1]
	v_pk_fma_f32 v[16:17], v[94:95], v[74:75], v[16:17] op_sel_hi:[0,1,1]
	v_pk_fma_f32 v[18:19], v[94:95], v[76:77], v[18:19] op_sel_hi:[0,1,1]
	s_waitcnt lgkmcnt(0)
	v_fmac_f32_e32 v8, v94, v58
	v_pk_fma_f32 v[12:13], v[96:97], v[30:31], v[12:13] op_sel_hi:[0,1,1]
	v_pk_fma_f32 v[14:15], v[96:97], v[38:39], v[14:15] op_sel_hi:[0,1,1]
	v_pk_fma_f32 v[16:17], v[96:97], v[46:47], v[16:17] op_sel_hi:[0,1,1]
	v_pk_fma_f32 v[18:19], v[96:97], v[54:55], v[18:19] op_sel_hi:[0,1,1]
	v_fmac_f32_e32 v8, v96, v59
	v_pk_fma_f32 v[12:13], v[98:99], v[26:27], v[12:13] op_sel_hi:[0,1,1]
	v_pk_fma_f32 v[14:15], v[98:99], v[34:35], v[14:15] op_sel_hi:[0,1,1]
	v_pk_fma_f32 v[16:17], v[98:99], v[42:43], v[16:17] op_sel_hi:[0,1,1]
	v_pk_fma_f32 v[18:19], v[98:99], v[50:51], v[18:19] op_sel_hi:[0,1,1]
	v_fmac_f32_e32 v8, v98, v60
	v_pk_fma_f32 v[12:13], v[100:101], v[32:33], v[12:13] op_sel_hi:[0,1,1]
	v_pk_fma_f32 v[14:15], v[100:101], v[40:41], v[14:15] op_sel_hi:[0,1,1]
	v_pk_fma_f32 v[16:17], v[100:101], v[48:49], v[16:17] op_sel_hi:[0,1,1]
	v_pk_fma_f32 v[18:19], v[100:101], v[56:57], v[18:19] op_sel_hi:[0,1,1]
	v_fmac_f32_e32 v8, v100, v61
	global_load_dword v94, v200, s[24:25]
	s_add_u32 s24, s24, 0x6000
	s_addc_u32 s25, s25, 0
	global_load_dword v96, v200, s[24:25]
	s_add_u32 s24, s24, 0x6000
	s_addc_u32 s25, s25, 0
	global_load_dword v98, v200, s[24:25]
	s_add_u32 s24, s24, 0x6000
	s_addc_u32 s25, s25, 0
	global_load_dword v100, v200, s[24:25]
	s_add_u32 s24, s24, 0x6000
	s_addc_u32 s25, s25, 0
	s_waitcnt vmcnt(56)
	v_add_u32_e32 v25, s20, v23
	ds_read_b128 v[26:29], v25
	ds_read_b128 v[30:33], v25 offset:8192
	ds_read_b128 v[34:37], v25 offset:16384
	ds_read_b128 v[38:41], v25 offset:24576
	ds_read_b128 v[42:45], v25 offset:32768
	ds_read_b128 v[46:49], v25 offset:40960
	ds_read_b128 v[50:53], v25 offset:49152
	ds_read_b128 v[54:57], v25 offset:57344
	v_add_u32_e32 v25, 0x10000, v25
	ds_read_b128 v[58:61], v25
	s_waitcnt lgkmcnt(6)
	v_mov_b32_e32 v70, v34
	v_mov_b32_e32 v71, v30
	v_mov_b32_e32 v72, v26
	s_waitcnt lgkmcnt(5)
	v_mov_b32_e32 v73, v38
	s_waitcnt lgkmcnt(4)
	v_mov_b32_e32 v74, v42
	s_waitcnt lgkmcnt(3)
	v_mov_b32_e32 v75, v46
	s_waitcnt lgkmcnt(2)
	v_mov_b32_e32 v76, v50
	s_waitcnt lgkmcnt(1)
	v_mov_b32_e32 v77, v54
	v_mov_b32_e32 v30, v35
	v_mov_b32_e32 v38, v27
	v_mov_b32_e32 v46, v43
	v_mov_b32_e32 v54, v51
	v_mov_b32_e32 v26, v36
	v_mov_b32_e32 v27, v32
	v_mov_b32_e32 v34, v28
	v_mov_b32_e32 v35, v40
	v_mov_b32_e32 v42, v44
	v_mov_b32_e32 v43, v48
	v_mov_b32_e32 v50, v52
	v_mov_b32_e32 v51, v56
	s_add_i32 s20, s20, 16
	v_mov_b32_e32 v32, v37
	v_mov_b32_e32 v40, v29
	v_mov_b32_e32 v48, v45
	v_mov_b32_e32 v56, v53
	v_pk_fma_f32 v[12:13], v[102:103], v[70:71], v[12:13] op_sel_hi:[0,1,1]
	v_pk_fma_f32 v[14:15], v[102:103], v[72:73], v[14:15] op_sel_hi:[0,1,1]
	v_pk_fma_f32 v[16:17], v[102:103], v[74:75], v[16:17] op_sel_hi:[0,1,1]
	v_pk_fma_f32 v[18:19], v[102:103], v[76:77], v[18:19] op_sel_hi:[0,1,1]
	s_waitcnt lgkmcnt(0)
	v_fmac_f32_e32 v8, v102, v58
	v_pk_fma_f32 v[12:13], v[104:105], v[30:31], v[12:13] op_sel_hi:[0,1,1]
	v_pk_fma_f32 v[14:15], v[104:105], v[38:39], v[14:15] op_sel_hi:[0,1,1]
	v_pk_fma_f32 v[16:17], v[104:105], v[46:47], v[16:17] op_sel_hi:[0,1,1]
	v_pk_fma_f32 v[18:19], v[104:105], v[54:55], v[18:19] op_sel_hi:[0,1,1]
	v_fmac_f32_e32 v8, v104, v59
	v_pk_fma_f32 v[12:13], v[106:107], v[26:27], v[12:13] op_sel_hi:[0,1,1]
	v_pk_fma_f32 v[14:15], v[106:107], v[34:35], v[14:15] op_sel_hi:[0,1,1]
	v_pk_fma_f32 v[16:17], v[106:107], v[42:43], v[16:17] op_sel_hi:[0,1,1]
	v_pk_fma_f32 v[18:19], v[106:107], v[50:51], v[18:19] op_sel_hi:[0,1,1]
	v_fmac_f32_e32 v8, v106, v60
	v_pk_fma_f32 v[12:13], v[108:109], v[32:33], v[12:13] op_sel_hi:[0,1,1]
	v_pk_fma_f32 v[14:15], v[108:109], v[40:41], v[14:15] op_sel_hi:[0,1,1]
	v_pk_fma_f32 v[16:17], v[108:109], v[48:49], v[16:17] op_sel_hi:[0,1,1]
	v_pk_fma_f32 v[18:19], v[108:109], v[56:57], v[18:19] op_sel_hi:[0,1,1]
	v_fmac_f32_e32 v8, v108, v61
	global_load_dword v102, v200, s[24:25]
	s_add_u32 s24, s24, 0x6000
	s_addc_u32 s25, s25, 0
	global_load_dword v104, v200, s[24:25]
	s_add_u32 s24, s24, 0x6000
	s_addc_u32 s25, s25, 0
	global_load_dword v106, v200, s[24:25]
	s_add_u32 s24, s24, 0x6000
	s_addc_u32 s25, s25, 0
	global_load_dword v108, v200, s[24:25]
	s_add_u32 s24, s24, 0x6000
	s_addc_u32 s25, s25, 0
	s_waitcnt vmcnt(56)
	v_add_u32_e32 v25, s20, v23
	ds_read_b128 v[26:29], v25
	ds_read_b128 v[30:33], v25 offset:8192
	ds_read_b128 v[34:37], v25 offset:16384
	ds_read_b128 v[38:41], v25 offset:24576
	ds_read_b128 v[42:45], v25 offset:32768
	ds_read_b128 v[46:49], v25 offset:40960
	ds_read_b128 v[50:53], v25 offset:49152
	ds_read_b128 v[54:57], v25 offset:57344
	v_add_u32_e32 v25, 0x10000, v25
	ds_read_b128 v[58:61], v25
	s_waitcnt lgkmcnt(6)
	v_mov_b32_e32 v70, v34
	v_mov_b32_e32 v71, v30
	v_mov_b32_e32 v72, v26
	s_waitcnt lgkmcnt(5)
	v_mov_b32_e32 v73, v38
	s_waitcnt lgkmcnt(4)
	v_mov_b32_e32 v74, v42
	s_waitcnt lgkmcnt(3)
	v_mov_b32_e32 v75, v46
	s_waitcnt lgkmcnt(2)
	v_mov_b32_e32 v76, v50
	s_waitcnt lgkmcnt(1)
	v_mov_b32_e32 v77, v54
	v_mov_b32_e32 v30, v35
	v_mov_b32_e32 v38, v27
	v_mov_b32_e32 v46, v43
	v_mov_b32_e32 v54, v51
	v_mov_b32_e32 v26, v36
	v_mov_b32_e32 v27, v32
	v_mov_b32_e32 v34, v28
	v_mov_b32_e32 v35, v40
	v_mov_b32_e32 v42, v44
	v_mov_b32_e32 v43, v48
	v_mov_b32_e32 v50, v52
	v_mov_b32_e32 v51, v56
	s_add_i32 s20, s20, 16
	v_mov_b32_e32 v32, v37
	v_mov_b32_e32 v40, v29
	v_mov_b32_e32 v48, v45
	v_mov_b32_e32 v56, v53
	v_pk_fma_f32 v[12:13], v[110:111], v[70:71], v[12:13] op_sel_hi:[0,1,1]
	v_pk_fma_f32 v[14:15], v[110:111], v[72:73], v[14:15] op_sel_hi:[0,1,1]
	v_pk_fma_f32 v[16:17], v[110:111], v[74:75], v[16:17] op_sel_hi:[0,1,1]
	v_pk_fma_f32 v[18:19], v[110:111], v[76:77], v[18:19] op_sel_hi:[0,1,1]
	s_waitcnt lgkmcnt(0)
	v_fmac_f32_e32 v8, v110, v58
	v_pk_fma_f32 v[12:13], v[112:113], v[30:31], v[12:13] op_sel_hi:[0,1,1]
	v_pk_fma_f32 v[14:15], v[112:113], v[38:39], v[14:15] op_sel_hi:[0,1,1]
	v_pk_fma_f32 v[16:17], v[112:113], v[46:47], v[16:17] op_sel_hi:[0,1,1]
	v_pk_fma_f32 v[18:19], v[112:113], v[54:55], v[18:19] op_sel_hi:[0,1,1]
	v_fmac_f32_e32 v8, v112, v59
	v_pk_fma_f32 v[12:13], v[114:115], v[26:27], v[12:13] op_sel_hi:[0,1,1]
	v_pk_fma_f32 v[14:15], v[114:115], v[34:35], v[14:15] op_sel_hi:[0,1,1]
	v_pk_fma_f32 v[16:17], v[114:115], v[42:43], v[16:17] op_sel_hi:[0,1,1]
	v_pk_fma_f32 v[18:19], v[114:115], v[50:51], v[18:19] op_sel_hi:[0,1,1]
	v_fmac_f32_e32 v8, v114, v60
	v_pk_fma_f32 v[12:13], v[116:117], v[32:33], v[12:13] op_sel_hi:[0,1,1]
	v_pk_fma_f32 v[14:15], v[116:117], v[40:41], v[14:15] op_sel_hi:[0,1,1]
	v_pk_fma_f32 v[16:17], v[116:117], v[48:49], v[16:17] op_sel_hi:[0,1,1]
	v_pk_fma_f32 v[18:19], v[116:117], v[56:57], v[18:19] op_sel_hi:[0,1,1]
	v_fmac_f32_e32 v8, v116, v61
	global_load_dword v110, v200, s[24:25]
	s_add_u32 s24, s24, 0x6000
	s_addc_u32 s25, s25, 0
	global_load_dword v112, v200, s[24:25]
	s_add_u32 s24, s24, 0x6000
	s_addc_u32 s25, s25, 0
	global_load_dword v114, v200, s[24:25]
	s_add_u32 s24, s24, 0x6000
	s_addc_u32 s25, s25, 0
	global_load_dword v116, v200, s[24:25]
	s_add_u32 s24, s24, 0x6000
	s_addc_u32 s25, s25, 0
	s_waitcnt vmcnt(56)
	v_add_u32_e32 v25, s20, v23
	ds_read_b128 v[26:29], v25
	ds_read_b128 v[30:33], v25 offset:8192
	ds_read_b128 v[34:37], v25 offset:16384
	ds_read_b128 v[38:41], v25 offset:24576
	ds_read_b128 v[42:45], v25 offset:32768
	ds_read_b128 v[46:49], v25 offset:40960
	ds_read_b128 v[50:53], v25 offset:49152
	ds_read_b128 v[54:57], v25 offset:57344
	v_add_u32_e32 v25, 0x10000, v25
	ds_read_b128 v[58:61], v25
	s_waitcnt lgkmcnt(6)
	v_mov_b32_e32 v70, v34
	v_mov_b32_e32 v71, v30
	v_mov_b32_e32 v72, v26
	s_waitcnt lgkmcnt(5)
	v_mov_b32_e32 v73, v38
	s_waitcnt lgkmcnt(4)
	v_mov_b32_e32 v74, v42
	s_waitcnt lgkmcnt(3)
	v_mov_b32_e32 v75, v46
	s_waitcnt lgkmcnt(2)
	v_mov_b32_e32 v76, v50
	s_waitcnt lgkmcnt(1)
	v_mov_b32_e32 v77, v54
	v_mov_b32_e32 v30, v35
	v_mov_b32_e32 v38, v27
	v_mov_b32_e32 v46, v43
	v_mov_b32_e32 v54, v51
	v_mov_b32_e32 v26, v36
	v_mov_b32_e32 v27, v32
	v_mov_b32_e32 v34, v28
	v_mov_b32_e32 v35, v40
	v_mov_b32_e32 v42, v44
	v_mov_b32_e32 v43, v48
	v_mov_b32_e32 v50, v52
	v_mov_b32_e32 v51, v56
	s_add_i32 s20, s20, 16
	v_mov_b32_e32 v32, v37
	v_mov_b32_e32 v40, v29
	v_mov_b32_e32 v48, v45
	v_mov_b32_e32 v56, v53
	v_pk_fma_f32 v[12:13], v[118:119], v[70:71], v[12:13] op_sel_hi:[0,1,1]
	v_pk_fma_f32 v[14:15], v[118:119], v[72:73], v[14:15] op_sel_hi:[0,1,1]
	v_pk_fma_f32 v[16:17], v[118:119], v[74:75], v[16:17] op_sel_hi:[0,1,1]
	v_pk_fma_f32 v[18:19], v[118:119], v[76:77], v[18:19] op_sel_hi:[0,1,1]
	s_waitcnt lgkmcnt(0)
	v_fmac_f32_e32 v8, v118, v58
	v_pk_fma_f32 v[12:13], v[120:121], v[30:31], v[12:13] op_sel_hi:[0,1,1]
	v_pk_fma_f32 v[14:15], v[120:121], v[38:39], v[14:15] op_sel_hi:[0,1,1]
	v_pk_fma_f32 v[16:17], v[120:121], v[46:47], v[16:17] op_sel_hi:[0,1,1]
	v_pk_fma_f32 v[18:19], v[120:121], v[54:55], v[18:19] op_sel_hi:[0,1,1]
	v_fmac_f32_e32 v8, v120, v59
	v_pk_fma_f32 v[12:13], v[122:123], v[26:27], v[12:13] op_sel_hi:[0,1,1]
	v_pk_fma_f32 v[14:15], v[122:123], v[34:35], v[14:15] op_sel_hi:[0,1,1]
	v_pk_fma_f32 v[16:17], v[122:123], v[42:43], v[16:17] op_sel_hi:[0,1,1]
	v_pk_fma_f32 v[18:19], v[122:123], v[50:51], v[18:19] op_sel_hi:[0,1,1]
	v_fmac_f32_e32 v8, v122, v60
	v_pk_fma_f32 v[12:13], v[124:125], v[32:33], v[12:13] op_sel_hi:[0,1,1]
	v_pk_fma_f32 v[14:15], v[124:125], v[40:41], v[14:15] op_sel_hi:[0,1,1]
	v_pk_fma_f32 v[16:17], v[124:125], v[48:49], v[16:17] op_sel_hi:[0,1,1]
	v_pk_fma_f32 v[18:19], v[124:125], v[56:57], v[18:19] op_sel_hi:[0,1,1]
	v_fmac_f32_e32 v8, v124, v61
	global_load_dword v118, v200, s[24:25]
	s_add_u32 s24, s24, 0x6000
	s_addc_u32 s25, s25, 0
	global_load_dword v120, v200, s[24:25]
	s_add_u32 s24, s24, 0x6000
	s_addc_u32 s25, s25, 0
	global_load_dword v122, v200, s[24:25]
	s_add_u32 s24, s24, 0x6000
	s_addc_u32 s25, s25, 0
	global_load_dword v124, v200, s[24:25]
	s_add_u32 s24, s24, 0x6000
	s_addc_u32 s25, s25, 0
	s_waitcnt vmcnt(56)
	v_add_u32_e32 v25, s20, v23
	ds_read_b128 v[26:29], v25
	ds_read_b128 v[30:33], v25 offset:8192
	ds_read_b128 v[34:37], v25 offset:16384
	ds_read_b128 v[38:41], v25 offset:24576
	ds_read_b128 v[42:45], v25 offset:32768
	ds_read_b128 v[46:49], v25 offset:40960
	ds_read_b128 v[50:53], v25 offset:49152
	ds_read_b128 v[54:57], v25 offset:57344
	v_add_u32_e32 v25, 0x10000, v25
	ds_read_b128 v[58:61], v25
	s_waitcnt lgkmcnt(6)
	v_mov_b32_e32 v70, v34
	v_mov_b32_e32 v71, v30
	v_mov_b32_e32 v72, v26
	s_waitcnt lgkmcnt(5)
	v_mov_b32_e32 v73, v38
	s_waitcnt lgkmcnt(4)
	v_mov_b32_e32 v74, v42
	s_waitcnt lgkmcnt(3)
	v_mov_b32_e32 v75, v46
	s_waitcnt lgkmcnt(2)
	v_mov_b32_e32 v76, v50
	s_waitcnt lgkmcnt(1)
	v_mov_b32_e32 v77, v54
	v_mov_b32_e32 v30, v35
	v_mov_b32_e32 v38, v27
	v_mov_b32_e32 v46, v43
	v_mov_b32_e32 v54, v51
	v_mov_b32_e32 v26, v36
	v_mov_b32_e32 v27, v32
	v_mov_b32_e32 v34, v28
	v_mov_b32_e32 v35, v40
	v_mov_b32_e32 v42, v44
	v_mov_b32_e32 v43, v48
	v_mov_b32_e32 v50, v52
	v_mov_b32_e32 v51, v56
	s_add_i32 s20, s20, 16
	v_mov_b32_e32 v32, v37
	v_mov_b32_e32 v40, v29
	v_mov_b32_e32 v48, v45
	v_mov_b32_e32 v56, v53
	v_pk_fma_f32 v[12:13], v[126:127], v[70:71], v[12:13] op_sel_hi:[0,1,1]
	v_pk_fma_f32 v[14:15], v[126:127], v[72:73], v[14:15] op_sel_hi:[0,1,1]
	v_pk_fma_f32 v[16:17], v[126:127], v[74:75], v[16:17] op_sel_hi:[0,1,1]
	v_pk_fma_f32 v[18:19], v[126:127], v[76:77], v[18:19] op_sel_hi:[0,1,1]
	s_waitcnt lgkmcnt(0)
	v_fmac_f32_e32 v8, v126, v58
	v_pk_fma_f32 v[12:13], v[128:129], v[30:31], v[12:13] op_sel_hi:[0,1,1]
	v_pk_fma_f32 v[14:15], v[128:129], v[38:39], v[14:15] op_sel_hi:[0,1,1]
	v_pk_fma_f32 v[16:17], v[128:129], v[46:47], v[16:17] op_sel_hi:[0,1,1]
	v_pk_fma_f32 v[18:19], v[128:129], v[54:55], v[18:19] op_sel_hi:[0,1,1]
	v_fmac_f32_e32 v8, v128, v59
	v_pk_fma_f32 v[12:13], v[130:131], v[26:27], v[12:13] op_sel_hi:[0,1,1]
	v_pk_fma_f32 v[14:15], v[130:131], v[34:35], v[14:15] op_sel_hi:[0,1,1]
	v_pk_fma_f32 v[16:17], v[130:131], v[42:43], v[16:17] op_sel_hi:[0,1,1]
	v_pk_fma_f32 v[18:19], v[130:131], v[50:51], v[18:19] op_sel_hi:[0,1,1]
	v_fmac_f32_e32 v8, v130, v60
	v_pk_fma_f32 v[12:13], v[132:133], v[32:33], v[12:13] op_sel_hi:[0,1,1]
	v_pk_fma_f32 v[14:15], v[132:133], v[40:41], v[14:15] op_sel_hi:[0,1,1]
	v_pk_fma_f32 v[16:17], v[132:133], v[48:49], v[16:17] op_sel_hi:[0,1,1]
	v_pk_fma_f32 v[18:19], v[132:133], v[56:57], v[18:19] op_sel_hi:[0,1,1]
	v_fmac_f32_e32 v8, v132, v61
	global_load_dword v126, v200, s[24:25]
	s_add_u32 s24, s24, 0x6000
	s_addc_u32 s25, s25, 0
	global_load_dword v128, v200, s[24:25]
	s_add_u32 s24, s24, 0x6000
	s_addc_u32 s25, s25, 0
	global_load_dword v130, v200, s[24:25]
	s_add_u32 s24, s24, 0x6000
	s_addc_u32 s25, s25, 0
	global_load_dword v132, v200, s[24:25]
	s_add_u32 s24, s24, 0x6000
	s_addc_u32 s25, s25, 0
	s_waitcnt vmcnt(56)
	v_add_u32_e32 v25, s20, v23
	ds_read_b128 v[26:29], v25
	ds_read_b128 v[30:33], v25 offset:8192
	ds_read_b128 v[34:37], v25 offset:16384
	ds_read_b128 v[38:41], v25 offset:24576
	ds_read_b128 v[42:45], v25 offset:32768
	ds_read_b128 v[46:49], v25 offset:40960
	ds_read_b128 v[50:53], v25 offset:49152
	ds_read_b128 v[54:57], v25 offset:57344
	v_add_u32_e32 v25, 0x10000, v25
	ds_read_b128 v[58:61], v25
	s_waitcnt lgkmcnt(6)
	v_mov_b32_e32 v70, v34
	v_mov_b32_e32 v71, v30
	v_mov_b32_e32 v72, v26
	s_waitcnt lgkmcnt(5)
	v_mov_b32_e32 v73, v38
	s_waitcnt lgkmcnt(4)
	v_mov_b32_e32 v74, v42
	s_waitcnt lgkmcnt(3)
	v_mov_b32_e32 v75, v46
	s_waitcnt lgkmcnt(2)
	v_mov_b32_e32 v76, v50
	s_waitcnt lgkmcnt(1)
	v_mov_b32_e32 v77, v54
	v_mov_b32_e32 v30, v35
	v_mov_b32_e32 v38, v27
	v_mov_b32_e32 v46, v43
	v_mov_b32_e32 v54, v51
	v_mov_b32_e32 v26, v36
	v_mov_b32_e32 v27, v32
	v_mov_b32_e32 v34, v28
	v_mov_b32_e32 v35, v40
	v_mov_b32_e32 v42, v44
	v_mov_b32_e32 v43, v48
	v_mov_b32_e32 v50, v52
	v_mov_b32_e32 v51, v56
	s_add_i32 s20, s20, 16
	v_mov_b32_e32 v32, v37
	v_mov_b32_e32 v40, v29
	v_mov_b32_e32 v48, v45
	v_mov_b32_e32 v56, v53
	v_pk_fma_f32 v[12:13], v[134:135], v[70:71], v[12:13] op_sel_hi:[0,1,1]
	v_pk_fma_f32 v[14:15], v[134:135], v[72:73], v[14:15] op_sel_hi:[0,1,1]
	v_pk_fma_f32 v[16:17], v[134:135], v[74:75], v[16:17] op_sel_hi:[0,1,1]
	v_pk_fma_f32 v[18:19], v[134:135], v[76:77], v[18:19] op_sel_hi:[0,1,1]
	s_waitcnt lgkmcnt(0)
	v_fmac_f32_e32 v8, v134, v58
	v_pk_fma_f32 v[12:13], v[136:137], v[30:31], v[12:13] op_sel_hi:[0,1,1]
	v_pk_fma_f32 v[14:15], v[136:137], v[38:39], v[14:15] op_sel_hi:[0,1,1]
	v_pk_fma_f32 v[16:17], v[136:137], v[46:47], v[16:17] op_sel_hi:[0,1,1]
	v_pk_fma_f32 v[18:19], v[136:137], v[54:55], v[18:19] op_sel_hi:[0,1,1]
	v_fmac_f32_e32 v8, v136, v59
	v_pk_fma_f32 v[12:13], v[138:139], v[26:27], v[12:13] op_sel_hi:[0,1,1]
	v_pk_fma_f32 v[14:15], v[138:139], v[34:35], v[14:15] op_sel_hi:[0,1,1]
	v_pk_fma_f32 v[16:17], v[138:139], v[42:43], v[16:17] op_sel_hi:[0,1,1]
	v_pk_fma_f32 v[18:19], v[138:139], v[50:51], v[18:19] op_sel_hi:[0,1,1]
	v_fmac_f32_e32 v8, v138, v60
	v_pk_fma_f32 v[12:13], v[140:141], v[32:33], v[12:13] op_sel_hi:[0,1,1]
	v_pk_fma_f32 v[14:15], v[140:141], v[40:41], v[14:15] op_sel_hi:[0,1,1]
	v_pk_fma_f32 v[16:17], v[140:141], v[48:49], v[16:17] op_sel_hi:[0,1,1]
	v_pk_fma_f32 v[18:19], v[140:141], v[56:57], v[18:19] op_sel_hi:[0,1,1]
	v_fmac_f32_e32 v8, v140, v61
	global_load_dword v134, v200, s[24:25]
	s_add_u32 s24, s24, 0x6000
	s_addc_u32 s25, s25, 0
	global_load_dword v136, v200, s[24:25]
	s_add_u32 s24, s24, 0x6000
	s_addc_u32 s25, s25, 0
	global_load_dword v138, v200, s[24:25]
	s_add_u32 s24, s24, 0x6000
	s_addc_u32 s25, s25, 0
	global_load_dword v140, v200, s[24:25]
	s_add_u32 s24, s24, 0x6000
	s_addc_u32 s25, s25, 0
	s_waitcnt vmcnt(56)
	v_add_u32_e32 v25, s20, v23
	ds_read_b128 v[26:29], v25
	ds_read_b128 v[30:33], v25 offset:8192
	ds_read_b128 v[34:37], v25 offset:16384
	ds_read_b128 v[38:41], v25 offset:24576
	ds_read_b128 v[42:45], v25 offset:32768
	ds_read_b128 v[46:49], v25 offset:40960
	ds_read_b128 v[50:53], v25 offset:49152
	ds_read_b128 v[54:57], v25 offset:57344
	v_add_u32_e32 v25, 0x10000, v25
	ds_read_b128 v[58:61], v25
	s_waitcnt lgkmcnt(6)
	v_mov_b32_e32 v70, v34
	v_mov_b32_e32 v71, v30
	v_mov_b32_e32 v72, v26
	s_waitcnt lgkmcnt(5)
	v_mov_b32_e32 v73, v38
	s_waitcnt lgkmcnt(4)
	v_mov_b32_e32 v74, v42
	s_waitcnt lgkmcnt(3)
	v_mov_b32_e32 v75, v46
	s_waitcnt lgkmcnt(2)
	v_mov_b32_e32 v76, v50
	s_waitcnt lgkmcnt(1)
	v_mov_b32_e32 v77, v54
	v_mov_b32_e32 v30, v35
	v_mov_b32_e32 v38, v27
	v_mov_b32_e32 v46, v43
	v_mov_b32_e32 v54, v51
	v_mov_b32_e32 v26, v36
	v_mov_b32_e32 v27, v32
	v_mov_b32_e32 v34, v28
	v_mov_b32_e32 v35, v40
	v_mov_b32_e32 v42, v44
	v_mov_b32_e32 v43, v48
	v_mov_b32_e32 v50, v52
	v_mov_b32_e32 v51, v56
	s_add_i32 s20, s20, 16
	v_mov_b32_e32 v32, v37
	v_mov_b32_e32 v40, v29
	v_mov_b32_e32 v48, v45
	v_mov_b32_e32 v56, v53
	v_pk_fma_f32 v[12:13], v[142:143], v[70:71], v[12:13] op_sel_hi:[0,1,1]
	v_pk_fma_f32 v[14:15], v[142:143], v[72:73], v[14:15] op_sel_hi:[0,1,1]
	v_pk_fma_f32 v[16:17], v[142:143], v[74:75], v[16:17] op_sel_hi:[0,1,1]
	v_pk_fma_f32 v[18:19], v[142:143], v[76:77], v[18:19] op_sel_hi:[0,1,1]
	s_waitcnt lgkmcnt(0)
	v_fmac_f32_e32 v8, v142, v58
	v_pk_fma_f32 v[12:13], v[144:145], v[30:31], v[12:13] op_sel_hi:[0,1,1]
	v_pk_fma_f32 v[14:15], v[144:145], v[38:39], v[14:15] op_sel_hi:[0,1,1]
	v_pk_fma_f32 v[16:17], v[144:145], v[46:47], v[16:17] op_sel_hi:[0,1,1]
	v_pk_fma_f32 v[18:19], v[144:145], v[54:55], v[18:19] op_sel_hi:[0,1,1]
	v_fmac_f32_e32 v8, v144, v59
	v_pk_fma_f32 v[12:13], v[146:147], v[26:27], v[12:13] op_sel_hi:[0,1,1]
	v_pk_fma_f32 v[14:15], v[146:147], v[34:35], v[14:15] op_sel_hi:[0,1,1]
	v_pk_fma_f32 v[16:17], v[146:147], v[42:43], v[16:17] op_sel_hi:[0,1,1]
	v_pk_fma_f32 v[18:19], v[146:147], v[50:51], v[18:19] op_sel_hi:[0,1,1]
	v_fmac_f32_e32 v8, v146, v60
	v_pk_fma_f32 v[12:13], v[148:149], v[32:33], v[12:13] op_sel_hi:[0,1,1]
	v_pk_fma_f32 v[14:15], v[148:149], v[40:41], v[14:15] op_sel_hi:[0,1,1]
	v_pk_fma_f32 v[16:17], v[148:149], v[48:49], v[16:17] op_sel_hi:[0,1,1]
	v_pk_fma_f32 v[18:19], v[148:149], v[56:57], v[18:19] op_sel_hi:[0,1,1]
	v_fmac_f32_e32 v8, v148, v61
	global_load_dword v142, v200, s[24:25]
	s_add_u32 s24, s24, 0x6000
	s_addc_u32 s25, s25, 0
	global_load_dword v144, v200, s[24:25]
	s_add_u32 s24, s24, 0x6000
	s_addc_u32 s25, s25, 0
	global_load_dword v146, v200, s[24:25]
	s_add_u32 s24, s24, 0x6000
	s_addc_u32 s25, s25, 0
	global_load_dword v148, v200, s[24:25]
	s_add_u32 s24, s24, 0x6000
	s_addc_u32 s25, s25, 0
	s_waitcnt vmcnt(56)
	v_add_u32_e32 v25, s20, v23
	ds_read_b128 v[26:29], v25
	ds_read_b128 v[30:33], v25 offset:8192
	ds_read_b128 v[34:37], v25 offset:16384
	ds_read_b128 v[38:41], v25 offset:24576
	ds_read_b128 v[42:45], v25 offset:32768
	ds_read_b128 v[46:49], v25 offset:40960
	ds_read_b128 v[50:53], v25 offset:49152
	ds_read_b128 v[54:57], v25 offset:57344
	v_add_u32_e32 v25, 0x10000, v25
	ds_read_b128 v[58:61], v25
	s_waitcnt lgkmcnt(6)
	v_mov_b32_e32 v70, v34
	v_mov_b32_e32 v71, v30
	v_mov_b32_e32 v72, v26
	s_waitcnt lgkmcnt(5)
	v_mov_b32_e32 v73, v38
	s_waitcnt lgkmcnt(4)
	v_mov_b32_e32 v74, v42
	s_waitcnt lgkmcnt(3)
	v_mov_b32_e32 v75, v46
	s_waitcnt lgkmcnt(2)
	v_mov_b32_e32 v76, v50
	s_waitcnt lgkmcnt(1)
	v_mov_b32_e32 v77, v54
	v_mov_b32_e32 v30, v35
	v_mov_b32_e32 v38, v27
	v_mov_b32_e32 v46, v43
	v_mov_b32_e32 v54, v51
	v_mov_b32_e32 v26, v36
	v_mov_b32_e32 v27, v32
	v_mov_b32_e32 v34, v28
	v_mov_b32_e32 v35, v40
	v_mov_b32_e32 v42, v44
	v_mov_b32_e32 v43, v48
	v_mov_b32_e32 v50, v52
	v_mov_b32_e32 v51, v56
	s_add_i32 s20, s20, 16
	v_mov_b32_e32 v32, v37
	v_mov_b32_e32 v40, v29
	v_mov_b32_e32 v48, v45
	v_mov_b32_e32 v56, v53
	v_pk_fma_f32 v[12:13], v[150:151], v[70:71], v[12:13] op_sel_hi:[0,1,1]
	v_pk_fma_f32 v[14:15], v[150:151], v[72:73], v[14:15] op_sel_hi:[0,1,1]
	v_pk_fma_f32 v[16:17], v[150:151], v[74:75], v[16:17] op_sel_hi:[0,1,1]
	v_pk_fma_f32 v[18:19], v[150:151], v[76:77], v[18:19] op_sel_hi:[0,1,1]
	s_waitcnt lgkmcnt(0)
	v_fmac_f32_e32 v8, v150, v58
	v_pk_fma_f32 v[12:13], v[152:153], v[30:31], v[12:13] op_sel_hi:[0,1,1]
	v_pk_fma_f32 v[14:15], v[152:153], v[38:39], v[14:15] op_sel_hi:[0,1,1]
	v_pk_fma_f32 v[16:17], v[152:153], v[46:47], v[16:17] op_sel_hi:[0,1,1]
	v_pk_fma_f32 v[18:19], v[152:153], v[54:55], v[18:19] op_sel_hi:[0,1,1]
	v_fmac_f32_e32 v8, v152, v59
	v_pk_fma_f32 v[12:13], v[154:155], v[26:27], v[12:13] op_sel_hi:[0,1,1]
	v_pk_fma_f32 v[14:15], v[154:155], v[34:35], v[14:15] op_sel_hi:[0,1,1]
	v_pk_fma_f32 v[16:17], v[154:155], v[42:43], v[16:17] op_sel_hi:[0,1,1]
	v_pk_fma_f32 v[18:19], v[154:155], v[50:51], v[18:19] op_sel_hi:[0,1,1]
	v_fmac_f32_e32 v8, v154, v60
	v_pk_fma_f32 v[12:13], v[156:157], v[32:33], v[12:13] op_sel_hi:[0,1,1]
	v_pk_fma_f32 v[14:15], v[156:157], v[40:41], v[14:15] op_sel_hi:[0,1,1]
	v_pk_fma_f32 v[16:17], v[156:157], v[48:49], v[16:17] op_sel_hi:[0,1,1]
	v_pk_fma_f32 v[18:19], v[156:157], v[56:57], v[18:19] op_sel_hi:[0,1,1]
	v_fmac_f32_e32 v8, v156, v61
	global_load_dword v150, v200, s[24:25]
	s_add_u32 s24, s24, 0x6000
	s_addc_u32 s25, s25, 0
	global_load_dword v152, v200, s[24:25]
	s_add_u32 s24, s24, 0x6000
	s_addc_u32 s25, s25, 0
	global_load_dword v154, v200, s[24:25]
	s_add_u32 s24, s24, 0x6000
	s_addc_u32 s25, s25, 0
	global_load_dword v156, v200, s[24:25]
	s_add_u32 s24, s24, 0x6000
	s_addc_u32 s25, s25, 0
	s_waitcnt vmcnt(56)
	v_add_u32_e32 v25, s20, v23
	ds_read_b128 v[26:29], v25
	ds_read_b128 v[30:33], v25 offset:8192
	ds_read_b128 v[34:37], v25 offset:16384
	ds_read_b128 v[38:41], v25 offset:24576
	ds_read_b128 v[42:45], v25 offset:32768
	ds_read_b128 v[46:49], v25 offset:40960
	ds_read_b128 v[50:53], v25 offset:49152
	ds_read_b128 v[54:57], v25 offset:57344
	v_add_u32_e32 v25, 0x10000, v25
	ds_read_b128 v[58:61], v25
	s_waitcnt lgkmcnt(6)
	v_mov_b32_e32 v70, v34
	v_mov_b32_e32 v71, v30
	v_mov_b32_e32 v72, v26
	s_waitcnt lgkmcnt(5)
	v_mov_b32_e32 v73, v38
	s_waitcnt lgkmcnt(4)
	v_mov_b32_e32 v74, v42
	s_waitcnt lgkmcnt(3)
	v_mov_b32_e32 v75, v46
	s_waitcnt lgkmcnt(2)
	v_mov_b32_e32 v76, v50
	s_waitcnt lgkmcnt(1)
	v_mov_b32_e32 v77, v54
	v_mov_b32_e32 v30, v35
	v_mov_b32_e32 v38, v27
	v_mov_b32_e32 v46, v43
	v_mov_b32_e32 v54, v51
	v_mov_b32_e32 v26, v36
	v_mov_b32_e32 v27, v32
	v_mov_b32_e32 v34, v28
	v_mov_b32_e32 v35, v40
	v_mov_b32_e32 v42, v44
	v_mov_b32_e32 v43, v48
	v_mov_b32_e32 v50, v52
	v_mov_b32_e32 v51, v56
	s_add_i32 s20, s20, 16
	v_mov_b32_e32 v32, v37
	v_mov_b32_e32 v40, v29
	v_mov_b32_e32 v48, v45
	v_mov_b32_e32 v56, v53
	v_pk_fma_f32 v[12:13], v[158:159], v[70:71], v[12:13] op_sel_hi:[0,1,1]
	v_pk_fma_f32 v[14:15], v[158:159], v[72:73], v[14:15] op_sel_hi:[0,1,1]
	v_pk_fma_f32 v[16:17], v[158:159], v[74:75], v[16:17] op_sel_hi:[0,1,1]
	v_pk_fma_f32 v[18:19], v[158:159], v[76:77], v[18:19] op_sel_hi:[0,1,1]
	s_waitcnt lgkmcnt(0)
	v_fmac_f32_e32 v8, v158, v58
	v_pk_fma_f32 v[12:13], v[160:161], v[30:31], v[12:13] op_sel_hi:[0,1,1]
	v_pk_fma_f32 v[14:15], v[160:161], v[38:39], v[14:15] op_sel_hi:[0,1,1]
	v_pk_fma_f32 v[16:17], v[160:161], v[46:47], v[16:17] op_sel_hi:[0,1,1]
	v_pk_fma_f32 v[18:19], v[160:161], v[54:55], v[18:19] op_sel_hi:[0,1,1]
	v_fmac_f32_e32 v8, v160, v59
	v_pk_fma_f32 v[12:13], v[162:163], v[26:27], v[12:13] op_sel_hi:[0,1,1]
	v_pk_fma_f32 v[14:15], v[162:163], v[34:35], v[14:15] op_sel_hi:[0,1,1]
	v_pk_fma_f32 v[16:17], v[162:163], v[42:43], v[16:17] op_sel_hi:[0,1,1]
	v_pk_fma_f32 v[18:19], v[162:163], v[50:51], v[18:19] op_sel_hi:[0,1,1]
	v_fmac_f32_e32 v8, v162, v60
	v_pk_fma_f32 v[12:13], v[164:165], v[32:33], v[12:13] op_sel_hi:[0,1,1]
	v_pk_fma_f32 v[14:15], v[164:165], v[40:41], v[14:15] op_sel_hi:[0,1,1]
	v_pk_fma_f32 v[16:17], v[164:165], v[48:49], v[16:17] op_sel_hi:[0,1,1]
	v_pk_fma_f32 v[18:19], v[164:165], v[56:57], v[18:19] op_sel_hi:[0,1,1]
	v_fmac_f32_e32 v8, v164, v61
	global_load_dword v158, v200, s[24:25]
	s_add_u32 s24, s24, 0x6000
	s_addc_u32 s25, s25, 0
	global_load_dword v160, v200, s[24:25]
	s_add_u32 s24, s24, 0x6000
	s_addc_u32 s25, s25, 0
	global_load_dword v162, v200, s[24:25]
	s_add_u32 s24, s24, 0x6000
	s_addc_u32 s25, s25, 0
	global_load_dword v164, v200, s[24:25]
	s_add_u32 s24, s24, 0x6000
	s_addc_u32 s25, s25, 0
	s_waitcnt vmcnt(56)
	v_add_u32_e32 v25, s20, v23
	ds_read_b128 v[26:29], v25
	ds_read_b128 v[30:33], v25 offset:8192
	ds_read_b128 v[34:37], v25 offset:16384
	ds_read_b128 v[38:41], v25 offset:24576
	ds_read_b128 v[42:45], v25 offset:32768
	ds_read_b128 v[46:49], v25 offset:40960
	ds_read_b128 v[50:53], v25 offset:49152
	ds_read_b128 v[54:57], v25 offset:57344
	v_add_u32_e32 v25, 0x10000, v25
	ds_read_b128 v[58:61], v25
	s_waitcnt lgkmcnt(6)
	v_mov_b32_e32 v70, v34
	v_mov_b32_e32 v71, v30
	v_mov_b32_e32 v72, v26
	s_waitcnt lgkmcnt(5)
	v_mov_b32_e32 v73, v38
	s_waitcnt lgkmcnt(4)
	v_mov_b32_e32 v74, v42
	s_waitcnt lgkmcnt(3)
	v_mov_b32_e32 v75, v46
	s_waitcnt lgkmcnt(2)
	v_mov_b32_e32 v76, v50
	s_waitcnt lgkmcnt(1)
	v_mov_b32_e32 v77, v54
	v_mov_b32_e32 v30, v35
	v_mov_b32_e32 v38, v27
	v_mov_b32_e32 v46, v43
	v_mov_b32_e32 v54, v51
	v_mov_b32_e32 v26, v36
	v_mov_b32_e32 v27, v32
	v_mov_b32_e32 v34, v28
	v_mov_b32_e32 v35, v40
	v_mov_b32_e32 v42, v44
	v_mov_b32_e32 v43, v48
	v_mov_b32_e32 v50, v52
	v_mov_b32_e32 v51, v56
	s_add_i32 s20, s20, 16
	v_mov_b32_e32 v32, v37
	v_mov_b32_e32 v40, v29
	v_mov_b32_e32 v48, v45
	v_mov_b32_e32 v56, v53
	v_pk_fma_f32 v[12:13], v[166:167], v[70:71], v[12:13] op_sel_hi:[0,1,1]
	v_pk_fma_f32 v[14:15], v[166:167], v[72:73], v[14:15] op_sel_hi:[0,1,1]
	v_pk_fma_f32 v[16:17], v[166:167], v[74:75], v[16:17] op_sel_hi:[0,1,1]
	v_pk_fma_f32 v[18:19], v[166:167], v[76:77], v[18:19] op_sel_hi:[0,1,1]
	s_waitcnt lgkmcnt(0)
	v_fmac_f32_e32 v8, v166, v58
	v_pk_fma_f32 v[12:13], v[168:169], v[30:31], v[12:13] op_sel_hi:[0,1,1]
	v_pk_fma_f32 v[14:15], v[168:169], v[38:39], v[14:15] op_sel_hi:[0,1,1]
	v_pk_fma_f32 v[16:17], v[168:169], v[46:47], v[16:17] op_sel_hi:[0,1,1]
	v_pk_fma_f32 v[18:19], v[168:169], v[54:55], v[18:19] op_sel_hi:[0,1,1]
	v_fmac_f32_e32 v8, v168, v59
	v_pk_fma_f32 v[12:13], v[170:171], v[26:27], v[12:13] op_sel_hi:[0,1,1]
	v_pk_fma_f32 v[14:15], v[170:171], v[34:35], v[14:15] op_sel_hi:[0,1,1]
	v_pk_fma_f32 v[16:17], v[170:171], v[42:43], v[16:17] op_sel_hi:[0,1,1]
	v_pk_fma_f32 v[18:19], v[170:171], v[50:51], v[18:19] op_sel_hi:[0,1,1]
	v_fmac_f32_e32 v8, v170, v60
	v_pk_fma_f32 v[12:13], v[172:173], v[32:33], v[12:13] op_sel_hi:[0,1,1]
	v_pk_fma_f32 v[14:15], v[172:173], v[40:41], v[14:15] op_sel_hi:[0,1,1]
	v_pk_fma_f32 v[16:17], v[172:173], v[48:49], v[16:17] op_sel_hi:[0,1,1]
	v_pk_fma_f32 v[18:19], v[172:173], v[56:57], v[18:19] op_sel_hi:[0,1,1]
	v_fmac_f32_e32 v8, v172, v61
	global_load_dword v166, v200, s[24:25]
	s_add_u32 s24, s24, 0x6000
	s_addc_u32 s25, s25, 0
	global_load_dword v168, v200, s[24:25]
	s_add_u32 s24, s24, 0x6000
	s_addc_u32 s25, s25, 0
	global_load_dword v170, v200, s[24:25]
	s_add_u32 s24, s24, 0x6000
	s_addc_u32 s25, s25, 0
	global_load_dword v172, v200, s[24:25]
	s_add_u32 s24, s24, 0x6000
	s_addc_u32 s25, s25, 0
	s_waitcnt vmcnt(56)
	v_add_u32_e32 v25, s20, v23
	ds_read_b128 v[26:29], v25
	ds_read_b128 v[30:33], v25 offset:8192
	ds_read_b128 v[34:37], v25 offset:16384
	ds_read_b128 v[38:41], v25 offset:24576
	ds_read_b128 v[42:45], v25 offset:32768
	ds_read_b128 v[46:49], v25 offset:40960
	ds_read_b128 v[50:53], v25 offset:49152
	ds_read_b128 v[54:57], v25 offset:57344
	v_add_u32_e32 v25, 0x10000, v25
	ds_read_b128 v[58:61], v25
	s_waitcnt lgkmcnt(6)
	v_mov_b32_e32 v70, v34
	v_mov_b32_e32 v71, v30
	v_mov_b32_e32 v72, v26
	s_waitcnt lgkmcnt(5)
	v_mov_b32_e32 v73, v38
	s_waitcnt lgkmcnt(4)
	v_mov_b32_e32 v74, v42
	s_waitcnt lgkmcnt(3)
	v_mov_b32_e32 v75, v46
	s_waitcnt lgkmcnt(2)
	v_mov_b32_e32 v76, v50
	s_waitcnt lgkmcnt(1)
	v_mov_b32_e32 v77, v54
	v_mov_b32_e32 v30, v35
	v_mov_b32_e32 v38, v27
	v_mov_b32_e32 v46, v43
	v_mov_b32_e32 v54, v51
	v_mov_b32_e32 v26, v36
	v_mov_b32_e32 v27, v32
	v_mov_b32_e32 v34, v28
	v_mov_b32_e32 v35, v40
	v_mov_b32_e32 v42, v44
	v_mov_b32_e32 v43, v48
	v_mov_b32_e32 v50, v52
	v_mov_b32_e32 v51, v56
	s_add_i32 s20, s20, 16
	v_mov_b32_e32 v32, v37
	v_mov_b32_e32 v40, v29
	v_mov_b32_e32 v48, v45
	v_mov_b32_e32 v56, v53
	v_pk_fma_f32 v[12:13], v[174:175], v[70:71], v[12:13] op_sel_hi:[0,1,1]
	v_pk_fma_f32 v[14:15], v[174:175], v[72:73], v[14:15] op_sel_hi:[0,1,1]
	v_pk_fma_f32 v[16:17], v[174:175], v[74:75], v[16:17] op_sel_hi:[0,1,1]
	v_pk_fma_f32 v[18:19], v[174:175], v[76:77], v[18:19] op_sel_hi:[0,1,1]
	s_waitcnt lgkmcnt(0)
	v_fmac_f32_e32 v8, v174, v58
	v_pk_fma_f32 v[12:13], v[176:177], v[30:31], v[12:13] op_sel_hi:[0,1,1]
	v_pk_fma_f32 v[14:15], v[176:177], v[38:39], v[14:15] op_sel_hi:[0,1,1]
	v_pk_fma_f32 v[16:17], v[176:177], v[46:47], v[16:17] op_sel_hi:[0,1,1]
	v_pk_fma_f32 v[18:19], v[176:177], v[54:55], v[18:19] op_sel_hi:[0,1,1]
	v_fmac_f32_e32 v8, v176, v59
	v_pk_fma_f32 v[12:13], v[178:179], v[26:27], v[12:13] op_sel_hi:[0,1,1]
	v_pk_fma_f32 v[14:15], v[178:179], v[34:35], v[14:15] op_sel_hi:[0,1,1]
	v_pk_fma_f32 v[16:17], v[178:179], v[42:43], v[16:17] op_sel_hi:[0,1,1]
	v_pk_fma_f32 v[18:19], v[178:179], v[50:51], v[18:19] op_sel_hi:[0,1,1]
	v_fmac_f32_e32 v8, v178, v60
	v_pk_fma_f32 v[12:13], v[180:181], v[32:33], v[12:13] op_sel_hi:[0,1,1]
	v_pk_fma_f32 v[14:15], v[180:181], v[40:41], v[14:15] op_sel_hi:[0,1,1]
	v_pk_fma_f32 v[16:17], v[180:181], v[48:49], v[16:17] op_sel_hi:[0,1,1]
	v_pk_fma_f32 v[18:19], v[180:181], v[56:57], v[18:19] op_sel_hi:[0,1,1]
	v_fmac_f32_e32 v8, v180, v61
	global_load_dword v174, v200, s[24:25]
	s_add_u32 s24, s24, 0x6000
	s_addc_u32 s25, s25, 0
	global_load_dword v176, v200, s[24:25]
	s_add_u32 s24, s24, 0x6000
	s_addc_u32 s25, s25, 0
	global_load_dword v178, v200, s[24:25]
	s_add_u32 s24, s24, 0x6000
	s_addc_u32 s25, s25, 0
	global_load_dword v180, v200, s[24:25]
	s_add_u32 s24, s24, 0x6000
	s_addc_u32 s25, s25, 0
	s_waitcnt vmcnt(56)
	v_add_u32_e32 v25, s20, v23
	ds_read_b128 v[26:29], v25
	ds_read_b128 v[30:33], v25 offset:8192
	ds_read_b128 v[34:37], v25 offset:16384
	ds_read_b128 v[38:41], v25 offset:24576
	ds_read_b128 v[42:45], v25 offset:32768
	ds_read_b128 v[46:49], v25 offset:40960
	ds_read_b128 v[50:53], v25 offset:49152
	ds_read_b128 v[54:57], v25 offset:57344
	v_add_u32_e32 v25, 0x10000, v25
	ds_read_b128 v[58:61], v25
	s_waitcnt lgkmcnt(6)
	v_mov_b32_e32 v70, v34
	v_mov_b32_e32 v71, v30
	v_mov_b32_e32 v72, v26
	s_waitcnt lgkmcnt(5)
	v_mov_b32_e32 v73, v38
	s_waitcnt lgkmcnt(4)
	v_mov_b32_e32 v74, v42
	s_waitcnt lgkmcnt(3)
	v_mov_b32_e32 v75, v46
	s_waitcnt lgkmcnt(2)
	v_mov_b32_e32 v76, v50
	s_waitcnt lgkmcnt(1)
	v_mov_b32_e32 v77, v54
	v_mov_b32_e32 v30, v35
	v_mov_b32_e32 v38, v27
	v_mov_b32_e32 v46, v43
	v_mov_b32_e32 v54, v51
	v_mov_b32_e32 v26, v36
	v_mov_b32_e32 v27, v32
	v_mov_b32_e32 v34, v28
	v_mov_b32_e32 v35, v40
	v_mov_b32_e32 v42, v44
	v_mov_b32_e32 v43, v48
	v_mov_b32_e32 v50, v52
	v_mov_b32_e32 v51, v56
	s_add_i32 s20, s20, 16
	v_mov_b32_e32 v32, v37
	v_mov_b32_e32 v40, v29
	v_mov_b32_e32 v48, v45
	v_mov_b32_e32 v56, v53
	v_pk_fma_f32 v[12:13], v[182:183], v[70:71], v[12:13] op_sel_hi:[0,1,1]
	v_pk_fma_f32 v[14:15], v[182:183], v[72:73], v[14:15] op_sel_hi:[0,1,1]
	v_pk_fma_f32 v[16:17], v[182:183], v[74:75], v[16:17] op_sel_hi:[0,1,1]
	v_pk_fma_f32 v[18:19], v[182:183], v[76:77], v[18:19] op_sel_hi:[0,1,1]
	s_waitcnt lgkmcnt(0)
	v_fmac_f32_e32 v8, v182, v58
	v_pk_fma_f32 v[12:13], v[184:185], v[30:31], v[12:13] op_sel_hi:[0,1,1]
	v_pk_fma_f32 v[14:15], v[184:185], v[38:39], v[14:15] op_sel_hi:[0,1,1]
	v_pk_fma_f32 v[16:17], v[184:185], v[46:47], v[16:17] op_sel_hi:[0,1,1]
	v_pk_fma_f32 v[18:19], v[184:185], v[54:55], v[18:19] op_sel_hi:[0,1,1]
	v_fmac_f32_e32 v8, v184, v59
	v_pk_fma_f32 v[12:13], v[186:187], v[26:27], v[12:13] op_sel_hi:[0,1,1]
	v_pk_fma_f32 v[14:15], v[186:187], v[34:35], v[14:15] op_sel_hi:[0,1,1]
	v_pk_fma_f32 v[16:17], v[186:187], v[42:43], v[16:17] op_sel_hi:[0,1,1]
	v_pk_fma_f32 v[18:19], v[186:187], v[50:51], v[18:19] op_sel_hi:[0,1,1]
	v_fmac_f32_e32 v8, v186, v60
	v_pk_fma_f32 v[12:13], v[188:189], v[32:33], v[12:13] op_sel_hi:[0,1,1]
	v_pk_fma_f32 v[14:15], v[188:189], v[40:41], v[14:15] op_sel_hi:[0,1,1]
	v_pk_fma_f32 v[16:17], v[188:189], v[48:49], v[16:17] op_sel_hi:[0,1,1]
	v_pk_fma_f32 v[18:19], v[188:189], v[56:57], v[18:19] op_sel_hi:[0,1,1]
	v_fmac_f32_e32 v8, v188, v61
	global_load_dword v182, v200, s[24:25]
	s_add_u32 s24, s24, 0x6000
	s_addc_u32 s25, s25, 0
	global_load_dword v184, v200, s[24:25]
	s_add_u32 s24, s24, 0x6000
	s_addc_u32 s25, s25, 0
	global_load_dword v186, v200, s[24:25]
	s_add_u32 s24, s24, 0x6000
	s_addc_u32 s25, s25, 0
	global_load_dword v188, v200, s[24:25]
	s_add_u32 s24, s24, 0x6000
	s_addc_u32 s25, s25, 0
	s_waitcnt vmcnt(56)
	v_add_u32_e32 v25, s20, v23
	ds_read_b128 v[26:29], v25
	ds_read_b128 v[30:33], v25 offset:8192
	ds_read_b128 v[34:37], v25 offset:16384
	ds_read_b128 v[38:41], v25 offset:24576
	ds_read_b128 v[42:45], v25 offset:32768
	ds_read_b128 v[46:49], v25 offset:40960
	ds_read_b128 v[50:53], v25 offset:49152
	ds_read_b128 v[54:57], v25 offset:57344
	v_add_u32_e32 v25, 0x10000, v25
	ds_read_b128 v[58:61], v25
	s_waitcnt lgkmcnt(6)
	v_mov_b32_e32 v70, v34
	v_mov_b32_e32 v71, v30
	v_mov_b32_e32 v72, v26
	s_waitcnt lgkmcnt(5)
	v_mov_b32_e32 v73, v38
	s_waitcnt lgkmcnt(4)
	v_mov_b32_e32 v74, v42
	s_waitcnt lgkmcnt(3)
	v_mov_b32_e32 v75, v46
	s_waitcnt lgkmcnt(2)
	v_mov_b32_e32 v76, v50
	s_waitcnt lgkmcnt(1)
	v_mov_b32_e32 v77, v54
	v_mov_b32_e32 v30, v35
	v_mov_b32_e32 v38, v27
	v_mov_b32_e32 v46, v43
	v_mov_b32_e32 v54, v51
	v_mov_b32_e32 v26, v36
	v_mov_b32_e32 v27, v32
	v_mov_b32_e32 v34, v28
	v_mov_b32_e32 v35, v40
	v_mov_b32_e32 v42, v44
	v_mov_b32_e32 v43, v48
	v_mov_b32_e32 v50, v52
	v_mov_b32_e32 v51, v56
	s_add_i32 s20, s20, 16
	v_mov_b32_e32 v32, v37
	v_mov_b32_e32 v40, v29
	v_mov_b32_e32 v48, v45
	v_mov_b32_e32 v56, v53
	v_pk_fma_f32 v[12:13], v[190:191], v[70:71], v[12:13] op_sel_hi:[0,1,1]
	v_pk_fma_f32 v[14:15], v[190:191], v[72:73], v[14:15] op_sel_hi:[0,1,1]
	v_pk_fma_f32 v[16:17], v[190:191], v[74:75], v[16:17] op_sel_hi:[0,1,1]
	v_pk_fma_f32 v[18:19], v[190:191], v[76:77], v[18:19] op_sel_hi:[0,1,1]
	s_waitcnt lgkmcnt(0)
	v_fmac_f32_e32 v8, v190, v58
	v_pk_fma_f32 v[12:13], v[192:193], v[30:31], v[12:13] op_sel_hi:[0,1,1]
	v_pk_fma_f32 v[14:15], v[192:193], v[38:39], v[14:15] op_sel_hi:[0,1,1]
	v_pk_fma_f32 v[16:17], v[192:193], v[46:47], v[16:17] op_sel_hi:[0,1,1]
	v_pk_fma_f32 v[18:19], v[192:193], v[54:55], v[18:19] op_sel_hi:[0,1,1]
	v_fmac_f32_e32 v8, v192, v59
	v_pk_fma_f32 v[12:13], v[194:195], v[26:27], v[12:13] op_sel_hi:[0,1,1]
	v_pk_fma_f32 v[14:15], v[194:195], v[34:35], v[14:15] op_sel_hi:[0,1,1]
	v_pk_fma_f32 v[16:17], v[194:195], v[42:43], v[16:17] op_sel_hi:[0,1,1]
	v_pk_fma_f32 v[18:19], v[194:195], v[50:51], v[18:19] op_sel_hi:[0,1,1]
	v_fmac_f32_e32 v8, v194, v60
	v_pk_fma_f32 v[12:13], v[196:197], v[32:33], v[12:13] op_sel_hi:[0,1,1]
	v_pk_fma_f32 v[14:15], v[196:197], v[40:41], v[14:15] op_sel_hi:[0,1,1]
	v_pk_fma_f32 v[16:17], v[196:197], v[48:49], v[16:17] op_sel_hi:[0,1,1]
	v_pk_fma_f32 v[18:19], v[196:197], v[56:57], v[18:19] op_sel_hi:[0,1,1]
	v_fmac_f32_e32 v8, v196, v61
	global_load_dword v190, v200, s[24:25]
	s_add_u32 s24, s24, 0x6000
	s_addc_u32 s25, s25, 0
	global_load_dword v192, v200, s[24:25]
	s_add_u32 s24, s24, 0x6000
	s_addc_u32 s25, s25, 0
	global_load_dword v194, v200, s[24:25]
	s_add_u32 s24, s24, 0x6000
	s_addc_u32 s25, s25, 0
	global_load_dword v196, v200, s[24:25]
	s_add_u32 s24, s24, 0x6000
	s_addc_u32 s25, s25, 0
	s_waitcnt vmcnt(56)
	v_add_u32_e32 v25, s20, v23
	ds_read_b128 v[26:29], v25
	ds_read_b128 v[30:33], v25 offset:8192
	ds_read_b128 v[34:37], v25 offset:16384
	ds_read_b128 v[38:41], v25 offset:24576
	ds_read_b128 v[42:45], v25 offset:32768
	ds_read_b128 v[46:49], v25 offset:40960
	ds_read_b128 v[50:53], v25 offset:49152
	ds_read_b128 v[54:57], v25 offset:57344
	v_add_u32_e32 v25, 0x10000, v25
	ds_read_b128 v[58:61], v25
	s_waitcnt lgkmcnt(6)
	v_mov_b32_e32 v70, v34
	v_mov_b32_e32 v71, v30
	v_mov_b32_e32 v72, v26
	s_waitcnt lgkmcnt(5)
	v_mov_b32_e32 v73, v38
	s_waitcnt lgkmcnt(4)
	v_mov_b32_e32 v74, v42
	s_waitcnt lgkmcnt(3)
	v_mov_b32_e32 v75, v46
	s_waitcnt lgkmcnt(2)
	v_mov_b32_e32 v76, v50
	s_waitcnt lgkmcnt(1)
	v_mov_b32_e32 v77, v54
	v_mov_b32_e32 v30, v35
	v_mov_b32_e32 v38, v27
	v_mov_b32_e32 v46, v43
	v_mov_b32_e32 v54, v51
	v_mov_b32_e32 v26, v36
	v_mov_b32_e32 v27, v32
	v_mov_b32_e32 v34, v28
	v_mov_b32_e32 v35, v40
	v_mov_b32_e32 v42, v44
	v_mov_b32_e32 v43, v48
	v_mov_b32_e32 v50, v52
	v_mov_b32_e32 v51, v56
	s_add_i32 s20, s20, 16
	v_mov_b32_e32 v32, v37
	v_mov_b32_e32 v40, v29
	v_mov_b32_e32 v48, v45
	v_mov_b32_e32 v56, v53
	v_pk_fma_f32 v[12:13], v[78:79], v[70:71], v[12:13] op_sel_hi:[0,1,1]
	v_pk_fma_f32 v[14:15], v[78:79], v[72:73], v[14:15] op_sel_hi:[0,1,1]
	v_pk_fma_f32 v[16:17], v[78:79], v[74:75], v[16:17] op_sel_hi:[0,1,1]
	v_pk_fma_f32 v[18:19], v[78:79], v[76:77], v[18:19] op_sel_hi:[0,1,1]
	s_waitcnt lgkmcnt(0)
	v_fmac_f32_e32 v8, v78, v58
	v_pk_fma_f32 v[12:13], v[80:81], v[30:31], v[12:13] op_sel_hi:[0,1,1]
	v_pk_fma_f32 v[14:15], v[80:81], v[38:39], v[14:15] op_sel_hi:[0,1,1]
	v_pk_fma_f32 v[16:17], v[80:81], v[46:47], v[16:17] op_sel_hi:[0,1,1]
	v_pk_fma_f32 v[18:19], v[80:81], v[54:55], v[18:19] op_sel_hi:[0,1,1]
	v_fmac_f32_e32 v8, v80, v59
	v_pk_fma_f32 v[12:13], v[82:83], v[26:27], v[12:13] op_sel_hi:[0,1,1]
	v_pk_fma_f32 v[14:15], v[82:83], v[34:35], v[14:15] op_sel_hi:[0,1,1]
	v_pk_fma_f32 v[16:17], v[82:83], v[42:43], v[16:17] op_sel_hi:[0,1,1]
	v_pk_fma_f32 v[18:19], v[82:83], v[50:51], v[18:19] op_sel_hi:[0,1,1]
	v_fmac_f32_e32 v8, v82, v60
	v_pk_fma_f32 v[12:13], v[84:85], v[32:33], v[12:13] op_sel_hi:[0,1,1]
	v_pk_fma_f32 v[14:15], v[84:85], v[40:41], v[14:15] op_sel_hi:[0,1,1]
	v_pk_fma_f32 v[16:17], v[84:85], v[48:49], v[16:17] op_sel_hi:[0,1,1]
	v_pk_fma_f32 v[18:19], v[84:85], v[56:57], v[18:19] op_sel_hi:[0,1,1]
	v_fmac_f32_e32 v8, v84, v61
	global_load_dword v78, v200, s[24:25]
	s_add_u32 s24, s24, 0x6000
	s_addc_u32 s25, s25, 0
	global_load_dword v80, v200, s[24:25]
	s_add_u32 s24, s24, 0x6000
	s_addc_u32 s25, s25, 0
	global_load_dword v82, v200, s[24:25]
	s_add_u32 s24, s24, 0x6000
	s_addc_u32 s25, s25, 0
	global_load_dword v84, v200, s[24:25]
	s_add_u32 s24, s24, 0x6000
	s_addc_u32 s25, s25, 0
	s_waitcnt vmcnt(56)
	v_add_u32_e32 v25, s20, v23
	ds_read_b128 v[26:29], v25
	ds_read_b128 v[30:33], v25 offset:8192
	ds_read_b128 v[34:37], v25 offset:16384
	ds_read_b128 v[38:41], v25 offset:24576
	ds_read_b128 v[42:45], v25 offset:32768
	ds_read_b128 v[46:49], v25 offset:40960
	ds_read_b128 v[50:53], v25 offset:49152
	ds_read_b128 v[54:57], v25 offset:57344
	v_add_u32_e32 v25, 0x10000, v25
	ds_read_b128 v[58:61], v25
	s_waitcnt lgkmcnt(6)
	v_mov_b32_e32 v70, v34
	v_mov_b32_e32 v71, v30
	v_mov_b32_e32 v72, v26
	s_waitcnt lgkmcnt(5)
	v_mov_b32_e32 v73, v38
	s_waitcnt lgkmcnt(4)
	v_mov_b32_e32 v74, v42
	s_waitcnt lgkmcnt(3)
	v_mov_b32_e32 v75, v46
	s_waitcnt lgkmcnt(2)
	v_mov_b32_e32 v76, v50
	s_waitcnt lgkmcnt(1)
	v_mov_b32_e32 v77, v54
	v_mov_b32_e32 v30, v35
	v_mov_b32_e32 v38, v27
	v_mov_b32_e32 v46, v43
	v_mov_b32_e32 v54, v51
	v_mov_b32_e32 v26, v36
	v_mov_b32_e32 v27, v32
	v_mov_b32_e32 v34, v28
	v_mov_b32_e32 v35, v40
	v_mov_b32_e32 v42, v44
	v_mov_b32_e32 v43, v48
	v_mov_b32_e32 v50, v52
	v_mov_b32_e32 v51, v56
	s_add_i32 s20, s20, 16
	v_mov_b32_e32 v32, v37
	v_mov_b32_e32 v40, v29
	v_mov_b32_e32 v48, v45
	v_mov_b32_e32 v56, v53
	v_pk_fma_f32 v[12:13], v[86:87], v[70:71], v[12:13] op_sel_hi:[0,1,1]
	v_pk_fma_f32 v[14:15], v[86:87], v[72:73], v[14:15] op_sel_hi:[0,1,1]
	v_pk_fma_f32 v[16:17], v[86:87], v[74:75], v[16:17] op_sel_hi:[0,1,1]
	v_pk_fma_f32 v[18:19], v[86:87], v[76:77], v[18:19] op_sel_hi:[0,1,1]
	s_waitcnt lgkmcnt(0)
	v_fmac_f32_e32 v8, v86, v58
	v_pk_fma_f32 v[12:13], v[88:89], v[30:31], v[12:13] op_sel_hi:[0,1,1]
	v_pk_fma_f32 v[14:15], v[88:89], v[38:39], v[14:15] op_sel_hi:[0,1,1]
	v_pk_fma_f32 v[16:17], v[88:89], v[46:47], v[16:17] op_sel_hi:[0,1,1]
	v_pk_fma_f32 v[18:19], v[88:89], v[54:55], v[18:19] op_sel_hi:[0,1,1]
	v_fmac_f32_e32 v8, v88, v59
	v_pk_fma_f32 v[12:13], v[90:91], v[26:27], v[12:13] op_sel_hi:[0,1,1]
	v_pk_fma_f32 v[14:15], v[90:91], v[34:35], v[14:15] op_sel_hi:[0,1,1]
	v_pk_fma_f32 v[16:17], v[90:91], v[42:43], v[16:17] op_sel_hi:[0,1,1]
	v_pk_fma_f32 v[18:19], v[90:91], v[50:51], v[18:19] op_sel_hi:[0,1,1]
	v_fmac_f32_e32 v8, v90, v60
	v_pk_fma_f32 v[12:13], v[92:93], v[32:33], v[12:13] op_sel_hi:[0,1,1]
	v_pk_fma_f32 v[14:15], v[92:93], v[40:41], v[14:15] op_sel_hi:[0,1,1]
	v_pk_fma_f32 v[16:17], v[92:93], v[48:49], v[16:17] op_sel_hi:[0,1,1]
	v_pk_fma_f32 v[18:19], v[92:93], v[56:57], v[18:19] op_sel_hi:[0,1,1]
	v_fmac_f32_e32 v8, v92, v61
	global_load_dword v86, v200, s[24:25]
	s_add_u32 s24, s24, 0x6000
	s_addc_u32 s25, s25, 0
	global_load_dword v88, v200, s[24:25]
	s_add_u32 s24, s24, 0x6000
	s_addc_u32 s25, s25, 0
	global_load_dword v90, v200, s[24:25]
	s_add_u32 s24, s24, 0x6000
	s_addc_u32 s25, s25, 0
	global_load_dword v92, v200, s[24:25]
	s_add_u32 s24, s24, 0x6000
	s_addc_u32 s25, s25, 0
	s_waitcnt vmcnt(56)
	v_add_u32_e32 v25, s20, v23
	ds_read_b128 v[26:29], v25
	ds_read_b128 v[30:33], v25 offset:8192
	ds_read_b128 v[34:37], v25 offset:16384
	ds_read_b128 v[38:41], v25 offset:24576
	ds_read_b128 v[42:45], v25 offset:32768
	ds_read_b128 v[46:49], v25 offset:40960
	ds_read_b128 v[50:53], v25 offset:49152
	ds_read_b128 v[54:57], v25 offset:57344
	v_add_u32_e32 v25, 0x10000, v25
	ds_read_b128 v[58:61], v25
	s_waitcnt lgkmcnt(6)
	v_mov_b32_e32 v70, v34
	v_mov_b32_e32 v71, v30
	v_mov_b32_e32 v72, v26
	s_waitcnt lgkmcnt(5)
	v_mov_b32_e32 v73, v38
	s_waitcnt lgkmcnt(4)
	v_mov_b32_e32 v74, v42
	s_waitcnt lgkmcnt(3)
	v_mov_b32_e32 v75, v46
	s_waitcnt lgkmcnt(2)
	v_mov_b32_e32 v76, v50
	s_waitcnt lgkmcnt(1)
	v_mov_b32_e32 v77, v54
	v_mov_b32_e32 v30, v35
	v_mov_b32_e32 v38, v27
	v_mov_b32_e32 v46, v43
	v_mov_b32_e32 v54, v51
	v_mov_b32_e32 v26, v36
	v_mov_b32_e32 v27, v32
	v_mov_b32_e32 v34, v28
	v_mov_b32_e32 v35, v40
	v_mov_b32_e32 v42, v44
	v_mov_b32_e32 v43, v48
	v_mov_b32_e32 v50, v52
	v_mov_b32_e32 v51, v56
	s_add_i32 s20, s20, 16
	v_mov_b32_e32 v32, v37
	v_mov_b32_e32 v40, v29
	v_mov_b32_e32 v48, v45
	v_mov_b32_e32 v56, v53
	v_pk_fma_f32 v[12:13], v[94:95], v[70:71], v[12:13] op_sel_hi:[0,1,1]
	v_pk_fma_f32 v[14:15], v[94:95], v[72:73], v[14:15] op_sel_hi:[0,1,1]
	v_pk_fma_f32 v[16:17], v[94:95], v[74:75], v[16:17] op_sel_hi:[0,1,1]
	v_pk_fma_f32 v[18:19], v[94:95], v[76:77], v[18:19] op_sel_hi:[0,1,1]
	s_waitcnt lgkmcnt(0)
	v_fmac_f32_e32 v8, v94, v58
	v_pk_fma_f32 v[12:13], v[96:97], v[30:31], v[12:13] op_sel_hi:[0,1,1]
	v_pk_fma_f32 v[14:15], v[96:97], v[38:39], v[14:15] op_sel_hi:[0,1,1]
	v_pk_fma_f32 v[16:17], v[96:97], v[46:47], v[16:17] op_sel_hi:[0,1,1]
	v_pk_fma_f32 v[18:19], v[96:97], v[54:55], v[18:19] op_sel_hi:[0,1,1]
	v_fmac_f32_e32 v8, v96, v59
	v_pk_fma_f32 v[12:13], v[98:99], v[26:27], v[12:13] op_sel_hi:[0,1,1]
	v_pk_fma_f32 v[14:15], v[98:99], v[34:35], v[14:15] op_sel_hi:[0,1,1]
	v_pk_fma_f32 v[16:17], v[98:99], v[42:43], v[16:17] op_sel_hi:[0,1,1]
	v_pk_fma_f32 v[18:19], v[98:99], v[50:51], v[18:19] op_sel_hi:[0,1,1]
	v_fmac_f32_e32 v8, v98, v60
	v_pk_fma_f32 v[12:13], v[100:101], v[32:33], v[12:13] op_sel_hi:[0,1,1]
	v_pk_fma_f32 v[14:15], v[100:101], v[40:41], v[14:15] op_sel_hi:[0,1,1]
	v_pk_fma_f32 v[16:17], v[100:101], v[48:49], v[16:17] op_sel_hi:[0,1,1]
	v_pk_fma_f32 v[18:19], v[100:101], v[56:57], v[18:19] op_sel_hi:[0,1,1]
	v_fmac_f32_e32 v8, v100, v61
	global_load_dword v94, v200, s[24:25]
	s_add_u32 s24, s24, 0x6000
	s_addc_u32 s25, s25, 0
	global_load_dword v96, v200, s[24:25]
	s_add_u32 s24, s24, 0x6000
	s_addc_u32 s25, s25, 0
	global_load_dword v98, v200, s[24:25]
	s_add_u32 s24, s24, 0x6000
	s_addc_u32 s25, s25, 0
	global_load_dword v100, v200, s[24:25]
	s_add_u32 s24, s24, 0x6000
	s_addc_u32 s25, s25, 0
	s_waitcnt vmcnt(56)
	v_add_u32_e32 v25, s20, v23
	ds_read_b128 v[26:29], v25
	ds_read_b128 v[30:33], v25 offset:8192
	ds_read_b128 v[34:37], v25 offset:16384
	ds_read_b128 v[38:41], v25 offset:24576
	ds_read_b128 v[42:45], v25 offset:32768
	ds_read_b128 v[46:49], v25 offset:40960
	ds_read_b128 v[50:53], v25 offset:49152
	ds_read_b128 v[54:57], v25 offset:57344
	v_add_u32_e32 v25, 0x10000, v25
	ds_read_b128 v[58:61], v25
	s_waitcnt lgkmcnt(6)
	v_mov_b32_e32 v70, v34
	v_mov_b32_e32 v71, v30
	v_mov_b32_e32 v72, v26
	s_waitcnt lgkmcnt(5)
	v_mov_b32_e32 v73, v38
	s_waitcnt lgkmcnt(4)
	v_mov_b32_e32 v74, v42
	s_waitcnt lgkmcnt(3)
	v_mov_b32_e32 v75, v46
	s_waitcnt lgkmcnt(2)
	v_mov_b32_e32 v76, v50
	s_waitcnt lgkmcnt(1)
	v_mov_b32_e32 v77, v54
	v_mov_b32_e32 v30, v35
	v_mov_b32_e32 v38, v27
	v_mov_b32_e32 v46, v43
	v_mov_b32_e32 v54, v51
	v_mov_b32_e32 v26, v36
	v_mov_b32_e32 v27, v32
	v_mov_b32_e32 v34, v28
	v_mov_b32_e32 v35, v40
	v_mov_b32_e32 v42, v44
	v_mov_b32_e32 v43, v48
	v_mov_b32_e32 v50, v52
	v_mov_b32_e32 v51, v56
	s_add_i32 s20, s20, 16
	v_mov_b32_e32 v32, v37
	v_mov_b32_e32 v40, v29
	v_mov_b32_e32 v48, v45
	v_mov_b32_e32 v56, v53
	v_pk_fma_f32 v[12:13], v[102:103], v[70:71], v[12:13] op_sel_hi:[0,1,1]
	v_pk_fma_f32 v[14:15], v[102:103], v[72:73], v[14:15] op_sel_hi:[0,1,1]
	v_pk_fma_f32 v[16:17], v[102:103], v[74:75], v[16:17] op_sel_hi:[0,1,1]
	v_pk_fma_f32 v[18:19], v[102:103], v[76:77], v[18:19] op_sel_hi:[0,1,1]
	s_waitcnt lgkmcnt(0)
	v_fmac_f32_e32 v8, v102, v58
	v_pk_fma_f32 v[12:13], v[104:105], v[30:31], v[12:13] op_sel_hi:[0,1,1]
	v_pk_fma_f32 v[14:15], v[104:105], v[38:39], v[14:15] op_sel_hi:[0,1,1]
	v_pk_fma_f32 v[16:17], v[104:105], v[46:47], v[16:17] op_sel_hi:[0,1,1]
	v_pk_fma_f32 v[18:19], v[104:105], v[54:55], v[18:19] op_sel_hi:[0,1,1]
	v_fmac_f32_e32 v8, v104, v59
	v_pk_fma_f32 v[12:13], v[106:107], v[26:27], v[12:13] op_sel_hi:[0,1,1]
	v_pk_fma_f32 v[14:15], v[106:107], v[34:35], v[14:15] op_sel_hi:[0,1,1]
	v_pk_fma_f32 v[16:17], v[106:107], v[42:43], v[16:17] op_sel_hi:[0,1,1]
	v_pk_fma_f32 v[18:19], v[106:107], v[50:51], v[18:19] op_sel_hi:[0,1,1]
	v_fmac_f32_e32 v8, v106, v60
	v_pk_fma_f32 v[12:13], v[108:109], v[32:33], v[12:13] op_sel_hi:[0,1,1]
	v_pk_fma_f32 v[14:15], v[108:109], v[40:41], v[14:15] op_sel_hi:[0,1,1]
	v_pk_fma_f32 v[16:17], v[108:109], v[48:49], v[16:17] op_sel_hi:[0,1,1]
	v_pk_fma_f32 v[18:19], v[108:109], v[56:57], v[18:19] op_sel_hi:[0,1,1]
	v_fmac_f32_e32 v8, v108, v61
	global_load_dword v102, v200, s[24:25]
	s_add_u32 s24, s24, 0x6000
	s_addc_u32 s25, s25, 0
	global_load_dword v104, v200, s[24:25]
	s_add_u32 s24, s24, 0x6000
	s_addc_u32 s25, s25, 0
	global_load_dword v106, v200, s[24:25]
	s_add_u32 s24, s24, 0x6000
	s_addc_u32 s25, s25, 0
	global_load_dword v108, v200, s[24:25]
	s_add_u32 s24, s24, 0x6000
	s_addc_u32 s25, s25, 0
	s_waitcnt vmcnt(56)
	v_add_u32_e32 v25, s20, v23
	ds_read_b128 v[26:29], v25
	ds_read_b128 v[30:33], v25 offset:8192
	ds_read_b128 v[34:37], v25 offset:16384
	ds_read_b128 v[38:41], v25 offset:24576
	ds_read_b128 v[42:45], v25 offset:32768
	ds_read_b128 v[46:49], v25 offset:40960
	ds_read_b128 v[50:53], v25 offset:49152
	ds_read_b128 v[54:57], v25 offset:57344
	v_add_u32_e32 v25, 0x10000, v25
	ds_read_b128 v[58:61], v25
	s_waitcnt lgkmcnt(6)
	v_mov_b32_e32 v70, v34
	v_mov_b32_e32 v71, v30
	v_mov_b32_e32 v72, v26
	s_waitcnt lgkmcnt(5)
	v_mov_b32_e32 v73, v38
	s_waitcnt lgkmcnt(4)
	v_mov_b32_e32 v74, v42
	s_waitcnt lgkmcnt(3)
	v_mov_b32_e32 v75, v46
	s_waitcnt lgkmcnt(2)
	v_mov_b32_e32 v76, v50
	s_waitcnt lgkmcnt(1)
	v_mov_b32_e32 v77, v54
	v_mov_b32_e32 v30, v35
	v_mov_b32_e32 v38, v27
	v_mov_b32_e32 v46, v43
	v_mov_b32_e32 v54, v51
	v_mov_b32_e32 v26, v36
	v_mov_b32_e32 v27, v32
	v_mov_b32_e32 v34, v28
	v_mov_b32_e32 v35, v40
	v_mov_b32_e32 v42, v44
	v_mov_b32_e32 v43, v48
	v_mov_b32_e32 v50, v52
	v_mov_b32_e32 v51, v56
	s_add_i32 s20, s20, 16
	v_mov_b32_e32 v32, v37
	v_mov_b32_e32 v40, v29
	v_mov_b32_e32 v48, v45
	v_mov_b32_e32 v56, v53
	v_pk_fma_f32 v[12:13], v[110:111], v[70:71], v[12:13] op_sel_hi:[0,1,1]
	v_pk_fma_f32 v[14:15], v[110:111], v[72:73], v[14:15] op_sel_hi:[0,1,1]
	v_pk_fma_f32 v[16:17], v[110:111], v[74:75], v[16:17] op_sel_hi:[0,1,1]
	v_pk_fma_f32 v[18:19], v[110:111], v[76:77], v[18:19] op_sel_hi:[0,1,1]
	s_waitcnt lgkmcnt(0)
	v_fmac_f32_e32 v8, v110, v58
	v_pk_fma_f32 v[12:13], v[112:113], v[30:31], v[12:13] op_sel_hi:[0,1,1]
	v_pk_fma_f32 v[14:15], v[112:113], v[38:39], v[14:15] op_sel_hi:[0,1,1]
	v_pk_fma_f32 v[16:17], v[112:113], v[46:47], v[16:17] op_sel_hi:[0,1,1]
	v_pk_fma_f32 v[18:19], v[112:113], v[54:55], v[18:19] op_sel_hi:[0,1,1]
	v_fmac_f32_e32 v8, v112, v59
	v_pk_fma_f32 v[12:13], v[114:115], v[26:27], v[12:13] op_sel_hi:[0,1,1]
	v_pk_fma_f32 v[14:15], v[114:115], v[34:35], v[14:15] op_sel_hi:[0,1,1]
	v_pk_fma_f32 v[16:17], v[114:115], v[42:43], v[16:17] op_sel_hi:[0,1,1]
	v_pk_fma_f32 v[18:19], v[114:115], v[50:51], v[18:19] op_sel_hi:[0,1,1]
	v_fmac_f32_e32 v8, v114, v60
	v_pk_fma_f32 v[12:13], v[116:117], v[32:33], v[12:13] op_sel_hi:[0,1,1]
	v_pk_fma_f32 v[14:15], v[116:117], v[40:41], v[14:15] op_sel_hi:[0,1,1]
	v_pk_fma_f32 v[16:17], v[116:117], v[48:49], v[16:17] op_sel_hi:[0,1,1]
	v_pk_fma_f32 v[18:19], v[116:117], v[56:57], v[18:19] op_sel_hi:[0,1,1]
	v_fmac_f32_e32 v8, v116, v61
	global_load_dword v110, v200, s[24:25]
	s_add_u32 s24, s24, 0x6000
	s_addc_u32 s25, s25, 0
	global_load_dword v112, v200, s[24:25]
	s_add_u32 s24, s24, 0x6000
	s_addc_u32 s25, s25, 0
	global_load_dword v114, v200, s[24:25]
	s_add_u32 s24, s24, 0x6000
	s_addc_u32 s25, s25, 0
	global_load_dword v116, v200, s[24:25]
	s_add_u32 s24, s24, 0x6000
	s_addc_u32 s25, s25, 0
	s_waitcnt vmcnt(56)
	v_add_u32_e32 v25, s20, v23
	ds_read_b128 v[26:29], v25
	ds_read_b128 v[30:33], v25 offset:8192
	ds_read_b128 v[34:37], v25 offset:16384
	ds_read_b128 v[38:41], v25 offset:24576
	ds_read_b128 v[42:45], v25 offset:32768
	ds_read_b128 v[46:49], v25 offset:40960
	ds_read_b128 v[50:53], v25 offset:49152
	ds_read_b128 v[54:57], v25 offset:57344
	v_add_u32_e32 v25, 0x10000, v25
	ds_read_b128 v[58:61], v25
	s_waitcnt lgkmcnt(6)
	v_mov_b32_e32 v70, v34
	v_mov_b32_e32 v71, v30
	v_mov_b32_e32 v72, v26
	s_waitcnt lgkmcnt(5)
	v_mov_b32_e32 v73, v38
	s_waitcnt lgkmcnt(4)
	v_mov_b32_e32 v74, v42
	s_waitcnt lgkmcnt(3)
	v_mov_b32_e32 v75, v46
	s_waitcnt lgkmcnt(2)
	v_mov_b32_e32 v76, v50
	s_waitcnt lgkmcnt(1)
	v_mov_b32_e32 v77, v54
	v_mov_b32_e32 v30, v35
	v_mov_b32_e32 v38, v27
	v_mov_b32_e32 v46, v43
	v_mov_b32_e32 v54, v51
	v_mov_b32_e32 v26, v36
	v_mov_b32_e32 v27, v32
	v_mov_b32_e32 v34, v28
	v_mov_b32_e32 v35, v40
	v_mov_b32_e32 v42, v44
	v_mov_b32_e32 v43, v48
	v_mov_b32_e32 v50, v52
	v_mov_b32_e32 v51, v56
	s_add_i32 s20, s20, 16
	v_mov_b32_e32 v32, v37
	v_mov_b32_e32 v40, v29
	v_mov_b32_e32 v48, v45
	v_mov_b32_e32 v56, v53
	v_pk_fma_f32 v[12:13], v[118:119], v[70:71], v[12:13] op_sel_hi:[0,1,1]
	v_pk_fma_f32 v[14:15], v[118:119], v[72:73], v[14:15] op_sel_hi:[0,1,1]
	v_pk_fma_f32 v[16:17], v[118:119], v[74:75], v[16:17] op_sel_hi:[0,1,1]
	v_pk_fma_f32 v[18:19], v[118:119], v[76:77], v[18:19] op_sel_hi:[0,1,1]
	s_waitcnt lgkmcnt(0)
	v_fmac_f32_e32 v8, v118, v58
	v_pk_fma_f32 v[12:13], v[120:121], v[30:31], v[12:13] op_sel_hi:[0,1,1]
	v_pk_fma_f32 v[14:15], v[120:121], v[38:39], v[14:15] op_sel_hi:[0,1,1]
	v_pk_fma_f32 v[16:17], v[120:121], v[46:47], v[16:17] op_sel_hi:[0,1,1]
	v_pk_fma_f32 v[18:19], v[120:121], v[54:55], v[18:19] op_sel_hi:[0,1,1]
	v_fmac_f32_e32 v8, v120, v59
	v_pk_fma_f32 v[12:13], v[122:123], v[26:27], v[12:13] op_sel_hi:[0,1,1]
	v_pk_fma_f32 v[14:15], v[122:123], v[34:35], v[14:15] op_sel_hi:[0,1,1]
	v_pk_fma_f32 v[16:17], v[122:123], v[42:43], v[16:17] op_sel_hi:[0,1,1]
	v_pk_fma_f32 v[18:19], v[122:123], v[50:51], v[18:19] op_sel_hi:[0,1,1]
	v_fmac_f32_e32 v8, v122, v60
	v_pk_fma_f32 v[12:13], v[124:125], v[32:33], v[12:13] op_sel_hi:[0,1,1]
	v_pk_fma_f32 v[14:15], v[124:125], v[40:41], v[14:15] op_sel_hi:[0,1,1]
	v_pk_fma_f32 v[16:17], v[124:125], v[48:49], v[16:17] op_sel_hi:[0,1,1]
	v_pk_fma_f32 v[18:19], v[124:125], v[56:57], v[18:19] op_sel_hi:[0,1,1]
	v_fmac_f32_e32 v8, v124, v61
	global_load_dword v118, v200, s[24:25]
	s_add_u32 s24, s24, 0x6000
	s_addc_u32 s25, s25, 0
	global_load_dword v120, v200, s[24:25]
	s_add_u32 s24, s24, 0x6000
	s_addc_u32 s25, s25, 0
	global_load_dword v122, v200, s[24:25]
	s_add_u32 s24, s24, 0x6000
	s_addc_u32 s25, s25, 0
	global_load_dword v124, v200, s[24:25]
	s_add_u32 s24, s24, 0x6000
	s_addc_u32 s25, s25, 0
	s_waitcnt vmcnt(56)
	v_add_u32_e32 v25, s20, v23
	ds_read_b128 v[26:29], v25
	ds_read_b128 v[30:33], v25 offset:8192
	ds_read_b128 v[34:37], v25 offset:16384
	ds_read_b128 v[38:41], v25 offset:24576
	ds_read_b128 v[42:45], v25 offset:32768
	ds_read_b128 v[46:49], v25 offset:40960
	ds_read_b128 v[50:53], v25 offset:49152
	ds_read_b128 v[54:57], v25 offset:57344
	v_add_u32_e32 v25, 0x10000, v25
	ds_read_b128 v[58:61], v25
	s_waitcnt lgkmcnt(6)
	v_mov_b32_e32 v70, v34
	v_mov_b32_e32 v71, v30
	v_mov_b32_e32 v72, v26
	s_waitcnt lgkmcnt(5)
	v_mov_b32_e32 v73, v38
	s_waitcnt lgkmcnt(4)
	v_mov_b32_e32 v74, v42
	s_waitcnt lgkmcnt(3)
	v_mov_b32_e32 v75, v46
	s_waitcnt lgkmcnt(2)
	v_mov_b32_e32 v76, v50
	s_waitcnt lgkmcnt(1)
	v_mov_b32_e32 v77, v54
	v_mov_b32_e32 v30, v35
	v_mov_b32_e32 v38, v27
	v_mov_b32_e32 v46, v43
	v_mov_b32_e32 v54, v51
	v_mov_b32_e32 v26, v36
	v_mov_b32_e32 v27, v32
	v_mov_b32_e32 v34, v28
	v_mov_b32_e32 v35, v40
	v_mov_b32_e32 v42, v44
	v_mov_b32_e32 v43, v48
	v_mov_b32_e32 v50, v52
	v_mov_b32_e32 v51, v56
	s_add_i32 s20, s20, 16
	v_mov_b32_e32 v32, v37
	v_mov_b32_e32 v40, v29
	v_mov_b32_e32 v48, v45
	v_mov_b32_e32 v56, v53
	v_pk_fma_f32 v[12:13], v[126:127], v[70:71], v[12:13] op_sel_hi:[0,1,1]
	v_pk_fma_f32 v[14:15], v[126:127], v[72:73], v[14:15] op_sel_hi:[0,1,1]
	v_pk_fma_f32 v[16:17], v[126:127], v[74:75], v[16:17] op_sel_hi:[0,1,1]
	v_pk_fma_f32 v[18:19], v[126:127], v[76:77], v[18:19] op_sel_hi:[0,1,1]
	s_waitcnt lgkmcnt(0)
	v_fmac_f32_e32 v8, v126, v58
	v_pk_fma_f32 v[12:13], v[128:129], v[30:31], v[12:13] op_sel_hi:[0,1,1]
	v_pk_fma_f32 v[14:15], v[128:129], v[38:39], v[14:15] op_sel_hi:[0,1,1]
	v_pk_fma_f32 v[16:17], v[128:129], v[46:47], v[16:17] op_sel_hi:[0,1,1]
	v_pk_fma_f32 v[18:19], v[128:129], v[54:55], v[18:19] op_sel_hi:[0,1,1]
	v_fmac_f32_e32 v8, v128, v59
	v_pk_fma_f32 v[12:13], v[130:131], v[26:27], v[12:13] op_sel_hi:[0,1,1]
	v_pk_fma_f32 v[14:15], v[130:131], v[34:35], v[14:15] op_sel_hi:[0,1,1]
	v_pk_fma_f32 v[16:17], v[130:131], v[42:43], v[16:17] op_sel_hi:[0,1,1]
	v_pk_fma_f32 v[18:19], v[130:131], v[50:51], v[18:19] op_sel_hi:[0,1,1]
	v_fmac_f32_e32 v8, v130, v60
	v_pk_fma_f32 v[12:13], v[132:133], v[32:33], v[12:13] op_sel_hi:[0,1,1]
	v_pk_fma_f32 v[14:15], v[132:133], v[40:41], v[14:15] op_sel_hi:[0,1,1]
	v_pk_fma_f32 v[16:17], v[132:133], v[48:49], v[16:17] op_sel_hi:[0,1,1]
	v_pk_fma_f32 v[18:19], v[132:133], v[56:57], v[18:19] op_sel_hi:[0,1,1]
	v_fmac_f32_e32 v8, v132, v61
	global_load_dword v126, v200, s[24:25]
	s_add_u32 s24, s24, 0x6000
	s_addc_u32 s25, s25, 0
	global_load_dword v128, v200, s[24:25]
	s_add_u32 s24, s24, 0x6000
	s_addc_u32 s25, s25, 0
	global_load_dword v130, v200, s[24:25]
	s_add_u32 s24, s24, 0x6000
	s_addc_u32 s25, s25, 0
	global_load_dword v132, v200, s[24:25]
	s_add_u32 s24, s24, 0x6000
	s_addc_u32 s25, s25, 0
	s_waitcnt vmcnt(56)
	v_add_u32_e32 v25, s20, v23
	ds_read_b128 v[26:29], v25
	ds_read_b128 v[30:33], v25 offset:8192
	ds_read_b128 v[34:37], v25 offset:16384
	ds_read_b128 v[38:41], v25 offset:24576
	ds_read_b128 v[42:45], v25 offset:32768
	ds_read_b128 v[46:49], v25 offset:40960
	ds_read_b128 v[50:53], v25 offset:49152
	ds_read_b128 v[54:57], v25 offset:57344
	v_add_u32_e32 v25, 0x10000, v25
	ds_read_b128 v[58:61], v25
	s_waitcnt lgkmcnt(6)
	v_mov_b32_e32 v70, v34
	v_mov_b32_e32 v71, v30
	v_mov_b32_e32 v72, v26
	s_waitcnt lgkmcnt(5)
	v_mov_b32_e32 v73, v38
	s_waitcnt lgkmcnt(4)
	v_mov_b32_e32 v74, v42
	s_waitcnt lgkmcnt(3)
	v_mov_b32_e32 v75, v46
	s_waitcnt lgkmcnt(2)
	v_mov_b32_e32 v76, v50
	s_waitcnt lgkmcnt(1)
	v_mov_b32_e32 v77, v54
	v_mov_b32_e32 v30, v35
	v_mov_b32_e32 v38, v27
	v_mov_b32_e32 v46, v43
	v_mov_b32_e32 v54, v51
	v_mov_b32_e32 v26, v36
	v_mov_b32_e32 v27, v32
	v_mov_b32_e32 v34, v28
	v_mov_b32_e32 v35, v40
	v_mov_b32_e32 v42, v44
	v_mov_b32_e32 v43, v48
	v_mov_b32_e32 v50, v52
	v_mov_b32_e32 v51, v56
	s_add_i32 s20, s20, 16
	v_mov_b32_e32 v32, v37
	v_mov_b32_e32 v40, v29
	v_mov_b32_e32 v48, v45
	v_mov_b32_e32 v56, v53
	v_pk_fma_f32 v[12:13], v[134:135], v[70:71], v[12:13] op_sel_hi:[0,1,1]
	v_pk_fma_f32 v[14:15], v[134:135], v[72:73], v[14:15] op_sel_hi:[0,1,1]
	v_pk_fma_f32 v[16:17], v[134:135], v[74:75], v[16:17] op_sel_hi:[0,1,1]
	v_pk_fma_f32 v[18:19], v[134:135], v[76:77], v[18:19] op_sel_hi:[0,1,1]
	s_waitcnt lgkmcnt(0)
	v_fmac_f32_e32 v8, v134, v58
	v_pk_fma_f32 v[12:13], v[136:137], v[30:31], v[12:13] op_sel_hi:[0,1,1]
	v_pk_fma_f32 v[14:15], v[136:137], v[38:39], v[14:15] op_sel_hi:[0,1,1]
	v_pk_fma_f32 v[16:17], v[136:137], v[46:47], v[16:17] op_sel_hi:[0,1,1]
	v_pk_fma_f32 v[18:19], v[136:137], v[54:55], v[18:19] op_sel_hi:[0,1,1]
	v_fmac_f32_e32 v8, v136, v59
	v_pk_fma_f32 v[12:13], v[138:139], v[26:27], v[12:13] op_sel_hi:[0,1,1]
	v_pk_fma_f32 v[14:15], v[138:139], v[34:35], v[14:15] op_sel_hi:[0,1,1]
	v_pk_fma_f32 v[16:17], v[138:139], v[42:43], v[16:17] op_sel_hi:[0,1,1]
	v_pk_fma_f32 v[18:19], v[138:139], v[50:51], v[18:19] op_sel_hi:[0,1,1]
	v_fmac_f32_e32 v8, v138, v60
	v_pk_fma_f32 v[12:13], v[140:141], v[32:33], v[12:13] op_sel_hi:[0,1,1]
	v_pk_fma_f32 v[14:15], v[140:141], v[40:41], v[14:15] op_sel_hi:[0,1,1]
	v_pk_fma_f32 v[16:17], v[140:141], v[48:49], v[16:17] op_sel_hi:[0,1,1]
	v_pk_fma_f32 v[18:19], v[140:141], v[56:57], v[18:19] op_sel_hi:[0,1,1]
	v_fmac_f32_e32 v8, v140, v61
	global_load_dword v134, v200, s[24:25]
	s_add_u32 s24, s24, 0x6000
	s_addc_u32 s25, s25, 0
	global_load_dword v136, v200, s[24:25]
	s_add_u32 s24, s24, 0x6000
	s_addc_u32 s25, s25, 0
	global_load_dword v138, v200, s[24:25]
	s_add_u32 s24, s24, 0x6000
	s_addc_u32 s25, s25, 0
	global_load_dword v140, v200, s[24:25]
	s_add_u32 s24, s24, 0x6000
	s_addc_u32 s25, s25, 0
	s_waitcnt vmcnt(56)
	v_add_u32_e32 v25, s20, v23
	ds_read_b128 v[26:29], v25
	ds_read_b128 v[30:33], v25 offset:8192
	ds_read_b128 v[34:37], v25 offset:16384
	ds_read_b128 v[38:41], v25 offset:24576
	ds_read_b128 v[42:45], v25 offset:32768
	ds_read_b128 v[46:49], v25 offset:40960
	ds_read_b128 v[50:53], v25 offset:49152
	ds_read_b128 v[54:57], v25 offset:57344
	v_add_u32_e32 v25, 0x10000, v25
	ds_read_b128 v[58:61], v25
	s_waitcnt lgkmcnt(6)
	v_mov_b32_e32 v70, v34
	v_mov_b32_e32 v71, v30
	v_mov_b32_e32 v72, v26
	s_waitcnt lgkmcnt(5)
	v_mov_b32_e32 v73, v38
	s_waitcnt lgkmcnt(4)
	v_mov_b32_e32 v74, v42
	s_waitcnt lgkmcnt(3)
	v_mov_b32_e32 v75, v46
	s_waitcnt lgkmcnt(2)
	v_mov_b32_e32 v76, v50
	s_waitcnt lgkmcnt(1)
	v_mov_b32_e32 v77, v54
	v_mov_b32_e32 v30, v35
	v_mov_b32_e32 v38, v27
	v_mov_b32_e32 v46, v43
	v_mov_b32_e32 v54, v51
	v_mov_b32_e32 v26, v36
	v_mov_b32_e32 v27, v32
	v_mov_b32_e32 v34, v28
	v_mov_b32_e32 v35, v40
	v_mov_b32_e32 v42, v44
	v_mov_b32_e32 v43, v48
	v_mov_b32_e32 v50, v52
	v_mov_b32_e32 v51, v56
	s_add_i32 s20, s20, 16
	v_mov_b32_e32 v32, v37
	v_mov_b32_e32 v40, v29
	v_mov_b32_e32 v48, v45
	v_mov_b32_e32 v56, v53
	v_pk_fma_f32 v[12:13], v[142:143], v[70:71], v[12:13] op_sel_hi:[0,1,1]
	v_pk_fma_f32 v[14:15], v[142:143], v[72:73], v[14:15] op_sel_hi:[0,1,1]
	v_pk_fma_f32 v[16:17], v[142:143], v[74:75], v[16:17] op_sel_hi:[0,1,1]
	v_pk_fma_f32 v[18:19], v[142:143], v[76:77], v[18:19] op_sel_hi:[0,1,1]
	s_waitcnt lgkmcnt(0)
	v_fmac_f32_e32 v8, v142, v58
	v_pk_fma_f32 v[12:13], v[144:145], v[30:31], v[12:13] op_sel_hi:[0,1,1]
	v_pk_fma_f32 v[14:15], v[144:145], v[38:39], v[14:15] op_sel_hi:[0,1,1]
	v_pk_fma_f32 v[16:17], v[144:145], v[46:47], v[16:17] op_sel_hi:[0,1,1]
	v_pk_fma_f32 v[18:19], v[144:145], v[54:55], v[18:19] op_sel_hi:[0,1,1]
	v_fmac_f32_e32 v8, v144, v59
	v_pk_fma_f32 v[12:13], v[146:147], v[26:27], v[12:13] op_sel_hi:[0,1,1]
	v_pk_fma_f32 v[14:15], v[146:147], v[34:35], v[14:15] op_sel_hi:[0,1,1]
	v_pk_fma_f32 v[16:17], v[146:147], v[42:43], v[16:17] op_sel_hi:[0,1,1]
	v_pk_fma_f32 v[18:19], v[146:147], v[50:51], v[18:19] op_sel_hi:[0,1,1]
	v_fmac_f32_e32 v8, v146, v60
	v_pk_fma_f32 v[12:13], v[148:149], v[32:33], v[12:13] op_sel_hi:[0,1,1]
	v_pk_fma_f32 v[14:15], v[148:149], v[40:41], v[14:15] op_sel_hi:[0,1,1]
	v_pk_fma_f32 v[16:17], v[148:149], v[48:49], v[16:17] op_sel_hi:[0,1,1]
	v_pk_fma_f32 v[18:19], v[148:149], v[56:57], v[18:19] op_sel_hi:[0,1,1]
	v_fmac_f32_e32 v8, v148, v61
	global_load_dword v142, v200, s[24:25]
	s_add_u32 s24, s24, 0x6000
	s_addc_u32 s25, s25, 0
	global_load_dword v144, v200, s[24:25]
	s_add_u32 s24, s24, 0x6000
	s_addc_u32 s25, s25, 0
	global_load_dword v146, v200, s[24:25]
	s_add_u32 s24, s24, 0x6000
	s_addc_u32 s25, s25, 0
	global_load_dword v148, v200, s[24:25]
	s_add_u32 s24, s24, 0x6000
	s_addc_u32 s25, s25, 0
	s_waitcnt vmcnt(56)
	v_add_u32_e32 v25, s20, v23
	ds_read_b128 v[26:29], v25
	ds_read_b128 v[30:33], v25 offset:8192
	ds_read_b128 v[34:37], v25 offset:16384
	ds_read_b128 v[38:41], v25 offset:24576
	ds_read_b128 v[42:45], v25 offset:32768
	ds_read_b128 v[46:49], v25 offset:40960
	ds_read_b128 v[50:53], v25 offset:49152
	ds_read_b128 v[54:57], v25 offset:57344
	v_add_u32_e32 v25, 0x10000, v25
	ds_read_b128 v[58:61], v25
	s_waitcnt lgkmcnt(6)
	v_mov_b32_e32 v70, v34
	v_mov_b32_e32 v71, v30
	v_mov_b32_e32 v72, v26
	s_waitcnt lgkmcnt(5)
	v_mov_b32_e32 v73, v38
	s_waitcnt lgkmcnt(4)
	v_mov_b32_e32 v74, v42
	s_waitcnt lgkmcnt(3)
	v_mov_b32_e32 v75, v46
	s_waitcnt lgkmcnt(2)
	v_mov_b32_e32 v76, v50
	s_waitcnt lgkmcnt(1)
	v_mov_b32_e32 v77, v54
	v_mov_b32_e32 v30, v35
	v_mov_b32_e32 v38, v27
	v_mov_b32_e32 v46, v43
	v_mov_b32_e32 v54, v51
	v_mov_b32_e32 v26, v36
	v_mov_b32_e32 v27, v32
	v_mov_b32_e32 v34, v28
	v_mov_b32_e32 v35, v40
	v_mov_b32_e32 v42, v44
	v_mov_b32_e32 v43, v48
	v_mov_b32_e32 v50, v52
	v_mov_b32_e32 v51, v56
	s_add_i32 s20, s20, 16
	v_mov_b32_e32 v32, v37
	v_mov_b32_e32 v40, v29
	v_mov_b32_e32 v48, v45
	v_mov_b32_e32 v56, v53
	v_pk_fma_f32 v[12:13], v[150:151], v[70:71], v[12:13] op_sel_hi:[0,1,1]
	v_pk_fma_f32 v[14:15], v[150:151], v[72:73], v[14:15] op_sel_hi:[0,1,1]
	v_pk_fma_f32 v[16:17], v[150:151], v[74:75], v[16:17] op_sel_hi:[0,1,1]
	v_pk_fma_f32 v[18:19], v[150:151], v[76:77], v[18:19] op_sel_hi:[0,1,1]
	s_waitcnt lgkmcnt(0)
	v_fmac_f32_e32 v8, v150, v58
	v_pk_fma_f32 v[12:13], v[152:153], v[30:31], v[12:13] op_sel_hi:[0,1,1]
	v_pk_fma_f32 v[14:15], v[152:153], v[38:39], v[14:15] op_sel_hi:[0,1,1]
	v_pk_fma_f32 v[16:17], v[152:153], v[46:47], v[16:17] op_sel_hi:[0,1,1]
	v_pk_fma_f32 v[18:19], v[152:153], v[54:55], v[18:19] op_sel_hi:[0,1,1]
	v_fmac_f32_e32 v8, v152, v59
	v_pk_fma_f32 v[12:13], v[154:155], v[26:27], v[12:13] op_sel_hi:[0,1,1]
	v_pk_fma_f32 v[14:15], v[154:155], v[34:35], v[14:15] op_sel_hi:[0,1,1]
	v_pk_fma_f32 v[16:17], v[154:155], v[42:43], v[16:17] op_sel_hi:[0,1,1]
	v_pk_fma_f32 v[18:19], v[154:155], v[50:51], v[18:19] op_sel_hi:[0,1,1]
	v_fmac_f32_e32 v8, v154, v60
	v_pk_fma_f32 v[12:13], v[156:157], v[32:33], v[12:13] op_sel_hi:[0,1,1]
	v_pk_fma_f32 v[14:15], v[156:157], v[40:41], v[14:15] op_sel_hi:[0,1,1]
	v_pk_fma_f32 v[16:17], v[156:157], v[48:49], v[16:17] op_sel_hi:[0,1,1]
	v_pk_fma_f32 v[18:19], v[156:157], v[56:57], v[18:19] op_sel_hi:[0,1,1]
	v_fmac_f32_e32 v8, v156, v61
	global_load_dword v150, v200, s[24:25]
	s_add_u32 s24, s24, 0x6000
	s_addc_u32 s25, s25, 0
	global_load_dword v152, v200, s[24:25]
	s_add_u32 s24, s24, 0x6000
	s_addc_u32 s25, s25, 0
	global_load_dword v154, v200, s[24:25]
	s_add_u32 s24, s24, 0x6000
	s_addc_u32 s25, s25, 0
	global_load_dword v156, v200, s[24:25]
	s_add_u32 s24, s24, 0x6000
	s_addc_u32 s25, s25, 0
	s_waitcnt vmcnt(56)
	v_add_u32_e32 v25, s20, v23
	ds_read_b128 v[26:29], v25
	ds_read_b128 v[30:33], v25 offset:8192
	ds_read_b128 v[34:37], v25 offset:16384
	ds_read_b128 v[38:41], v25 offset:24576
	ds_read_b128 v[42:45], v25 offset:32768
	ds_read_b128 v[46:49], v25 offset:40960
	ds_read_b128 v[50:53], v25 offset:49152
	ds_read_b128 v[54:57], v25 offset:57344
	v_add_u32_e32 v25, 0x10000, v25
	ds_read_b128 v[58:61], v25
	s_waitcnt lgkmcnt(6)
	v_mov_b32_e32 v70, v34
	v_mov_b32_e32 v71, v30
	v_mov_b32_e32 v72, v26
	s_waitcnt lgkmcnt(5)
	v_mov_b32_e32 v73, v38
	s_waitcnt lgkmcnt(4)
	v_mov_b32_e32 v74, v42
	s_waitcnt lgkmcnt(3)
	v_mov_b32_e32 v75, v46
	s_waitcnt lgkmcnt(2)
	v_mov_b32_e32 v76, v50
	s_waitcnt lgkmcnt(1)
	v_mov_b32_e32 v77, v54
	v_mov_b32_e32 v30, v35
	v_mov_b32_e32 v38, v27
	v_mov_b32_e32 v46, v43
	v_mov_b32_e32 v54, v51
	v_mov_b32_e32 v26, v36
	v_mov_b32_e32 v27, v32
	v_mov_b32_e32 v34, v28
	v_mov_b32_e32 v35, v40
	v_mov_b32_e32 v42, v44
	v_mov_b32_e32 v43, v48
	v_mov_b32_e32 v50, v52
	v_mov_b32_e32 v51, v56
	s_add_i32 s20, s20, 16
	v_mov_b32_e32 v32, v37
	v_mov_b32_e32 v40, v29
	v_mov_b32_e32 v48, v45
	v_mov_b32_e32 v56, v53
	v_pk_fma_f32 v[12:13], v[158:159], v[70:71], v[12:13] op_sel_hi:[0,1,1]
	v_pk_fma_f32 v[14:15], v[158:159], v[72:73], v[14:15] op_sel_hi:[0,1,1]
	v_pk_fma_f32 v[16:17], v[158:159], v[74:75], v[16:17] op_sel_hi:[0,1,1]
	v_pk_fma_f32 v[18:19], v[158:159], v[76:77], v[18:19] op_sel_hi:[0,1,1]
	s_waitcnt lgkmcnt(0)
	v_fmac_f32_e32 v8, v158, v58
	v_pk_fma_f32 v[12:13], v[160:161], v[30:31], v[12:13] op_sel_hi:[0,1,1]
	v_pk_fma_f32 v[14:15], v[160:161], v[38:39], v[14:15] op_sel_hi:[0,1,1]
	v_pk_fma_f32 v[16:17], v[160:161], v[46:47], v[16:17] op_sel_hi:[0,1,1]
	v_pk_fma_f32 v[18:19], v[160:161], v[54:55], v[18:19] op_sel_hi:[0,1,1]
	v_fmac_f32_e32 v8, v160, v59
	v_pk_fma_f32 v[12:13], v[162:163], v[26:27], v[12:13] op_sel_hi:[0,1,1]
	v_pk_fma_f32 v[14:15], v[162:163], v[34:35], v[14:15] op_sel_hi:[0,1,1]
	v_pk_fma_f32 v[16:17], v[162:163], v[42:43], v[16:17] op_sel_hi:[0,1,1]
	v_pk_fma_f32 v[18:19], v[162:163], v[50:51], v[18:19] op_sel_hi:[0,1,1]
	v_fmac_f32_e32 v8, v162, v60
	v_pk_fma_f32 v[12:13], v[164:165], v[32:33], v[12:13] op_sel_hi:[0,1,1]
	v_pk_fma_f32 v[14:15], v[164:165], v[40:41], v[14:15] op_sel_hi:[0,1,1]
	v_pk_fma_f32 v[16:17], v[164:165], v[48:49], v[16:17] op_sel_hi:[0,1,1]
	v_pk_fma_f32 v[18:19], v[164:165], v[56:57], v[18:19] op_sel_hi:[0,1,1]
	v_fmac_f32_e32 v8, v164, v61
	global_load_dword v158, v200, s[24:25]
	s_add_u32 s24, s24, 0x6000
	s_addc_u32 s25, s25, 0
	global_load_dword v160, v200, s[24:25]
	s_add_u32 s24, s24, 0x6000
	s_addc_u32 s25, s25, 0
	global_load_dword v162, v200, s[24:25]
	s_add_u32 s24, s24, 0x6000
	s_addc_u32 s25, s25, 0
	global_load_dword v164, v200, s[24:25]
	s_add_u32 s24, s24, 0x6000
	s_addc_u32 s25, s25, 0
	s_waitcnt vmcnt(56)
	v_add_u32_e32 v25, s20, v23
	ds_read_b128 v[26:29], v25
	ds_read_b128 v[30:33], v25 offset:8192
	ds_read_b128 v[34:37], v25 offset:16384
	ds_read_b128 v[38:41], v25 offset:24576
	ds_read_b128 v[42:45], v25 offset:32768
	ds_read_b128 v[46:49], v25 offset:40960
	ds_read_b128 v[50:53], v25 offset:49152
	ds_read_b128 v[54:57], v25 offset:57344
	v_add_u32_e32 v25, 0x10000, v25
	ds_read_b128 v[58:61], v25
	s_waitcnt lgkmcnt(6)
	v_mov_b32_e32 v70, v34
	v_mov_b32_e32 v71, v30
	v_mov_b32_e32 v72, v26
	s_waitcnt lgkmcnt(5)
	v_mov_b32_e32 v73, v38
	s_waitcnt lgkmcnt(4)
	v_mov_b32_e32 v74, v42
	s_waitcnt lgkmcnt(3)
	v_mov_b32_e32 v75, v46
	s_waitcnt lgkmcnt(2)
	v_mov_b32_e32 v76, v50
	s_waitcnt lgkmcnt(1)
	v_mov_b32_e32 v77, v54
	v_mov_b32_e32 v30, v35
	v_mov_b32_e32 v38, v27
	v_mov_b32_e32 v46, v43
	v_mov_b32_e32 v54, v51
	v_mov_b32_e32 v26, v36
	v_mov_b32_e32 v27, v32
	v_mov_b32_e32 v34, v28
	v_mov_b32_e32 v35, v40
	v_mov_b32_e32 v42, v44
	v_mov_b32_e32 v43, v48
	v_mov_b32_e32 v50, v52
	v_mov_b32_e32 v51, v56
	s_add_i32 s20, s20, 16
	v_mov_b32_e32 v32, v37
	v_mov_b32_e32 v40, v29
	v_mov_b32_e32 v48, v45
	v_mov_b32_e32 v56, v53
	v_pk_fma_f32 v[12:13], v[166:167], v[70:71], v[12:13] op_sel_hi:[0,1,1]
	v_pk_fma_f32 v[14:15], v[166:167], v[72:73], v[14:15] op_sel_hi:[0,1,1]
	v_pk_fma_f32 v[16:17], v[166:167], v[74:75], v[16:17] op_sel_hi:[0,1,1]
	v_pk_fma_f32 v[18:19], v[166:167], v[76:77], v[18:19] op_sel_hi:[0,1,1]
	s_waitcnt lgkmcnt(0)
	v_fmac_f32_e32 v8, v166, v58
	v_pk_fma_f32 v[12:13], v[168:169], v[30:31], v[12:13] op_sel_hi:[0,1,1]
	v_pk_fma_f32 v[14:15], v[168:169], v[38:39], v[14:15] op_sel_hi:[0,1,1]
	v_pk_fma_f32 v[16:17], v[168:169], v[46:47], v[16:17] op_sel_hi:[0,1,1]
	v_pk_fma_f32 v[18:19], v[168:169], v[54:55], v[18:19] op_sel_hi:[0,1,1]
	v_fmac_f32_e32 v8, v168, v59
	v_pk_fma_f32 v[12:13], v[170:171], v[26:27], v[12:13] op_sel_hi:[0,1,1]
	v_pk_fma_f32 v[14:15], v[170:171], v[34:35], v[14:15] op_sel_hi:[0,1,1]
	v_pk_fma_f32 v[16:17], v[170:171], v[42:43], v[16:17] op_sel_hi:[0,1,1]
	v_pk_fma_f32 v[18:19], v[170:171], v[50:51], v[18:19] op_sel_hi:[0,1,1]
	v_fmac_f32_e32 v8, v170, v60
	v_pk_fma_f32 v[12:13], v[172:173], v[32:33], v[12:13] op_sel_hi:[0,1,1]
	v_pk_fma_f32 v[14:15], v[172:173], v[40:41], v[14:15] op_sel_hi:[0,1,1]
	v_pk_fma_f32 v[16:17], v[172:173], v[48:49], v[16:17] op_sel_hi:[0,1,1]
	v_pk_fma_f32 v[18:19], v[172:173], v[56:57], v[18:19] op_sel_hi:[0,1,1]
	v_fmac_f32_e32 v8, v172, v61
	global_load_dword v166, v200, s[24:25]
	s_add_u32 s24, s24, 0x6000
	s_addc_u32 s25, s25, 0
	global_load_dword v168, v200, s[24:25]
	s_add_u32 s24, s24, 0x6000
	s_addc_u32 s25, s25, 0
	global_load_dword v170, v200, s[24:25]
	s_add_u32 s24, s24, 0x6000
	s_addc_u32 s25, s25, 0
	global_load_dword v172, v200, s[24:25]
	s_add_u32 s24, s24, 0x6000
	s_addc_u32 s25, s25, 0
	s_waitcnt vmcnt(56)
	v_add_u32_e32 v25, s20, v23
	ds_read_b128 v[26:29], v25
	ds_read_b128 v[30:33], v25 offset:8192
	ds_read_b128 v[34:37], v25 offset:16384
	ds_read_b128 v[38:41], v25 offset:24576
	ds_read_b128 v[42:45], v25 offset:32768
	ds_read_b128 v[46:49], v25 offset:40960
	ds_read_b128 v[50:53], v25 offset:49152
	ds_read_b128 v[54:57], v25 offset:57344
	v_add_u32_e32 v25, 0x10000, v25
	ds_read_b128 v[58:61], v25
	s_waitcnt lgkmcnt(6)
	v_mov_b32_e32 v70, v34
	v_mov_b32_e32 v71, v30
	v_mov_b32_e32 v72, v26
	s_waitcnt lgkmcnt(5)
	v_mov_b32_e32 v73, v38
	s_waitcnt lgkmcnt(4)
	v_mov_b32_e32 v74, v42
	s_waitcnt lgkmcnt(3)
	v_mov_b32_e32 v75, v46
	s_waitcnt lgkmcnt(2)
	v_mov_b32_e32 v76, v50
	s_waitcnt lgkmcnt(1)
	v_mov_b32_e32 v77, v54
	v_mov_b32_e32 v30, v35
	v_mov_b32_e32 v38, v27
	v_mov_b32_e32 v46, v43
	v_mov_b32_e32 v54, v51
	v_mov_b32_e32 v26, v36
	v_mov_b32_e32 v27, v32
	v_mov_b32_e32 v34, v28
	v_mov_b32_e32 v35, v40
	v_mov_b32_e32 v42, v44
	v_mov_b32_e32 v43, v48
	v_mov_b32_e32 v50, v52
	v_mov_b32_e32 v51, v56
	s_add_i32 s20, s20, 16
	v_mov_b32_e32 v32, v37
	v_mov_b32_e32 v40, v29
	v_mov_b32_e32 v48, v45
	v_mov_b32_e32 v56, v53
	v_pk_fma_f32 v[12:13], v[174:175], v[70:71], v[12:13] op_sel_hi:[0,1,1]
	v_pk_fma_f32 v[14:15], v[174:175], v[72:73], v[14:15] op_sel_hi:[0,1,1]
	v_pk_fma_f32 v[16:17], v[174:175], v[74:75], v[16:17] op_sel_hi:[0,1,1]
	v_pk_fma_f32 v[18:19], v[174:175], v[76:77], v[18:19] op_sel_hi:[0,1,1]
	s_waitcnt lgkmcnt(0)
	v_fmac_f32_e32 v8, v174, v58
	v_pk_fma_f32 v[12:13], v[176:177], v[30:31], v[12:13] op_sel_hi:[0,1,1]
	v_pk_fma_f32 v[14:15], v[176:177], v[38:39], v[14:15] op_sel_hi:[0,1,1]
	v_pk_fma_f32 v[16:17], v[176:177], v[46:47], v[16:17] op_sel_hi:[0,1,1]
	v_pk_fma_f32 v[18:19], v[176:177], v[54:55], v[18:19] op_sel_hi:[0,1,1]
	v_fmac_f32_e32 v8, v176, v59
	v_pk_fma_f32 v[12:13], v[178:179], v[26:27], v[12:13] op_sel_hi:[0,1,1]
	v_pk_fma_f32 v[14:15], v[178:179], v[34:35], v[14:15] op_sel_hi:[0,1,1]
	v_pk_fma_f32 v[16:17], v[178:179], v[42:43], v[16:17] op_sel_hi:[0,1,1]
	v_pk_fma_f32 v[18:19], v[178:179], v[50:51], v[18:19] op_sel_hi:[0,1,1]
	v_fmac_f32_e32 v8, v178, v60
	v_pk_fma_f32 v[12:13], v[180:181], v[32:33], v[12:13] op_sel_hi:[0,1,1]
	v_pk_fma_f32 v[14:15], v[180:181], v[40:41], v[14:15] op_sel_hi:[0,1,1]
	v_pk_fma_f32 v[16:17], v[180:181], v[48:49], v[16:17] op_sel_hi:[0,1,1]
	v_pk_fma_f32 v[18:19], v[180:181], v[56:57], v[18:19] op_sel_hi:[0,1,1]
	v_fmac_f32_e32 v8, v180, v61
	global_load_dword v174, v200, s[24:25]
	s_add_u32 s24, s24, 0x6000
	s_addc_u32 s25, s25, 0
	global_load_dword v176, v200, s[24:25]
	s_add_u32 s24, s24, 0x6000
	s_addc_u32 s25, s25, 0
	global_load_dword v178, v200, s[24:25]
	s_add_u32 s24, s24, 0x6000
	s_addc_u32 s25, s25, 0
	global_load_dword v180, v200, s[24:25]
	s_add_u32 s24, s24, 0x6000
	s_addc_u32 s25, s25, 0
	s_waitcnt vmcnt(56)
	v_add_u32_e32 v25, s20, v23
	ds_read_b128 v[26:29], v25
	ds_read_b128 v[30:33], v25 offset:8192
	ds_read_b128 v[34:37], v25 offset:16384
	ds_read_b128 v[38:41], v25 offset:24576
	ds_read_b128 v[42:45], v25 offset:32768
	ds_read_b128 v[46:49], v25 offset:40960
	ds_read_b128 v[50:53], v25 offset:49152
	ds_read_b128 v[54:57], v25 offset:57344
	v_add_u32_e32 v25, 0x10000, v25
	ds_read_b128 v[58:61], v25
	s_waitcnt lgkmcnt(6)
	v_mov_b32_e32 v70, v34
	v_mov_b32_e32 v71, v30
	v_mov_b32_e32 v72, v26
	s_waitcnt lgkmcnt(5)
	v_mov_b32_e32 v73, v38
	s_waitcnt lgkmcnt(4)
	v_mov_b32_e32 v74, v42
	s_waitcnt lgkmcnt(3)
	v_mov_b32_e32 v75, v46
	s_waitcnt lgkmcnt(2)
	v_mov_b32_e32 v76, v50
	s_waitcnt lgkmcnt(1)
	v_mov_b32_e32 v77, v54
	v_mov_b32_e32 v30, v35
	v_mov_b32_e32 v38, v27
	v_mov_b32_e32 v46, v43
	v_mov_b32_e32 v54, v51
	v_mov_b32_e32 v26, v36
	v_mov_b32_e32 v27, v32
	v_mov_b32_e32 v34, v28
	v_mov_b32_e32 v35, v40
	v_mov_b32_e32 v42, v44
	v_mov_b32_e32 v43, v48
	v_mov_b32_e32 v50, v52
	v_mov_b32_e32 v51, v56
	s_add_i32 s20, s20, 16
	v_mov_b32_e32 v32, v37
	v_mov_b32_e32 v40, v29
	v_mov_b32_e32 v48, v45
	v_mov_b32_e32 v56, v53
	v_pk_fma_f32 v[12:13], v[182:183], v[70:71], v[12:13] op_sel_hi:[0,1,1]
	v_pk_fma_f32 v[14:15], v[182:183], v[72:73], v[14:15] op_sel_hi:[0,1,1]
	v_pk_fma_f32 v[16:17], v[182:183], v[74:75], v[16:17] op_sel_hi:[0,1,1]
	v_pk_fma_f32 v[18:19], v[182:183], v[76:77], v[18:19] op_sel_hi:[0,1,1]
	s_waitcnt lgkmcnt(0)
	v_fmac_f32_e32 v8, v182, v58
	v_pk_fma_f32 v[12:13], v[184:185], v[30:31], v[12:13] op_sel_hi:[0,1,1]
	v_pk_fma_f32 v[14:15], v[184:185], v[38:39], v[14:15] op_sel_hi:[0,1,1]
	v_pk_fma_f32 v[16:17], v[184:185], v[46:47], v[16:17] op_sel_hi:[0,1,1]
	v_pk_fma_f32 v[18:19], v[184:185], v[54:55], v[18:19] op_sel_hi:[0,1,1]
	v_fmac_f32_e32 v8, v184, v59
	v_pk_fma_f32 v[12:13], v[186:187], v[26:27], v[12:13] op_sel_hi:[0,1,1]
	v_pk_fma_f32 v[14:15], v[186:187], v[34:35], v[14:15] op_sel_hi:[0,1,1]
	v_pk_fma_f32 v[16:17], v[186:187], v[42:43], v[16:17] op_sel_hi:[0,1,1]
	v_pk_fma_f32 v[18:19], v[186:187], v[50:51], v[18:19] op_sel_hi:[0,1,1]
	v_fmac_f32_e32 v8, v186, v60
	v_pk_fma_f32 v[12:13], v[188:189], v[32:33], v[12:13] op_sel_hi:[0,1,1]
	v_pk_fma_f32 v[14:15], v[188:189], v[40:41], v[14:15] op_sel_hi:[0,1,1]
	v_pk_fma_f32 v[16:17], v[188:189], v[48:49], v[16:17] op_sel_hi:[0,1,1]
	v_pk_fma_f32 v[18:19], v[188:189], v[56:57], v[18:19] op_sel_hi:[0,1,1]
	v_fmac_f32_e32 v8, v188, v61
	global_load_dword v182, v200, s[24:25]
	s_add_u32 s24, s24, 0x6000
	s_addc_u32 s25, s25, 0
	global_load_dword v184, v200, s[24:25]
	s_add_u32 s24, s24, 0x6000
	s_addc_u32 s25, s25, 0
	global_load_dword v186, v200, s[24:25]
	s_add_u32 s24, s24, 0x6000
	s_addc_u32 s25, s25, 0
	global_load_dword v188, v200, s[24:25]
	s_add_u32 s24, s24, 0x6000
	s_addc_u32 s25, s25, 0
	s_waitcnt vmcnt(56)
	v_add_u32_e32 v25, s20, v23
	ds_read_b128 v[26:29], v25
	ds_read_b128 v[30:33], v25 offset:8192
	ds_read_b128 v[34:37], v25 offset:16384
	ds_read_b128 v[38:41], v25 offset:24576
	ds_read_b128 v[42:45], v25 offset:32768
	ds_read_b128 v[46:49], v25 offset:40960
	ds_read_b128 v[50:53], v25 offset:49152
	ds_read_b128 v[54:57], v25 offset:57344
	v_add_u32_e32 v25, 0x10000, v25
	ds_read_b128 v[58:61], v25
	s_waitcnt lgkmcnt(6)
	v_mov_b32_e32 v70, v34
	v_mov_b32_e32 v71, v30
	v_mov_b32_e32 v72, v26
	s_waitcnt lgkmcnt(5)
	v_mov_b32_e32 v73, v38
	s_waitcnt lgkmcnt(4)
	v_mov_b32_e32 v74, v42
	s_waitcnt lgkmcnt(3)
	v_mov_b32_e32 v75, v46
	s_waitcnt lgkmcnt(2)
	v_mov_b32_e32 v76, v50
	s_waitcnt lgkmcnt(1)
	v_mov_b32_e32 v77, v54
	v_mov_b32_e32 v30, v35
	v_mov_b32_e32 v38, v27
	v_mov_b32_e32 v46, v43
	v_mov_b32_e32 v54, v51
	v_mov_b32_e32 v26, v36
	v_mov_b32_e32 v27, v32
	v_mov_b32_e32 v34, v28
	v_mov_b32_e32 v35, v40
	v_mov_b32_e32 v42, v44
	v_mov_b32_e32 v43, v48
	v_mov_b32_e32 v50, v52
	v_mov_b32_e32 v51, v56
	s_add_i32 s20, s20, 16
	v_mov_b32_e32 v32, v37
	v_mov_b32_e32 v40, v29
	v_mov_b32_e32 v48, v45
	v_mov_b32_e32 v56, v53
	v_pk_fma_f32 v[12:13], v[190:191], v[70:71], v[12:13] op_sel_hi:[0,1,1]
	v_pk_fma_f32 v[14:15], v[190:191], v[72:73], v[14:15] op_sel_hi:[0,1,1]
	v_pk_fma_f32 v[16:17], v[190:191], v[74:75], v[16:17] op_sel_hi:[0,1,1]
	v_pk_fma_f32 v[18:19], v[190:191], v[76:77], v[18:19] op_sel_hi:[0,1,1]
	s_waitcnt lgkmcnt(0)
	v_fmac_f32_e32 v8, v190, v58
	v_pk_fma_f32 v[12:13], v[192:193], v[30:31], v[12:13] op_sel_hi:[0,1,1]
	v_pk_fma_f32 v[14:15], v[192:193], v[38:39], v[14:15] op_sel_hi:[0,1,1]
	v_pk_fma_f32 v[16:17], v[192:193], v[46:47], v[16:17] op_sel_hi:[0,1,1]
	v_pk_fma_f32 v[18:19], v[192:193], v[54:55], v[18:19] op_sel_hi:[0,1,1]
	v_fmac_f32_e32 v8, v192, v59
	v_pk_fma_f32 v[12:13], v[194:195], v[26:27], v[12:13] op_sel_hi:[0,1,1]
	v_pk_fma_f32 v[14:15], v[194:195], v[34:35], v[14:15] op_sel_hi:[0,1,1]
	v_pk_fma_f32 v[16:17], v[194:195], v[42:43], v[16:17] op_sel_hi:[0,1,1]
	v_pk_fma_f32 v[18:19], v[194:195], v[50:51], v[18:19] op_sel_hi:[0,1,1]
	v_fmac_f32_e32 v8, v194, v60
	v_pk_fma_f32 v[12:13], v[196:197], v[32:33], v[12:13] op_sel_hi:[0,1,1]
	v_pk_fma_f32 v[14:15], v[196:197], v[40:41], v[14:15] op_sel_hi:[0,1,1]
	v_pk_fma_f32 v[16:17], v[196:197], v[48:49], v[16:17] op_sel_hi:[0,1,1]
	v_pk_fma_f32 v[18:19], v[196:197], v[56:57], v[18:19] op_sel_hi:[0,1,1]
	v_fmac_f32_e32 v8, v196, v61
	global_load_dword v190, v200, s[24:25]
	s_add_u32 s24, s24, 0x6000
	s_addc_u32 s25, s25, 0
	global_load_dword v192, v200, s[24:25]
	s_add_u32 s24, s24, 0x6000
	s_addc_u32 s25, s25, 0
	global_load_dword v194, v200, s[24:25]
	s_add_u32 s24, s24, 0x6000
	s_addc_u32 s25, s25, 0
	global_load_dword v196, v200, s[24:25]
	s_add_u32 s24, s24, 0x6000
	s_addc_u32 s25, s25, 0
	s_waitcnt vmcnt(56)
	v_add_u32_e32 v25, s20, v23
	ds_read_b128 v[26:29], v25
	ds_read_b128 v[30:33], v25 offset:8192
	ds_read_b128 v[34:37], v25 offset:16384
	ds_read_b128 v[38:41], v25 offset:24576
	ds_read_b128 v[42:45], v25 offset:32768
	ds_read_b128 v[46:49], v25 offset:40960
	ds_read_b128 v[50:53], v25 offset:49152
	ds_read_b128 v[54:57], v25 offset:57344
	v_add_u32_e32 v25, 0x10000, v25
	ds_read_b128 v[58:61], v25
	s_waitcnt lgkmcnt(6)
	v_mov_b32_e32 v70, v34
	v_mov_b32_e32 v71, v30
	v_mov_b32_e32 v72, v26
	s_waitcnt lgkmcnt(5)
	v_mov_b32_e32 v73, v38
	s_waitcnt lgkmcnt(4)
	v_mov_b32_e32 v74, v42
	s_waitcnt lgkmcnt(3)
	v_mov_b32_e32 v75, v46
	s_waitcnt lgkmcnt(2)
	v_mov_b32_e32 v76, v50
	s_waitcnt lgkmcnt(1)
	v_mov_b32_e32 v77, v54
	v_mov_b32_e32 v30, v35
	v_mov_b32_e32 v38, v27
	v_mov_b32_e32 v46, v43
	v_mov_b32_e32 v54, v51
	v_mov_b32_e32 v26, v36
	v_mov_b32_e32 v27, v32
	v_mov_b32_e32 v34, v28
	v_mov_b32_e32 v35, v40
	v_mov_b32_e32 v42, v44
	v_mov_b32_e32 v43, v48
	v_mov_b32_e32 v50, v52
	v_mov_b32_e32 v51, v56
	s_add_i32 s20, s20, 16
	v_mov_b32_e32 v32, v37
	v_mov_b32_e32 v40, v29
	v_mov_b32_e32 v48, v45
	v_mov_b32_e32 v56, v53
	v_pk_fma_f32 v[12:13], v[78:79], v[70:71], v[12:13] op_sel_hi:[0,1,1]
	v_pk_fma_f32 v[14:15], v[78:79], v[72:73], v[14:15] op_sel_hi:[0,1,1]
	v_pk_fma_f32 v[16:17], v[78:79], v[74:75], v[16:17] op_sel_hi:[0,1,1]
	v_pk_fma_f32 v[18:19], v[78:79], v[76:77], v[18:19] op_sel_hi:[0,1,1]
	s_waitcnt lgkmcnt(0)
	v_fmac_f32_e32 v8, v78, v58
	v_pk_fma_f32 v[12:13], v[80:81], v[30:31], v[12:13] op_sel_hi:[0,1,1]
	v_pk_fma_f32 v[14:15], v[80:81], v[38:39], v[14:15] op_sel_hi:[0,1,1]
	v_pk_fma_f32 v[16:17], v[80:81], v[46:47], v[16:17] op_sel_hi:[0,1,1]
	v_pk_fma_f32 v[18:19], v[80:81], v[54:55], v[18:19] op_sel_hi:[0,1,1]
	v_fmac_f32_e32 v8, v80, v59
	v_pk_fma_f32 v[12:13], v[82:83], v[26:27], v[12:13] op_sel_hi:[0,1,1]
	v_pk_fma_f32 v[14:15], v[82:83], v[34:35], v[14:15] op_sel_hi:[0,1,1]
	v_pk_fma_f32 v[16:17], v[82:83], v[42:43], v[16:17] op_sel_hi:[0,1,1]
	v_pk_fma_f32 v[18:19], v[82:83], v[50:51], v[18:19] op_sel_hi:[0,1,1]
	v_fmac_f32_e32 v8, v82, v60
	v_pk_fma_f32 v[12:13], v[84:85], v[32:33], v[12:13] op_sel_hi:[0,1,1]
	v_pk_fma_f32 v[14:15], v[84:85], v[40:41], v[14:15] op_sel_hi:[0,1,1]
	v_pk_fma_f32 v[16:17], v[84:85], v[48:49], v[16:17] op_sel_hi:[0,1,1]
	v_pk_fma_f32 v[18:19], v[84:85], v[56:57], v[18:19] op_sel_hi:[0,1,1]
	v_fmac_f32_e32 v8, v84, v61
	global_load_dword v78, v200, s[24:25]
	s_add_u32 s24, s24, 0x6000
	s_addc_u32 s25, s25, 0
	global_load_dword v80, v200, s[24:25]
	s_add_u32 s24, s24, 0x6000
	s_addc_u32 s25, s25, 0
	global_load_dword v82, v200, s[24:25]
	s_add_u32 s24, s24, 0x6000
	s_addc_u32 s25, s25, 0
	global_load_dword v84, v200, s[24:25]
	s_add_u32 s24, s24, 0x6000
	s_addc_u32 s25, s25, 0
	s_waitcnt vmcnt(56)
	v_add_u32_e32 v25, s20, v23
	ds_read_b128 v[26:29], v25
	ds_read_b128 v[30:33], v25 offset:8192
	ds_read_b128 v[34:37], v25 offset:16384
	ds_read_b128 v[38:41], v25 offset:24576
	ds_read_b128 v[42:45], v25 offset:32768
	ds_read_b128 v[46:49], v25 offset:40960
	ds_read_b128 v[50:53], v25 offset:49152
	ds_read_b128 v[54:57], v25 offset:57344
	v_add_u32_e32 v25, 0x10000, v25
	ds_read_b128 v[58:61], v25
	s_waitcnt lgkmcnt(6)
	v_mov_b32_e32 v70, v34
	v_mov_b32_e32 v71, v30
	v_mov_b32_e32 v72, v26
	s_waitcnt lgkmcnt(5)
	v_mov_b32_e32 v73, v38
	s_waitcnt lgkmcnt(4)
	v_mov_b32_e32 v74, v42
	s_waitcnt lgkmcnt(3)
	v_mov_b32_e32 v75, v46
	s_waitcnt lgkmcnt(2)
	v_mov_b32_e32 v76, v50
	s_waitcnt lgkmcnt(1)
	v_mov_b32_e32 v77, v54
	v_mov_b32_e32 v30, v35
	v_mov_b32_e32 v38, v27
	v_mov_b32_e32 v46, v43
	v_mov_b32_e32 v54, v51
	v_mov_b32_e32 v26, v36
	v_mov_b32_e32 v27, v32
	v_mov_b32_e32 v34, v28
	v_mov_b32_e32 v35, v40
	v_mov_b32_e32 v42, v44
	v_mov_b32_e32 v43, v48
	v_mov_b32_e32 v50, v52
	v_mov_b32_e32 v51, v56
	s_add_i32 s20, s20, 16
	v_mov_b32_e32 v32, v37
	v_mov_b32_e32 v40, v29
	v_mov_b32_e32 v48, v45
	v_mov_b32_e32 v56, v53
	v_pk_fma_f32 v[12:13], v[86:87], v[70:71], v[12:13] op_sel_hi:[0,1,1]
	v_pk_fma_f32 v[14:15], v[86:87], v[72:73], v[14:15] op_sel_hi:[0,1,1]
	v_pk_fma_f32 v[16:17], v[86:87], v[74:75], v[16:17] op_sel_hi:[0,1,1]
	v_pk_fma_f32 v[18:19], v[86:87], v[76:77], v[18:19] op_sel_hi:[0,1,1]
	s_waitcnt lgkmcnt(0)
	v_fmac_f32_e32 v8, v86, v58
	v_pk_fma_f32 v[12:13], v[88:89], v[30:31], v[12:13] op_sel_hi:[0,1,1]
	v_pk_fma_f32 v[14:15], v[88:89], v[38:39], v[14:15] op_sel_hi:[0,1,1]
	v_pk_fma_f32 v[16:17], v[88:89], v[46:47], v[16:17] op_sel_hi:[0,1,1]
	v_pk_fma_f32 v[18:19], v[88:89], v[54:55], v[18:19] op_sel_hi:[0,1,1]
	v_fmac_f32_e32 v8, v88, v59
	v_pk_fma_f32 v[12:13], v[90:91], v[26:27], v[12:13] op_sel_hi:[0,1,1]
	v_pk_fma_f32 v[14:15], v[90:91], v[34:35], v[14:15] op_sel_hi:[0,1,1]
	v_pk_fma_f32 v[16:17], v[90:91], v[42:43], v[16:17] op_sel_hi:[0,1,1]
	v_pk_fma_f32 v[18:19], v[90:91], v[50:51], v[18:19] op_sel_hi:[0,1,1]
	v_fmac_f32_e32 v8, v90, v60
	v_pk_fma_f32 v[12:13], v[92:93], v[32:33], v[12:13] op_sel_hi:[0,1,1]
	v_pk_fma_f32 v[14:15], v[92:93], v[40:41], v[14:15] op_sel_hi:[0,1,1]
	v_pk_fma_f32 v[16:17], v[92:93], v[48:49], v[16:17] op_sel_hi:[0,1,1]
	v_pk_fma_f32 v[18:19], v[92:93], v[56:57], v[18:19] op_sel_hi:[0,1,1]
	v_fmac_f32_e32 v8, v92, v61
	global_load_dword v86, v200, s[24:25]
	s_add_u32 s24, s24, 0x6000
	s_addc_u32 s25, s25, 0
	global_load_dword v88, v200, s[24:25]
	s_add_u32 s24, s24, 0x6000
	s_addc_u32 s25, s25, 0
	global_load_dword v90, v200, s[24:25]
	s_add_u32 s24, s24, 0x6000
	s_addc_u32 s25, s25, 0
	global_load_dword v92, v200, s[24:25]
	s_add_u32 s24, s24, 0x6000
	s_addc_u32 s25, s25, 0
	s_waitcnt vmcnt(56)
	v_add_u32_e32 v25, s20, v23
	ds_read_b128 v[26:29], v25
	ds_read_b128 v[30:33], v25 offset:8192
	ds_read_b128 v[34:37], v25 offset:16384
	ds_read_b128 v[38:41], v25 offset:24576
	ds_read_b128 v[42:45], v25 offset:32768
	ds_read_b128 v[46:49], v25 offset:40960
	ds_read_b128 v[50:53], v25 offset:49152
	ds_read_b128 v[54:57], v25 offset:57344
	v_add_u32_e32 v25, 0x10000, v25
	ds_read_b128 v[58:61], v25
	s_waitcnt lgkmcnt(6)
	v_mov_b32_e32 v70, v34
	v_mov_b32_e32 v71, v30
	v_mov_b32_e32 v72, v26
	s_waitcnt lgkmcnt(5)
	v_mov_b32_e32 v73, v38
	s_waitcnt lgkmcnt(4)
	v_mov_b32_e32 v74, v42
	s_waitcnt lgkmcnt(3)
	v_mov_b32_e32 v75, v46
	s_waitcnt lgkmcnt(2)
	v_mov_b32_e32 v76, v50
	s_waitcnt lgkmcnt(1)
	v_mov_b32_e32 v77, v54
	v_mov_b32_e32 v30, v35
	v_mov_b32_e32 v38, v27
	v_mov_b32_e32 v46, v43
	v_mov_b32_e32 v54, v51
	v_mov_b32_e32 v26, v36
	v_mov_b32_e32 v27, v32
	v_mov_b32_e32 v34, v28
	v_mov_b32_e32 v35, v40
	v_mov_b32_e32 v42, v44
	v_mov_b32_e32 v43, v48
	v_mov_b32_e32 v50, v52
	v_mov_b32_e32 v51, v56
	s_add_i32 s20, s20, 16
	v_mov_b32_e32 v32, v37
	v_mov_b32_e32 v40, v29
	v_mov_b32_e32 v48, v45
	v_mov_b32_e32 v56, v53
	v_pk_fma_f32 v[12:13], v[94:95], v[70:71], v[12:13] op_sel_hi:[0,1,1]
	v_pk_fma_f32 v[14:15], v[94:95], v[72:73], v[14:15] op_sel_hi:[0,1,1]
	v_pk_fma_f32 v[16:17], v[94:95], v[74:75], v[16:17] op_sel_hi:[0,1,1]
	v_pk_fma_f32 v[18:19], v[94:95], v[76:77], v[18:19] op_sel_hi:[0,1,1]
	s_waitcnt lgkmcnt(0)
	v_fmac_f32_e32 v8, v94, v58
	v_pk_fma_f32 v[12:13], v[96:97], v[30:31], v[12:13] op_sel_hi:[0,1,1]
	v_pk_fma_f32 v[14:15], v[96:97], v[38:39], v[14:15] op_sel_hi:[0,1,1]
	v_pk_fma_f32 v[16:17], v[96:97], v[46:47], v[16:17] op_sel_hi:[0,1,1]
	v_pk_fma_f32 v[18:19], v[96:97], v[54:55], v[18:19] op_sel_hi:[0,1,1]
	v_fmac_f32_e32 v8, v96, v59
	v_pk_fma_f32 v[12:13], v[98:99], v[26:27], v[12:13] op_sel_hi:[0,1,1]
	v_pk_fma_f32 v[14:15], v[98:99], v[34:35], v[14:15] op_sel_hi:[0,1,1]
	v_pk_fma_f32 v[16:17], v[98:99], v[42:43], v[16:17] op_sel_hi:[0,1,1]
	v_pk_fma_f32 v[18:19], v[98:99], v[50:51], v[18:19] op_sel_hi:[0,1,1]
	v_fmac_f32_e32 v8, v98, v60
	v_pk_fma_f32 v[12:13], v[100:101], v[32:33], v[12:13] op_sel_hi:[0,1,1]
	v_pk_fma_f32 v[14:15], v[100:101], v[40:41], v[14:15] op_sel_hi:[0,1,1]
	v_pk_fma_f32 v[16:17], v[100:101], v[48:49], v[16:17] op_sel_hi:[0,1,1]
	v_pk_fma_f32 v[18:19], v[100:101], v[56:57], v[18:19] op_sel_hi:[0,1,1]
	v_fmac_f32_e32 v8, v100, v61
	global_load_dword v94, v200, s[24:25]
	s_add_u32 s24, s24, 0x6000
	s_addc_u32 s25, s25, 0
	global_load_dword v96, v200, s[24:25]
	s_add_u32 s24, s24, 0x6000
	s_addc_u32 s25, s25, 0
	global_load_dword v98, v200, s[24:25]
	s_add_u32 s24, s24, 0x6000
	s_addc_u32 s25, s25, 0
	global_load_dword v100, v200, s[24:25]
	s_add_u32 s24, s24, 0x6000
	s_addc_u32 s25, s25, 0
	s_waitcnt vmcnt(56)
	v_add_u32_e32 v25, s20, v23
	ds_read_b128 v[26:29], v25
	ds_read_b128 v[30:33], v25 offset:8192
	ds_read_b128 v[34:37], v25 offset:16384
	ds_read_b128 v[38:41], v25 offset:24576
	ds_read_b128 v[42:45], v25 offset:32768
	ds_read_b128 v[46:49], v25 offset:40960
	ds_read_b128 v[50:53], v25 offset:49152
	ds_read_b128 v[54:57], v25 offset:57344
	v_add_u32_e32 v25, 0x10000, v25
	ds_read_b128 v[58:61], v25
	s_waitcnt lgkmcnt(6)
	v_mov_b32_e32 v70, v34
	v_mov_b32_e32 v71, v30
	v_mov_b32_e32 v72, v26
	s_waitcnt lgkmcnt(5)
	v_mov_b32_e32 v73, v38
	s_waitcnt lgkmcnt(4)
	v_mov_b32_e32 v74, v42
	s_waitcnt lgkmcnt(3)
	v_mov_b32_e32 v75, v46
	s_waitcnt lgkmcnt(2)
	v_mov_b32_e32 v76, v50
	s_waitcnt lgkmcnt(1)
	v_mov_b32_e32 v77, v54
	v_mov_b32_e32 v30, v35
	v_mov_b32_e32 v38, v27
	v_mov_b32_e32 v46, v43
	v_mov_b32_e32 v54, v51
	v_mov_b32_e32 v26, v36
	v_mov_b32_e32 v27, v32
	v_mov_b32_e32 v34, v28
	v_mov_b32_e32 v35, v40
	v_mov_b32_e32 v42, v44
	v_mov_b32_e32 v43, v48
	v_mov_b32_e32 v50, v52
	v_mov_b32_e32 v51, v56
	s_add_i32 s20, s20, 16
	v_mov_b32_e32 v32, v37
	v_mov_b32_e32 v40, v29
	v_mov_b32_e32 v48, v45
	v_mov_b32_e32 v56, v53
	v_pk_fma_f32 v[12:13], v[102:103], v[70:71], v[12:13] op_sel_hi:[0,1,1]
	v_pk_fma_f32 v[14:15], v[102:103], v[72:73], v[14:15] op_sel_hi:[0,1,1]
	v_pk_fma_f32 v[16:17], v[102:103], v[74:75], v[16:17] op_sel_hi:[0,1,1]
	v_pk_fma_f32 v[18:19], v[102:103], v[76:77], v[18:19] op_sel_hi:[0,1,1]
	s_waitcnt lgkmcnt(0)
	v_fmac_f32_e32 v8, v102, v58
	v_pk_fma_f32 v[12:13], v[104:105], v[30:31], v[12:13] op_sel_hi:[0,1,1]
	v_pk_fma_f32 v[14:15], v[104:105], v[38:39], v[14:15] op_sel_hi:[0,1,1]
	v_pk_fma_f32 v[16:17], v[104:105], v[46:47], v[16:17] op_sel_hi:[0,1,1]
	v_pk_fma_f32 v[18:19], v[104:105], v[54:55], v[18:19] op_sel_hi:[0,1,1]
	v_fmac_f32_e32 v8, v104, v59
	v_pk_fma_f32 v[12:13], v[106:107], v[26:27], v[12:13] op_sel_hi:[0,1,1]
	v_pk_fma_f32 v[14:15], v[106:107], v[34:35], v[14:15] op_sel_hi:[0,1,1]
	v_pk_fma_f32 v[16:17], v[106:107], v[42:43], v[16:17] op_sel_hi:[0,1,1]
	v_pk_fma_f32 v[18:19], v[106:107], v[50:51], v[18:19] op_sel_hi:[0,1,1]
	v_fmac_f32_e32 v8, v106, v60
	v_pk_fma_f32 v[12:13], v[108:109], v[32:33], v[12:13] op_sel_hi:[0,1,1]
	v_pk_fma_f32 v[14:15], v[108:109], v[40:41], v[14:15] op_sel_hi:[0,1,1]
	v_pk_fma_f32 v[16:17], v[108:109], v[48:49], v[16:17] op_sel_hi:[0,1,1]
	v_pk_fma_f32 v[18:19], v[108:109], v[56:57], v[18:19] op_sel_hi:[0,1,1]
	v_fmac_f32_e32 v8, v108, v61
	global_load_dword v102, v200, s[24:25]
	s_add_u32 s24, s24, 0x6000
	s_addc_u32 s25, s25, 0
	global_load_dword v104, v200, s[24:25]
	s_add_u32 s24, s24, 0x6000
	s_addc_u32 s25, s25, 0
	global_load_dword v106, v200, s[24:25]
	s_add_u32 s24, s24, 0x6000
	s_addc_u32 s25, s25, 0
	global_load_dword v108, v200, s[24:25]
	s_add_u32 s24, s24, 0x6000
	s_addc_u32 s25, s25, 0
	s_waitcnt vmcnt(56)
	v_add_u32_e32 v25, s20, v23
	ds_read_b128 v[26:29], v25
	ds_read_b128 v[30:33], v25 offset:8192
	ds_read_b128 v[34:37], v25 offset:16384
	ds_read_b128 v[38:41], v25 offset:24576
	ds_read_b128 v[42:45], v25 offset:32768
	ds_read_b128 v[46:49], v25 offset:40960
	ds_read_b128 v[50:53], v25 offset:49152
	ds_read_b128 v[54:57], v25 offset:57344
	v_add_u32_e32 v25, 0x10000, v25
	ds_read_b128 v[58:61], v25
	s_waitcnt lgkmcnt(6)
	v_mov_b32_e32 v70, v34
	v_mov_b32_e32 v71, v30
	v_mov_b32_e32 v72, v26
	s_waitcnt lgkmcnt(5)
	v_mov_b32_e32 v73, v38
	s_waitcnt lgkmcnt(4)
	v_mov_b32_e32 v74, v42
	s_waitcnt lgkmcnt(3)
	v_mov_b32_e32 v75, v46
	s_waitcnt lgkmcnt(2)
	v_mov_b32_e32 v76, v50
	s_waitcnt lgkmcnt(1)
	v_mov_b32_e32 v77, v54
	v_mov_b32_e32 v30, v35
	v_mov_b32_e32 v38, v27
	v_mov_b32_e32 v46, v43
	v_mov_b32_e32 v54, v51
	v_mov_b32_e32 v26, v36
	v_mov_b32_e32 v27, v32
	v_mov_b32_e32 v34, v28
	v_mov_b32_e32 v35, v40
	v_mov_b32_e32 v42, v44
	v_mov_b32_e32 v43, v48
	v_mov_b32_e32 v50, v52
	v_mov_b32_e32 v51, v56
	s_add_i32 s20, s20, 16
	v_mov_b32_e32 v32, v37
	v_mov_b32_e32 v40, v29
	v_mov_b32_e32 v48, v45
	v_mov_b32_e32 v56, v53
	v_pk_fma_f32 v[12:13], v[110:111], v[70:71], v[12:13] op_sel_hi:[0,1,1]
	v_pk_fma_f32 v[14:15], v[110:111], v[72:73], v[14:15] op_sel_hi:[0,1,1]
	v_pk_fma_f32 v[16:17], v[110:111], v[74:75], v[16:17] op_sel_hi:[0,1,1]
	v_pk_fma_f32 v[18:19], v[110:111], v[76:77], v[18:19] op_sel_hi:[0,1,1]
	s_waitcnt lgkmcnt(0)
	v_fmac_f32_e32 v8, v110, v58
	v_pk_fma_f32 v[12:13], v[112:113], v[30:31], v[12:13] op_sel_hi:[0,1,1]
	v_pk_fma_f32 v[14:15], v[112:113], v[38:39], v[14:15] op_sel_hi:[0,1,1]
	v_pk_fma_f32 v[16:17], v[112:113], v[46:47], v[16:17] op_sel_hi:[0,1,1]
	v_pk_fma_f32 v[18:19], v[112:113], v[54:55], v[18:19] op_sel_hi:[0,1,1]
	v_fmac_f32_e32 v8, v112, v59
	v_pk_fma_f32 v[12:13], v[114:115], v[26:27], v[12:13] op_sel_hi:[0,1,1]
	v_pk_fma_f32 v[14:15], v[114:115], v[34:35], v[14:15] op_sel_hi:[0,1,1]
	v_pk_fma_f32 v[16:17], v[114:115], v[42:43], v[16:17] op_sel_hi:[0,1,1]
	v_pk_fma_f32 v[18:19], v[114:115], v[50:51], v[18:19] op_sel_hi:[0,1,1]
	v_fmac_f32_e32 v8, v114, v60
	v_pk_fma_f32 v[12:13], v[116:117], v[32:33], v[12:13] op_sel_hi:[0,1,1]
	v_pk_fma_f32 v[14:15], v[116:117], v[40:41], v[14:15] op_sel_hi:[0,1,1]
	v_pk_fma_f32 v[16:17], v[116:117], v[48:49], v[16:17] op_sel_hi:[0,1,1]
	v_pk_fma_f32 v[18:19], v[116:117], v[56:57], v[18:19] op_sel_hi:[0,1,1]
	v_fmac_f32_e32 v8, v116, v61
	global_load_dword v110, v200, s[24:25]
	s_add_u32 s24, s24, 0x6000
	s_addc_u32 s25, s25, 0
	global_load_dword v112, v200, s[24:25]
	s_add_u32 s24, s24, 0x6000
	s_addc_u32 s25, s25, 0
	global_load_dword v114, v200, s[24:25]
	s_add_u32 s24, s24, 0x6000
	s_addc_u32 s25, s25, 0
	global_load_dword v116, v200, s[24:25]
	s_add_u32 s24, s24, 0x6000
	s_addc_u32 s25, s25, 0
	s_waitcnt vmcnt(56)
	v_add_u32_e32 v25, s20, v23
	ds_read_b128 v[26:29], v25
	ds_read_b128 v[30:33], v25 offset:8192
	ds_read_b128 v[34:37], v25 offset:16384
	ds_read_b128 v[38:41], v25 offset:24576
	ds_read_b128 v[42:45], v25 offset:32768
	ds_read_b128 v[46:49], v25 offset:40960
	ds_read_b128 v[50:53], v25 offset:49152
	ds_read_b128 v[54:57], v25 offset:57344
	v_add_u32_e32 v25, 0x10000, v25
	ds_read_b128 v[58:61], v25
	s_waitcnt lgkmcnt(6)
	v_mov_b32_e32 v70, v34
	v_mov_b32_e32 v71, v30
	v_mov_b32_e32 v72, v26
	s_waitcnt lgkmcnt(5)
	v_mov_b32_e32 v73, v38
	s_waitcnt lgkmcnt(4)
	v_mov_b32_e32 v74, v42
	s_waitcnt lgkmcnt(3)
	v_mov_b32_e32 v75, v46
	s_waitcnt lgkmcnt(2)
	v_mov_b32_e32 v76, v50
	s_waitcnt lgkmcnt(1)
	v_mov_b32_e32 v77, v54
	v_mov_b32_e32 v30, v35
	v_mov_b32_e32 v38, v27
	v_mov_b32_e32 v46, v43
	v_mov_b32_e32 v54, v51
	v_mov_b32_e32 v26, v36
	v_mov_b32_e32 v27, v32
	v_mov_b32_e32 v34, v28
	v_mov_b32_e32 v35, v40
	v_mov_b32_e32 v42, v44
	v_mov_b32_e32 v43, v48
	v_mov_b32_e32 v50, v52
	v_mov_b32_e32 v51, v56
	s_add_i32 s20, s20, 16
	v_mov_b32_e32 v32, v37
	v_mov_b32_e32 v40, v29
	v_mov_b32_e32 v48, v45
	v_mov_b32_e32 v56, v53
	v_pk_fma_f32 v[12:13], v[118:119], v[70:71], v[12:13] op_sel_hi:[0,1,1]
	v_pk_fma_f32 v[14:15], v[118:119], v[72:73], v[14:15] op_sel_hi:[0,1,1]
	v_pk_fma_f32 v[16:17], v[118:119], v[74:75], v[16:17] op_sel_hi:[0,1,1]
	v_pk_fma_f32 v[18:19], v[118:119], v[76:77], v[18:19] op_sel_hi:[0,1,1]
	s_waitcnt lgkmcnt(0)
	v_fmac_f32_e32 v8, v118, v58
	v_pk_fma_f32 v[12:13], v[120:121], v[30:31], v[12:13] op_sel_hi:[0,1,1]
	v_pk_fma_f32 v[14:15], v[120:121], v[38:39], v[14:15] op_sel_hi:[0,1,1]
	v_pk_fma_f32 v[16:17], v[120:121], v[46:47], v[16:17] op_sel_hi:[0,1,1]
	v_pk_fma_f32 v[18:19], v[120:121], v[54:55], v[18:19] op_sel_hi:[0,1,1]
	v_fmac_f32_e32 v8, v120, v59
	v_pk_fma_f32 v[12:13], v[122:123], v[26:27], v[12:13] op_sel_hi:[0,1,1]
	v_pk_fma_f32 v[14:15], v[122:123], v[34:35], v[14:15] op_sel_hi:[0,1,1]
	v_pk_fma_f32 v[16:17], v[122:123], v[42:43], v[16:17] op_sel_hi:[0,1,1]
	v_pk_fma_f32 v[18:19], v[122:123], v[50:51], v[18:19] op_sel_hi:[0,1,1]
	v_fmac_f32_e32 v8, v122, v60
	v_pk_fma_f32 v[12:13], v[124:125], v[32:33], v[12:13] op_sel_hi:[0,1,1]
	v_pk_fma_f32 v[14:15], v[124:125], v[40:41], v[14:15] op_sel_hi:[0,1,1]
	v_pk_fma_f32 v[16:17], v[124:125], v[48:49], v[16:17] op_sel_hi:[0,1,1]
	v_pk_fma_f32 v[18:19], v[124:125], v[56:57], v[18:19] op_sel_hi:[0,1,1]
	v_fmac_f32_e32 v8, v124, v61
	global_load_dword v118, v200, s[24:25]
	s_add_u32 s24, s24, 0x6000
	s_addc_u32 s25, s25, 0
	global_load_dword v120, v200, s[24:25]
	s_add_u32 s24, s24, 0x6000
	s_addc_u32 s25, s25, 0
	global_load_dword v122, v200, s[24:25]
	s_add_u32 s24, s24, 0x6000
	s_addc_u32 s25, s25, 0
	global_load_dword v124, v200, s[24:25]
	s_add_u32 s24, s24, 0x6000
	s_addc_u32 s25, s25, 0
	s_waitcnt vmcnt(56)
	v_add_u32_e32 v25, s20, v23
	ds_read_b128 v[26:29], v25
	ds_read_b128 v[30:33], v25 offset:8192
	ds_read_b128 v[34:37], v25 offset:16384
	ds_read_b128 v[38:41], v25 offset:24576
	ds_read_b128 v[42:45], v25 offset:32768
	ds_read_b128 v[46:49], v25 offset:40960
	ds_read_b128 v[50:53], v25 offset:49152
	ds_read_b128 v[54:57], v25 offset:57344
	v_add_u32_e32 v25, 0x10000, v25
	ds_read_b128 v[58:61], v25
	s_waitcnt lgkmcnt(6)
	v_mov_b32_e32 v70, v34
	v_mov_b32_e32 v71, v30
	v_mov_b32_e32 v72, v26
	s_waitcnt lgkmcnt(5)
	v_mov_b32_e32 v73, v38
	s_waitcnt lgkmcnt(4)
	v_mov_b32_e32 v74, v42
	s_waitcnt lgkmcnt(3)
	v_mov_b32_e32 v75, v46
	s_waitcnt lgkmcnt(2)
	v_mov_b32_e32 v76, v50
	s_waitcnt lgkmcnt(1)
	v_mov_b32_e32 v77, v54
	v_mov_b32_e32 v30, v35
	v_mov_b32_e32 v38, v27
	v_mov_b32_e32 v46, v43
	v_mov_b32_e32 v54, v51
	v_mov_b32_e32 v26, v36
	v_mov_b32_e32 v27, v32
	v_mov_b32_e32 v34, v28
	v_mov_b32_e32 v35, v40
	v_mov_b32_e32 v42, v44
	v_mov_b32_e32 v43, v48
	v_mov_b32_e32 v50, v52
	v_mov_b32_e32 v51, v56
	s_add_i32 s20, s20, 16
	v_mov_b32_e32 v32, v37
	v_mov_b32_e32 v40, v29
	v_mov_b32_e32 v48, v45
	v_mov_b32_e32 v56, v53
	v_pk_fma_f32 v[12:13], v[126:127], v[70:71], v[12:13] op_sel_hi:[0,1,1]
	v_pk_fma_f32 v[14:15], v[126:127], v[72:73], v[14:15] op_sel_hi:[0,1,1]
	v_pk_fma_f32 v[16:17], v[126:127], v[74:75], v[16:17] op_sel_hi:[0,1,1]
	v_pk_fma_f32 v[18:19], v[126:127], v[76:77], v[18:19] op_sel_hi:[0,1,1]
	s_waitcnt lgkmcnt(0)
	v_fmac_f32_e32 v8, v126, v58
	v_pk_fma_f32 v[12:13], v[128:129], v[30:31], v[12:13] op_sel_hi:[0,1,1]
	v_pk_fma_f32 v[14:15], v[128:129], v[38:39], v[14:15] op_sel_hi:[0,1,1]
	v_pk_fma_f32 v[16:17], v[128:129], v[46:47], v[16:17] op_sel_hi:[0,1,1]
	v_pk_fma_f32 v[18:19], v[128:129], v[54:55], v[18:19] op_sel_hi:[0,1,1]
	v_fmac_f32_e32 v8, v128, v59
	v_pk_fma_f32 v[12:13], v[130:131], v[26:27], v[12:13] op_sel_hi:[0,1,1]
	v_pk_fma_f32 v[14:15], v[130:131], v[34:35], v[14:15] op_sel_hi:[0,1,1]
	v_pk_fma_f32 v[16:17], v[130:131], v[42:43], v[16:17] op_sel_hi:[0,1,1]
	v_pk_fma_f32 v[18:19], v[130:131], v[50:51], v[18:19] op_sel_hi:[0,1,1]
	v_fmac_f32_e32 v8, v130, v60
	v_pk_fma_f32 v[12:13], v[132:133], v[32:33], v[12:13] op_sel_hi:[0,1,1]
	v_pk_fma_f32 v[14:15], v[132:133], v[40:41], v[14:15] op_sel_hi:[0,1,1]
	v_pk_fma_f32 v[16:17], v[132:133], v[48:49], v[16:17] op_sel_hi:[0,1,1]
	v_pk_fma_f32 v[18:19], v[132:133], v[56:57], v[18:19] op_sel_hi:[0,1,1]
	v_fmac_f32_e32 v8, v132, v61
	global_load_dword v126, v200, s[24:25]
	s_add_u32 s24, s24, 0x6000
	s_addc_u32 s25, s25, 0
	global_load_dword v128, v200, s[24:25]
	s_add_u32 s24, s24, 0x6000
	s_addc_u32 s25, s25, 0
	global_load_dword v130, v200, s[24:25]
	s_add_u32 s24, s24, 0x6000
	s_addc_u32 s25, s25, 0
	global_load_dword v132, v200, s[24:25]
	s_add_u32 s24, s24, 0x6000
	s_addc_u32 s25, s25, 0
	s_waitcnt vmcnt(56)
	v_add_u32_e32 v25, s20, v23
	ds_read_b128 v[26:29], v25
	ds_read_b128 v[30:33], v25 offset:8192
	ds_read_b128 v[34:37], v25 offset:16384
	ds_read_b128 v[38:41], v25 offset:24576
	ds_read_b128 v[42:45], v25 offset:32768
	ds_read_b128 v[46:49], v25 offset:40960
	ds_read_b128 v[50:53], v25 offset:49152
	ds_read_b128 v[54:57], v25 offset:57344
	v_add_u32_e32 v25, 0x10000, v25
	ds_read_b128 v[58:61], v25
	s_waitcnt lgkmcnt(6)
	v_mov_b32_e32 v70, v34
	v_mov_b32_e32 v71, v30
	v_mov_b32_e32 v72, v26
	s_waitcnt lgkmcnt(5)
	v_mov_b32_e32 v73, v38
	s_waitcnt lgkmcnt(4)
	v_mov_b32_e32 v74, v42
	s_waitcnt lgkmcnt(3)
	v_mov_b32_e32 v75, v46
	s_waitcnt lgkmcnt(2)
	v_mov_b32_e32 v76, v50
	s_waitcnt lgkmcnt(1)
	v_mov_b32_e32 v77, v54
	v_mov_b32_e32 v30, v35
	v_mov_b32_e32 v38, v27
	v_mov_b32_e32 v46, v43
	v_mov_b32_e32 v54, v51
	v_mov_b32_e32 v26, v36
	v_mov_b32_e32 v27, v32
	v_mov_b32_e32 v34, v28
	v_mov_b32_e32 v35, v40
	v_mov_b32_e32 v42, v44
	v_mov_b32_e32 v43, v48
	v_mov_b32_e32 v50, v52
	v_mov_b32_e32 v51, v56
	s_add_i32 s20, s20, 16
	v_mov_b32_e32 v32, v37
	v_mov_b32_e32 v40, v29
	v_mov_b32_e32 v48, v45
	v_mov_b32_e32 v56, v53
	v_pk_fma_f32 v[12:13], v[134:135], v[70:71], v[12:13] op_sel_hi:[0,1,1]
	v_pk_fma_f32 v[14:15], v[134:135], v[72:73], v[14:15] op_sel_hi:[0,1,1]
	v_pk_fma_f32 v[16:17], v[134:135], v[74:75], v[16:17] op_sel_hi:[0,1,1]
	v_pk_fma_f32 v[18:19], v[134:135], v[76:77], v[18:19] op_sel_hi:[0,1,1]
	s_waitcnt lgkmcnt(0)
	v_fmac_f32_e32 v8, v134, v58
	v_pk_fma_f32 v[12:13], v[136:137], v[30:31], v[12:13] op_sel_hi:[0,1,1]
	v_pk_fma_f32 v[14:15], v[136:137], v[38:39], v[14:15] op_sel_hi:[0,1,1]
	v_pk_fma_f32 v[16:17], v[136:137], v[46:47], v[16:17] op_sel_hi:[0,1,1]
	v_pk_fma_f32 v[18:19], v[136:137], v[54:55], v[18:19] op_sel_hi:[0,1,1]
	v_fmac_f32_e32 v8, v136, v59
	v_pk_fma_f32 v[12:13], v[138:139], v[26:27], v[12:13] op_sel_hi:[0,1,1]
	v_pk_fma_f32 v[14:15], v[138:139], v[34:35], v[14:15] op_sel_hi:[0,1,1]
	v_pk_fma_f32 v[16:17], v[138:139], v[42:43], v[16:17] op_sel_hi:[0,1,1]
	v_pk_fma_f32 v[18:19], v[138:139], v[50:51], v[18:19] op_sel_hi:[0,1,1]
	v_fmac_f32_e32 v8, v138, v60
	v_pk_fma_f32 v[12:13], v[140:141], v[32:33], v[12:13] op_sel_hi:[0,1,1]
	v_pk_fma_f32 v[14:15], v[140:141], v[40:41], v[14:15] op_sel_hi:[0,1,1]
	v_pk_fma_f32 v[16:17], v[140:141], v[48:49], v[16:17] op_sel_hi:[0,1,1]
	v_pk_fma_f32 v[18:19], v[140:141], v[56:57], v[18:19] op_sel_hi:[0,1,1]
	v_fmac_f32_e32 v8, v140, v61
	global_load_dword v134, v200, s[24:25]
	s_add_u32 s24, s24, 0x6000
	s_addc_u32 s25, s25, 0
	global_load_dword v136, v200, s[24:25]
	s_add_u32 s24, s24, 0x6000
	s_addc_u32 s25, s25, 0
	global_load_dword v138, v200, s[24:25]
	s_add_u32 s24, s24, 0x6000
	s_addc_u32 s25, s25, 0
	global_load_dword v140, v200, s[24:25]
	s_add_u32 s24, s24, 0x6000
	s_addc_u32 s25, s25, 0
	s_waitcnt vmcnt(56)
	v_add_u32_e32 v25, s20, v23
	ds_read_b128 v[26:29], v25
	ds_read_b128 v[30:33], v25 offset:8192
	ds_read_b128 v[34:37], v25 offset:16384
	ds_read_b128 v[38:41], v25 offset:24576
	ds_read_b128 v[42:45], v25 offset:32768
	ds_read_b128 v[46:49], v25 offset:40960
	ds_read_b128 v[50:53], v25 offset:49152
	ds_read_b128 v[54:57], v25 offset:57344
	v_add_u32_e32 v25, 0x10000, v25
	ds_read_b128 v[58:61], v25
	s_waitcnt lgkmcnt(6)
	v_mov_b32_e32 v70, v34
	v_mov_b32_e32 v71, v30
	v_mov_b32_e32 v72, v26
	s_waitcnt lgkmcnt(5)
	v_mov_b32_e32 v73, v38
	s_waitcnt lgkmcnt(4)
	v_mov_b32_e32 v74, v42
	s_waitcnt lgkmcnt(3)
	v_mov_b32_e32 v75, v46
	s_waitcnt lgkmcnt(2)
	v_mov_b32_e32 v76, v50
	s_waitcnt lgkmcnt(1)
	v_mov_b32_e32 v77, v54
	v_mov_b32_e32 v30, v35
	v_mov_b32_e32 v38, v27
	v_mov_b32_e32 v46, v43
	v_mov_b32_e32 v54, v51
	v_mov_b32_e32 v26, v36
	v_mov_b32_e32 v27, v32
	v_mov_b32_e32 v34, v28
	v_mov_b32_e32 v35, v40
	v_mov_b32_e32 v42, v44
	v_mov_b32_e32 v43, v48
	v_mov_b32_e32 v50, v52
	v_mov_b32_e32 v51, v56
	s_add_i32 s20, s20, 16
	v_mov_b32_e32 v32, v37
	v_mov_b32_e32 v40, v29
	v_mov_b32_e32 v48, v45
	v_mov_b32_e32 v56, v53
	v_pk_fma_f32 v[12:13], v[142:143], v[70:71], v[12:13] op_sel_hi:[0,1,1]
	v_pk_fma_f32 v[14:15], v[142:143], v[72:73], v[14:15] op_sel_hi:[0,1,1]
	v_pk_fma_f32 v[16:17], v[142:143], v[74:75], v[16:17] op_sel_hi:[0,1,1]
	v_pk_fma_f32 v[18:19], v[142:143], v[76:77], v[18:19] op_sel_hi:[0,1,1]
	s_waitcnt lgkmcnt(0)
	v_fmac_f32_e32 v8, v142, v58
	v_pk_fma_f32 v[12:13], v[144:145], v[30:31], v[12:13] op_sel_hi:[0,1,1]
	v_pk_fma_f32 v[14:15], v[144:145], v[38:39], v[14:15] op_sel_hi:[0,1,1]
	v_pk_fma_f32 v[16:17], v[144:145], v[46:47], v[16:17] op_sel_hi:[0,1,1]
	v_pk_fma_f32 v[18:19], v[144:145], v[54:55], v[18:19] op_sel_hi:[0,1,1]
	v_fmac_f32_e32 v8, v144, v59
	v_pk_fma_f32 v[12:13], v[146:147], v[26:27], v[12:13] op_sel_hi:[0,1,1]
	v_pk_fma_f32 v[14:15], v[146:147], v[34:35], v[14:15] op_sel_hi:[0,1,1]
	v_pk_fma_f32 v[16:17], v[146:147], v[42:43], v[16:17] op_sel_hi:[0,1,1]
	v_pk_fma_f32 v[18:19], v[146:147], v[50:51], v[18:19] op_sel_hi:[0,1,1]
	v_fmac_f32_e32 v8, v146, v60
	v_pk_fma_f32 v[12:13], v[148:149], v[32:33], v[12:13] op_sel_hi:[0,1,1]
	v_pk_fma_f32 v[14:15], v[148:149], v[40:41], v[14:15] op_sel_hi:[0,1,1]
	v_pk_fma_f32 v[16:17], v[148:149], v[48:49], v[16:17] op_sel_hi:[0,1,1]
	v_pk_fma_f32 v[18:19], v[148:149], v[56:57], v[18:19] op_sel_hi:[0,1,1]
	v_fmac_f32_e32 v8, v148, v61
	global_load_dword v142, v200, s[24:25]
	s_add_u32 s24, s24, 0x6000
	s_addc_u32 s25, s25, 0
	global_load_dword v144, v200, s[24:25]
	s_add_u32 s24, s24, 0x6000
	s_addc_u32 s25, s25, 0
	global_load_dword v146, v200, s[24:25]
	s_add_u32 s24, s24, 0x6000
	s_addc_u32 s25, s25, 0
	global_load_dword v148, v200, s[24:25]
	s_add_u32 s24, s24, 0x6000
	s_addc_u32 s25, s25, 0
	s_waitcnt vmcnt(56)
	v_add_u32_e32 v25, s20, v23
	ds_read_b128 v[26:29], v25
	ds_read_b128 v[30:33], v25 offset:8192
	ds_read_b128 v[34:37], v25 offset:16384
	ds_read_b128 v[38:41], v25 offset:24576
	ds_read_b128 v[42:45], v25 offset:32768
	ds_read_b128 v[46:49], v25 offset:40960
	ds_read_b128 v[50:53], v25 offset:49152
	ds_read_b128 v[54:57], v25 offset:57344
	v_add_u32_e32 v25, 0x10000, v25
	ds_read_b128 v[58:61], v25
	s_waitcnt lgkmcnt(6)
	v_mov_b32_e32 v70, v34
	v_mov_b32_e32 v71, v30
	v_mov_b32_e32 v72, v26
	s_waitcnt lgkmcnt(5)
	v_mov_b32_e32 v73, v38
	s_waitcnt lgkmcnt(4)
	v_mov_b32_e32 v74, v42
	s_waitcnt lgkmcnt(3)
	v_mov_b32_e32 v75, v46
	s_waitcnt lgkmcnt(2)
	v_mov_b32_e32 v76, v50
	s_waitcnt lgkmcnt(1)
	v_mov_b32_e32 v77, v54
	v_mov_b32_e32 v30, v35
	v_mov_b32_e32 v38, v27
	v_mov_b32_e32 v46, v43
	v_mov_b32_e32 v54, v51
	v_mov_b32_e32 v26, v36
	v_mov_b32_e32 v27, v32
	v_mov_b32_e32 v34, v28
	v_mov_b32_e32 v35, v40
	v_mov_b32_e32 v42, v44
	v_mov_b32_e32 v43, v48
	v_mov_b32_e32 v50, v52
	v_mov_b32_e32 v51, v56
	s_add_i32 s20, s20, 16
	v_mov_b32_e32 v32, v37
	v_mov_b32_e32 v40, v29
	v_mov_b32_e32 v48, v45
	v_mov_b32_e32 v56, v53
	v_pk_fma_f32 v[12:13], v[150:151], v[70:71], v[12:13] op_sel_hi:[0,1,1]
	v_pk_fma_f32 v[14:15], v[150:151], v[72:73], v[14:15] op_sel_hi:[0,1,1]
	v_pk_fma_f32 v[16:17], v[150:151], v[74:75], v[16:17] op_sel_hi:[0,1,1]
	v_pk_fma_f32 v[18:19], v[150:151], v[76:77], v[18:19] op_sel_hi:[0,1,1]
	s_waitcnt lgkmcnt(0)
	v_fmac_f32_e32 v8, v150, v58
	v_pk_fma_f32 v[12:13], v[152:153], v[30:31], v[12:13] op_sel_hi:[0,1,1]
	v_pk_fma_f32 v[14:15], v[152:153], v[38:39], v[14:15] op_sel_hi:[0,1,1]
	v_pk_fma_f32 v[16:17], v[152:153], v[46:47], v[16:17] op_sel_hi:[0,1,1]
	v_pk_fma_f32 v[18:19], v[152:153], v[54:55], v[18:19] op_sel_hi:[0,1,1]
	v_fmac_f32_e32 v8, v152, v59
	v_pk_fma_f32 v[12:13], v[154:155], v[26:27], v[12:13] op_sel_hi:[0,1,1]
	v_pk_fma_f32 v[14:15], v[154:155], v[34:35], v[14:15] op_sel_hi:[0,1,1]
	v_pk_fma_f32 v[16:17], v[154:155], v[42:43], v[16:17] op_sel_hi:[0,1,1]
	v_pk_fma_f32 v[18:19], v[154:155], v[50:51], v[18:19] op_sel_hi:[0,1,1]
	v_fmac_f32_e32 v8, v154, v60
	v_pk_fma_f32 v[12:13], v[156:157], v[32:33], v[12:13] op_sel_hi:[0,1,1]
	v_pk_fma_f32 v[14:15], v[156:157], v[40:41], v[14:15] op_sel_hi:[0,1,1]
	v_pk_fma_f32 v[16:17], v[156:157], v[48:49], v[16:17] op_sel_hi:[0,1,1]
	v_pk_fma_f32 v[18:19], v[156:157], v[56:57], v[18:19] op_sel_hi:[0,1,1]
	v_fmac_f32_e32 v8, v156, v61
	global_load_dword v150, v200, s[24:25]
	s_add_u32 s24, s24, 0x6000
	s_addc_u32 s25, s25, 0
	global_load_dword v152, v200, s[24:25]
	s_add_u32 s24, s24, 0x6000
	s_addc_u32 s25, s25, 0
	global_load_dword v154, v200, s[24:25]
	s_add_u32 s24, s24, 0x6000
	s_addc_u32 s25, s25, 0
	global_load_dword v156, v200, s[24:25]
	s_add_u32 s24, s24, 0x6000
	s_addc_u32 s25, s25, 0
	s_waitcnt vmcnt(56)
	v_add_u32_e32 v25, s20, v23
	ds_read_b128 v[26:29], v25
	ds_read_b128 v[30:33], v25 offset:8192
	ds_read_b128 v[34:37], v25 offset:16384
	ds_read_b128 v[38:41], v25 offset:24576
	ds_read_b128 v[42:45], v25 offset:32768
	ds_read_b128 v[46:49], v25 offset:40960
	ds_read_b128 v[50:53], v25 offset:49152
	ds_read_b128 v[54:57], v25 offset:57344
	v_add_u32_e32 v25, 0x10000, v25
	ds_read_b128 v[58:61], v25
	s_waitcnt lgkmcnt(6)
	v_mov_b32_e32 v70, v34
	v_mov_b32_e32 v71, v30
	v_mov_b32_e32 v72, v26
	s_waitcnt lgkmcnt(5)
	v_mov_b32_e32 v73, v38
	s_waitcnt lgkmcnt(4)
	v_mov_b32_e32 v74, v42
	s_waitcnt lgkmcnt(3)
	v_mov_b32_e32 v75, v46
	s_waitcnt lgkmcnt(2)
	v_mov_b32_e32 v76, v50
	s_waitcnt lgkmcnt(1)
	v_mov_b32_e32 v77, v54
	v_mov_b32_e32 v30, v35
	v_mov_b32_e32 v38, v27
	v_mov_b32_e32 v46, v43
	v_mov_b32_e32 v54, v51
	v_mov_b32_e32 v26, v36
	v_mov_b32_e32 v27, v32
	v_mov_b32_e32 v34, v28
	v_mov_b32_e32 v35, v40
	v_mov_b32_e32 v42, v44
	v_mov_b32_e32 v43, v48
	v_mov_b32_e32 v50, v52
	v_mov_b32_e32 v51, v56
	s_add_i32 s20, s20, 16
	v_mov_b32_e32 v32, v37
	v_mov_b32_e32 v40, v29
	v_mov_b32_e32 v48, v45
	v_mov_b32_e32 v56, v53
	v_pk_fma_f32 v[12:13], v[158:159], v[70:71], v[12:13] op_sel_hi:[0,1,1]
	v_pk_fma_f32 v[14:15], v[158:159], v[72:73], v[14:15] op_sel_hi:[0,1,1]
	v_pk_fma_f32 v[16:17], v[158:159], v[74:75], v[16:17] op_sel_hi:[0,1,1]
	v_pk_fma_f32 v[18:19], v[158:159], v[76:77], v[18:19] op_sel_hi:[0,1,1]
	s_waitcnt lgkmcnt(0)
	v_fmac_f32_e32 v8, v158, v58
	v_pk_fma_f32 v[12:13], v[160:161], v[30:31], v[12:13] op_sel_hi:[0,1,1]
	v_pk_fma_f32 v[14:15], v[160:161], v[38:39], v[14:15] op_sel_hi:[0,1,1]
	v_pk_fma_f32 v[16:17], v[160:161], v[46:47], v[16:17] op_sel_hi:[0,1,1]
	v_pk_fma_f32 v[18:19], v[160:161], v[54:55], v[18:19] op_sel_hi:[0,1,1]
	v_fmac_f32_e32 v8, v160, v59
	v_pk_fma_f32 v[12:13], v[162:163], v[26:27], v[12:13] op_sel_hi:[0,1,1]
	v_pk_fma_f32 v[14:15], v[162:163], v[34:35], v[14:15] op_sel_hi:[0,1,1]
	v_pk_fma_f32 v[16:17], v[162:163], v[42:43], v[16:17] op_sel_hi:[0,1,1]
	v_pk_fma_f32 v[18:19], v[162:163], v[50:51], v[18:19] op_sel_hi:[0,1,1]
	v_fmac_f32_e32 v8, v162, v60
	v_pk_fma_f32 v[12:13], v[164:165], v[32:33], v[12:13] op_sel_hi:[0,1,1]
	v_pk_fma_f32 v[14:15], v[164:165], v[40:41], v[14:15] op_sel_hi:[0,1,1]
	v_pk_fma_f32 v[16:17], v[164:165], v[48:49], v[16:17] op_sel_hi:[0,1,1]
	v_pk_fma_f32 v[18:19], v[164:165], v[56:57], v[18:19] op_sel_hi:[0,1,1]
	v_fmac_f32_e32 v8, v164, v61
	global_load_dword v158, v200, s[24:25]
	s_add_u32 s24, s24, 0x6000
	s_addc_u32 s25, s25, 0
	global_load_dword v160, v200, s[24:25]
	s_add_u32 s24, s24, 0x6000
	s_addc_u32 s25, s25, 0
	global_load_dword v162, v200, s[24:25]
	s_add_u32 s24, s24, 0x6000
	s_addc_u32 s25, s25, 0
	global_load_dword v164, v200, s[24:25]
	s_add_u32 s24, s24, 0x6000
	s_addc_u32 s25, s25, 0
	s_waitcnt vmcnt(56)
	v_add_u32_e32 v25, s20, v23
	ds_read_b128 v[26:29], v25
	ds_read_b128 v[30:33], v25 offset:8192
	ds_read_b128 v[34:37], v25 offset:16384
	ds_read_b128 v[38:41], v25 offset:24576
	ds_read_b128 v[42:45], v25 offset:32768
	ds_read_b128 v[46:49], v25 offset:40960
	ds_read_b128 v[50:53], v25 offset:49152
	ds_read_b128 v[54:57], v25 offset:57344
	v_add_u32_e32 v25, 0x10000, v25
	ds_read_b128 v[58:61], v25
	s_waitcnt lgkmcnt(6)
	v_mov_b32_e32 v70, v34
	v_mov_b32_e32 v71, v30
	v_mov_b32_e32 v72, v26
	s_waitcnt lgkmcnt(5)
	v_mov_b32_e32 v73, v38
	s_waitcnt lgkmcnt(4)
	v_mov_b32_e32 v74, v42
	s_waitcnt lgkmcnt(3)
	v_mov_b32_e32 v75, v46
	s_waitcnt lgkmcnt(2)
	v_mov_b32_e32 v76, v50
	s_waitcnt lgkmcnt(1)
	v_mov_b32_e32 v77, v54
	v_mov_b32_e32 v30, v35
	v_mov_b32_e32 v38, v27
	v_mov_b32_e32 v46, v43
	v_mov_b32_e32 v54, v51
	v_mov_b32_e32 v26, v36
	v_mov_b32_e32 v27, v32
	v_mov_b32_e32 v34, v28
	v_mov_b32_e32 v35, v40
	v_mov_b32_e32 v42, v44
	v_mov_b32_e32 v43, v48
	v_mov_b32_e32 v50, v52
	v_mov_b32_e32 v51, v56
	s_add_i32 s20, s20, 16
	v_mov_b32_e32 v32, v37
	v_mov_b32_e32 v40, v29
	v_mov_b32_e32 v48, v45
	v_mov_b32_e32 v56, v53
	v_pk_fma_f32 v[12:13], v[166:167], v[70:71], v[12:13] op_sel_hi:[0,1,1]
	v_pk_fma_f32 v[14:15], v[166:167], v[72:73], v[14:15] op_sel_hi:[0,1,1]
	v_pk_fma_f32 v[16:17], v[166:167], v[74:75], v[16:17] op_sel_hi:[0,1,1]
	v_pk_fma_f32 v[18:19], v[166:167], v[76:77], v[18:19] op_sel_hi:[0,1,1]
	s_waitcnt lgkmcnt(0)
	v_fmac_f32_e32 v8, v166, v58
	v_pk_fma_f32 v[12:13], v[168:169], v[30:31], v[12:13] op_sel_hi:[0,1,1]
	v_pk_fma_f32 v[14:15], v[168:169], v[38:39], v[14:15] op_sel_hi:[0,1,1]
	v_pk_fma_f32 v[16:17], v[168:169], v[46:47], v[16:17] op_sel_hi:[0,1,1]
	v_pk_fma_f32 v[18:19], v[168:169], v[54:55], v[18:19] op_sel_hi:[0,1,1]
	v_fmac_f32_e32 v8, v168, v59
	v_pk_fma_f32 v[12:13], v[170:171], v[26:27], v[12:13] op_sel_hi:[0,1,1]
	v_pk_fma_f32 v[14:15], v[170:171], v[34:35], v[14:15] op_sel_hi:[0,1,1]
	v_pk_fma_f32 v[16:17], v[170:171], v[42:43], v[16:17] op_sel_hi:[0,1,1]
	v_pk_fma_f32 v[18:19], v[170:171], v[50:51], v[18:19] op_sel_hi:[0,1,1]
	v_fmac_f32_e32 v8, v170, v60
	v_pk_fma_f32 v[12:13], v[172:173], v[32:33], v[12:13] op_sel_hi:[0,1,1]
	v_pk_fma_f32 v[14:15], v[172:173], v[40:41], v[14:15] op_sel_hi:[0,1,1]
	v_pk_fma_f32 v[16:17], v[172:173], v[48:49], v[16:17] op_sel_hi:[0,1,1]
	v_pk_fma_f32 v[18:19], v[172:173], v[56:57], v[18:19] op_sel_hi:[0,1,1]
	v_fmac_f32_e32 v8, v172, v61
	global_load_dword v166, v200, s[24:25]
	s_add_u32 s24, s24, 0x6000
	s_addc_u32 s25, s25, 0
	global_load_dword v168, v200, s[24:25]
	s_add_u32 s24, s24, 0x6000
	s_addc_u32 s25, s25, 0
	global_load_dword v170, v200, s[24:25]
	s_add_u32 s24, s24, 0x6000
	s_addc_u32 s25, s25, 0
	global_load_dword v172, v200, s[24:25]
	s_add_u32 s24, s24, 0x6000
	s_addc_u32 s25, s25, 0
	s_waitcnt vmcnt(56)
	v_add_u32_e32 v25, s20, v23
	ds_read_b128 v[26:29], v25
	ds_read_b128 v[30:33], v25 offset:8192
	ds_read_b128 v[34:37], v25 offset:16384
	ds_read_b128 v[38:41], v25 offset:24576
	ds_read_b128 v[42:45], v25 offset:32768
	ds_read_b128 v[46:49], v25 offset:40960
	ds_read_b128 v[50:53], v25 offset:49152
	ds_read_b128 v[54:57], v25 offset:57344
	v_add_u32_e32 v25, 0x10000, v25
	ds_read_b128 v[58:61], v25
	s_waitcnt lgkmcnt(6)
	v_mov_b32_e32 v70, v34
	v_mov_b32_e32 v71, v30
	v_mov_b32_e32 v72, v26
	s_waitcnt lgkmcnt(5)
	v_mov_b32_e32 v73, v38
	s_waitcnt lgkmcnt(4)
	v_mov_b32_e32 v74, v42
	s_waitcnt lgkmcnt(3)
	v_mov_b32_e32 v75, v46
	s_waitcnt lgkmcnt(2)
	v_mov_b32_e32 v76, v50
	s_waitcnt lgkmcnt(1)
	v_mov_b32_e32 v77, v54
	v_mov_b32_e32 v30, v35
	v_mov_b32_e32 v38, v27
	v_mov_b32_e32 v46, v43
	v_mov_b32_e32 v54, v51
	v_mov_b32_e32 v26, v36
	v_mov_b32_e32 v27, v32
	v_mov_b32_e32 v34, v28
	v_mov_b32_e32 v35, v40
	v_mov_b32_e32 v42, v44
	v_mov_b32_e32 v43, v48
	v_mov_b32_e32 v50, v52
	v_mov_b32_e32 v51, v56
	s_add_i32 s20, s20, 16
	v_mov_b32_e32 v32, v37
	v_mov_b32_e32 v40, v29
	v_mov_b32_e32 v48, v45
	v_mov_b32_e32 v56, v53
	v_pk_fma_f32 v[12:13], v[174:175], v[70:71], v[12:13] op_sel_hi:[0,1,1]
	v_pk_fma_f32 v[14:15], v[174:175], v[72:73], v[14:15] op_sel_hi:[0,1,1]
	v_pk_fma_f32 v[16:17], v[174:175], v[74:75], v[16:17] op_sel_hi:[0,1,1]
	v_pk_fma_f32 v[18:19], v[174:175], v[76:77], v[18:19] op_sel_hi:[0,1,1]
	s_waitcnt lgkmcnt(0)
	v_fmac_f32_e32 v8, v174, v58
	v_pk_fma_f32 v[12:13], v[176:177], v[30:31], v[12:13] op_sel_hi:[0,1,1]
	v_pk_fma_f32 v[14:15], v[176:177], v[38:39], v[14:15] op_sel_hi:[0,1,1]
	v_pk_fma_f32 v[16:17], v[176:177], v[46:47], v[16:17] op_sel_hi:[0,1,1]
	v_pk_fma_f32 v[18:19], v[176:177], v[54:55], v[18:19] op_sel_hi:[0,1,1]
	v_fmac_f32_e32 v8, v176, v59
	v_pk_fma_f32 v[12:13], v[178:179], v[26:27], v[12:13] op_sel_hi:[0,1,1]
	v_pk_fma_f32 v[14:15], v[178:179], v[34:35], v[14:15] op_sel_hi:[0,1,1]
	v_pk_fma_f32 v[16:17], v[178:179], v[42:43], v[16:17] op_sel_hi:[0,1,1]
	v_pk_fma_f32 v[18:19], v[178:179], v[50:51], v[18:19] op_sel_hi:[0,1,1]
	v_fmac_f32_e32 v8, v178, v60
	v_pk_fma_f32 v[12:13], v[180:181], v[32:33], v[12:13] op_sel_hi:[0,1,1]
	v_pk_fma_f32 v[14:15], v[180:181], v[40:41], v[14:15] op_sel_hi:[0,1,1]
	v_pk_fma_f32 v[16:17], v[180:181], v[48:49], v[16:17] op_sel_hi:[0,1,1]
	v_pk_fma_f32 v[18:19], v[180:181], v[56:57], v[18:19] op_sel_hi:[0,1,1]
	v_fmac_f32_e32 v8, v180, v61
	global_load_dword v174, v200, s[24:25]
	s_add_u32 s24, s24, 0x6000
	s_addc_u32 s25, s25, 0
	global_load_dword v176, v200, s[24:25]
	s_add_u32 s24, s24, 0x6000
	s_addc_u32 s25, s25, 0
	global_load_dword v178, v200, s[24:25]
	s_add_u32 s24, s24, 0x6000
	s_addc_u32 s25, s25, 0
	global_load_dword v180, v200, s[24:25]
	s_add_u32 s24, s24, 0x6000
	s_addc_u32 s25, s25, 0
	s_waitcnt vmcnt(56)
	v_add_u32_e32 v25, s20, v23
	ds_read_b128 v[26:29], v25
	ds_read_b128 v[30:33], v25 offset:8192
	ds_read_b128 v[34:37], v25 offset:16384
	ds_read_b128 v[38:41], v25 offset:24576
	ds_read_b128 v[42:45], v25 offset:32768
	ds_read_b128 v[46:49], v25 offset:40960
	ds_read_b128 v[50:53], v25 offset:49152
	ds_read_b128 v[54:57], v25 offset:57344
	v_add_u32_e32 v25, 0x10000, v25
	ds_read_b128 v[58:61], v25
	s_waitcnt lgkmcnt(6)
	v_mov_b32_e32 v70, v34
	v_mov_b32_e32 v71, v30
	v_mov_b32_e32 v72, v26
	s_waitcnt lgkmcnt(5)
	v_mov_b32_e32 v73, v38
	s_waitcnt lgkmcnt(4)
	v_mov_b32_e32 v74, v42
	s_waitcnt lgkmcnt(3)
	v_mov_b32_e32 v75, v46
	s_waitcnt lgkmcnt(2)
	v_mov_b32_e32 v76, v50
	s_waitcnt lgkmcnt(1)
	v_mov_b32_e32 v77, v54
	v_mov_b32_e32 v30, v35
	v_mov_b32_e32 v38, v27
	v_mov_b32_e32 v46, v43
	v_mov_b32_e32 v54, v51
	v_mov_b32_e32 v26, v36
	v_mov_b32_e32 v27, v32
	v_mov_b32_e32 v34, v28
	v_mov_b32_e32 v35, v40
	v_mov_b32_e32 v42, v44
	v_mov_b32_e32 v43, v48
	v_mov_b32_e32 v50, v52
	v_mov_b32_e32 v51, v56
	s_add_i32 s20, s20, 16
	v_mov_b32_e32 v32, v37
	v_mov_b32_e32 v40, v29
	v_mov_b32_e32 v48, v45
	v_mov_b32_e32 v56, v53
	v_pk_fma_f32 v[12:13], v[182:183], v[70:71], v[12:13] op_sel_hi:[0,1,1]
	v_pk_fma_f32 v[14:15], v[182:183], v[72:73], v[14:15] op_sel_hi:[0,1,1]
	v_pk_fma_f32 v[16:17], v[182:183], v[74:75], v[16:17] op_sel_hi:[0,1,1]
	v_pk_fma_f32 v[18:19], v[182:183], v[76:77], v[18:19] op_sel_hi:[0,1,1]
	s_waitcnt lgkmcnt(0)
	v_fmac_f32_e32 v8, v182, v58
	v_pk_fma_f32 v[12:13], v[184:185], v[30:31], v[12:13] op_sel_hi:[0,1,1]
	v_pk_fma_f32 v[14:15], v[184:185], v[38:39], v[14:15] op_sel_hi:[0,1,1]
	v_pk_fma_f32 v[16:17], v[184:185], v[46:47], v[16:17] op_sel_hi:[0,1,1]
	v_pk_fma_f32 v[18:19], v[184:185], v[54:55], v[18:19] op_sel_hi:[0,1,1]
	v_fmac_f32_e32 v8, v184, v59
	v_pk_fma_f32 v[12:13], v[186:187], v[26:27], v[12:13] op_sel_hi:[0,1,1]
	v_pk_fma_f32 v[14:15], v[186:187], v[34:35], v[14:15] op_sel_hi:[0,1,1]
	v_pk_fma_f32 v[16:17], v[186:187], v[42:43], v[16:17] op_sel_hi:[0,1,1]
	v_pk_fma_f32 v[18:19], v[186:187], v[50:51], v[18:19] op_sel_hi:[0,1,1]
	v_fmac_f32_e32 v8, v186, v60
	v_pk_fma_f32 v[12:13], v[188:189], v[32:33], v[12:13] op_sel_hi:[0,1,1]
	v_pk_fma_f32 v[14:15], v[188:189], v[40:41], v[14:15] op_sel_hi:[0,1,1]
	v_pk_fma_f32 v[16:17], v[188:189], v[48:49], v[16:17] op_sel_hi:[0,1,1]
	v_pk_fma_f32 v[18:19], v[188:189], v[56:57], v[18:19] op_sel_hi:[0,1,1]
	v_fmac_f32_e32 v8, v188, v61
	global_load_dword v182, v200, s[24:25]
	s_add_u32 s24, s24, 0x6000
	s_addc_u32 s25, s25, 0
	global_load_dword v184, v200, s[24:25]
	s_add_u32 s24, s24, 0x6000
	s_addc_u32 s25, s25, 0
	global_load_dword v186, v200, s[24:25]
	s_add_u32 s24, s24, 0x6000
	s_addc_u32 s25, s25, 0
	global_load_dword v188, v200, s[24:25]
	s_add_u32 s24, s24, 0x6000
	s_addc_u32 s25, s25, 0
	s_waitcnt vmcnt(56)
	v_add_u32_e32 v25, s20, v23
	ds_read_b128 v[26:29], v25
	ds_read_b128 v[30:33], v25 offset:8192
	ds_read_b128 v[34:37], v25 offset:16384
	ds_read_b128 v[38:41], v25 offset:24576
	ds_read_b128 v[42:45], v25 offset:32768
	ds_read_b128 v[46:49], v25 offset:40960
	ds_read_b128 v[50:53], v25 offset:49152
	ds_read_b128 v[54:57], v25 offset:57344
	v_add_u32_e32 v25, 0x10000, v25
	ds_read_b128 v[58:61], v25
	s_waitcnt lgkmcnt(6)
	v_mov_b32_e32 v70, v34
	v_mov_b32_e32 v71, v30
	v_mov_b32_e32 v72, v26
	s_waitcnt lgkmcnt(5)
	v_mov_b32_e32 v73, v38
	s_waitcnt lgkmcnt(4)
	v_mov_b32_e32 v74, v42
	s_waitcnt lgkmcnt(3)
	v_mov_b32_e32 v75, v46
	s_waitcnt lgkmcnt(2)
	v_mov_b32_e32 v76, v50
	s_waitcnt lgkmcnt(1)
	v_mov_b32_e32 v77, v54
	v_mov_b32_e32 v30, v35
	v_mov_b32_e32 v38, v27
	v_mov_b32_e32 v46, v43
	v_mov_b32_e32 v54, v51
	v_mov_b32_e32 v26, v36
	v_mov_b32_e32 v27, v32
	v_mov_b32_e32 v34, v28
	v_mov_b32_e32 v35, v40
	v_mov_b32_e32 v42, v44
	v_mov_b32_e32 v43, v48
	v_mov_b32_e32 v50, v52
	v_mov_b32_e32 v51, v56
	s_add_i32 s20, s20, 16
	v_mov_b32_e32 v32, v37
	v_mov_b32_e32 v40, v29
	v_mov_b32_e32 v48, v45
	v_mov_b32_e32 v56, v53
	v_pk_fma_f32 v[12:13], v[190:191], v[70:71], v[12:13] op_sel_hi:[0,1,1]
	v_pk_fma_f32 v[14:15], v[190:191], v[72:73], v[14:15] op_sel_hi:[0,1,1]
	v_pk_fma_f32 v[16:17], v[190:191], v[74:75], v[16:17] op_sel_hi:[0,1,1]
	v_pk_fma_f32 v[18:19], v[190:191], v[76:77], v[18:19] op_sel_hi:[0,1,1]
	s_waitcnt lgkmcnt(0)
	v_fmac_f32_e32 v8, v190, v58
	v_pk_fma_f32 v[12:13], v[192:193], v[30:31], v[12:13] op_sel_hi:[0,1,1]
	v_pk_fma_f32 v[14:15], v[192:193], v[38:39], v[14:15] op_sel_hi:[0,1,1]
	v_pk_fma_f32 v[16:17], v[192:193], v[46:47], v[16:17] op_sel_hi:[0,1,1]
	v_pk_fma_f32 v[18:19], v[192:193], v[54:55], v[18:19] op_sel_hi:[0,1,1]
	v_fmac_f32_e32 v8, v192, v59
	v_pk_fma_f32 v[12:13], v[194:195], v[26:27], v[12:13] op_sel_hi:[0,1,1]
	v_pk_fma_f32 v[14:15], v[194:195], v[34:35], v[14:15] op_sel_hi:[0,1,1]
	v_pk_fma_f32 v[16:17], v[194:195], v[42:43], v[16:17] op_sel_hi:[0,1,1]
	v_pk_fma_f32 v[18:19], v[194:195], v[50:51], v[18:19] op_sel_hi:[0,1,1]
	v_fmac_f32_e32 v8, v194, v60
	v_pk_fma_f32 v[12:13], v[196:197], v[32:33], v[12:13] op_sel_hi:[0,1,1]
	v_pk_fma_f32 v[14:15], v[196:197], v[40:41], v[14:15] op_sel_hi:[0,1,1]
	v_pk_fma_f32 v[16:17], v[196:197], v[48:49], v[16:17] op_sel_hi:[0,1,1]
	v_pk_fma_f32 v[18:19], v[196:197], v[56:57], v[18:19] op_sel_hi:[0,1,1]
	v_fmac_f32_e32 v8, v196, v61
	global_load_dword v190, v200, s[24:25]
	s_add_u32 s24, s24, 0x6000
	s_addc_u32 s25, s25, 0
	global_load_dword v192, v200, s[24:25]
	s_add_u32 s24, s24, 0x6000
	s_addc_u32 s25, s25, 0
	global_load_dword v194, v200, s[24:25]
	s_add_u32 s24, s24, 0x6000
	s_addc_u32 s25, s25, 0
	global_load_dword v196, v200, s[24:25]
	s_add_u32 s24, s24, 0x6000
	s_addc_u32 s25, s25, 0
	s_waitcnt vmcnt(56)
	v_add_u32_e32 v25, s20, v23
	ds_read_b128 v[26:29], v25
	ds_read_b128 v[30:33], v25 offset:8192
	ds_read_b128 v[34:37], v25 offset:16384
	ds_read_b128 v[38:41], v25 offset:24576
	ds_read_b128 v[42:45], v25 offset:32768
	ds_read_b128 v[46:49], v25 offset:40960
	ds_read_b128 v[50:53], v25 offset:49152
	ds_read_b128 v[54:57], v25 offset:57344
	v_add_u32_e32 v25, 0x10000, v25
	ds_read_b128 v[58:61], v25
	s_waitcnt lgkmcnt(6)
	v_mov_b32_e32 v70, v34
	v_mov_b32_e32 v71, v30
	v_mov_b32_e32 v72, v26
	s_waitcnt lgkmcnt(5)
	v_mov_b32_e32 v73, v38
	s_waitcnt lgkmcnt(4)
	v_mov_b32_e32 v74, v42
	s_waitcnt lgkmcnt(3)
	v_mov_b32_e32 v75, v46
	s_waitcnt lgkmcnt(2)
	v_mov_b32_e32 v76, v50
	s_waitcnt lgkmcnt(1)
	v_mov_b32_e32 v77, v54
	v_mov_b32_e32 v30, v35
	v_mov_b32_e32 v38, v27
	v_mov_b32_e32 v46, v43
	v_mov_b32_e32 v54, v51
	v_mov_b32_e32 v26, v36
	v_mov_b32_e32 v27, v32
	v_mov_b32_e32 v34, v28
	v_mov_b32_e32 v35, v40
	v_mov_b32_e32 v42, v44
	v_mov_b32_e32 v43, v48
	v_mov_b32_e32 v50, v52
	v_mov_b32_e32 v51, v56
	s_add_i32 s20, s20, 16
	v_mov_b32_e32 v32, v37
	v_mov_b32_e32 v40, v29
	v_mov_b32_e32 v48, v45
	v_mov_b32_e32 v56, v53
	v_pk_fma_f32 v[12:13], v[78:79], v[70:71], v[12:13] op_sel_hi:[0,1,1]
	v_pk_fma_f32 v[14:15], v[78:79], v[72:73], v[14:15] op_sel_hi:[0,1,1]
	v_pk_fma_f32 v[16:17], v[78:79], v[74:75], v[16:17] op_sel_hi:[0,1,1]
	v_pk_fma_f32 v[18:19], v[78:79], v[76:77], v[18:19] op_sel_hi:[0,1,1]
	s_waitcnt lgkmcnt(0)
	v_fmac_f32_e32 v8, v78, v58
	v_pk_fma_f32 v[12:13], v[80:81], v[30:31], v[12:13] op_sel_hi:[0,1,1]
	v_pk_fma_f32 v[14:15], v[80:81], v[38:39], v[14:15] op_sel_hi:[0,1,1]
	v_pk_fma_f32 v[16:17], v[80:81], v[46:47], v[16:17] op_sel_hi:[0,1,1]
	v_pk_fma_f32 v[18:19], v[80:81], v[54:55], v[18:19] op_sel_hi:[0,1,1]
	v_fmac_f32_e32 v8, v80, v59
	v_pk_fma_f32 v[12:13], v[82:83], v[26:27], v[12:13] op_sel_hi:[0,1,1]
	v_pk_fma_f32 v[14:15], v[82:83], v[34:35], v[14:15] op_sel_hi:[0,1,1]
	v_pk_fma_f32 v[16:17], v[82:83], v[42:43], v[16:17] op_sel_hi:[0,1,1]
	v_pk_fma_f32 v[18:19], v[82:83], v[50:51], v[18:19] op_sel_hi:[0,1,1]
	v_fmac_f32_e32 v8, v82, v60
	v_pk_fma_f32 v[12:13], v[84:85], v[32:33], v[12:13] op_sel_hi:[0,1,1]
	v_pk_fma_f32 v[14:15], v[84:85], v[40:41], v[14:15] op_sel_hi:[0,1,1]
	v_pk_fma_f32 v[16:17], v[84:85], v[48:49], v[16:17] op_sel_hi:[0,1,1]
	v_pk_fma_f32 v[18:19], v[84:85], v[56:57], v[18:19] op_sel_hi:[0,1,1]
	v_fmac_f32_e32 v8, v84, v61
	global_load_dword v78, v200, s[24:25]
	s_add_u32 s24, s24, 0x6000
	s_addc_u32 s25, s25, 0
	global_load_dword v80, v200, s[24:25]
	s_add_u32 s24, s24, 0x6000
	s_addc_u32 s25, s25, 0
	global_load_dword v82, v200, s[24:25]
	s_add_u32 s24, s24, 0x6000
	s_addc_u32 s25, s25, 0
	global_load_dword v84, v200, s[24:25]
	s_add_u32 s24, s24, 0x6000
	s_addc_u32 s25, s25, 0
	s_waitcnt vmcnt(56)
	v_add_u32_e32 v25, s20, v23
	ds_read_b128 v[26:29], v25
	ds_read_b128 v[30:33], v25 offset:8192
	ds_read_b128 v[34:37], v25 offset:16384
	ds_read_b128 v[38:41], v25 offset:24576
	ds_read_b128 v[42:45], v25 offset:32768
	ds_read_b128 v[46:49], v25 offset:40960
	ds_read_b128 v[50:53], v25 offset:49152
	ds_read_b128 v[54:57], v25 offset:57344
	v_add_u32_e32 v25, 0x10000, v25
	ds_read_b128 v[58:61], v25
	s_waitcnt lgkmcnt(6)
	v_mov_b32_e32 v70, v34
	v_mov_b32_e32 v71, v30
	v_mov_b32_e32 v72, v26
	s_waitcnt lgkmcnt(5)
	v_mov_b32_e32 v73, v38
	s_waitcnt lgkmcnt(4)
	v_mov_b32_e32 v74, v42
	s_waitcnt lgkmcnt(3)
	v_mov_b32_e32 v75, v46
	s_waitcnt lgkmcnt(2)
	v_mov_b32_e32 v76, v50
	s_waitcnt lgkmcnt(1)
	v_mov_b32_e32 v77, v54
	v_mov_b32_e32 v30, v35
	v_mov_b32_e32 v38, v27
	v_mov_b32_e32 v46, v43
	v_mov_b32_e32 v54, v51
	v_mov_b32_e32 v26, v36
	v_mov_b32_e32 v27, v32
	v_mov_b32_e32 v34, v28
	v_mov_b32_e32 v35, v40
	v_mov_b32_e32 v42, v44
	v_mov_b32_e32 v43, v48
	v_mov_b32_e32 v50, v52
	v_mov_b32_e32 v51, v56
	s_add_i32 s20, s20, 16
	v_mov_b32_e32 v32, v37
	v_mov_b32_e32 v40, v29
	v_mov_b32_e32 v48, v45
	v_mov_b32_e32 v56, v53
	v_pk_fma_f32 v[12:13], v[86:87], v[70:71], v[12:13] op_sel_hi:[0,1,1]
	v_pk_fma_f32 v[14:15], v[86:87], v[72:73], v[14:15] op_sel_hi:[0,1,1]
	v_pk_fma_f32 v[16:17], v[86:87], v[74:75], v[16:17] op_sel_hi:[0,1,1]
	v_pk_fma_f32 v[18:19], v[86:87], v[76:77], v[18:19] op_sel_hi:[0,1,1]
	s_waitcnt lgkmcnt(0)
	v_fmac_f32_e32 v8, v86, v58
	v_pk_fma_f32 v[12:13], v[88:89], v[30:31], v[12:13] op_sel_hi:[0,1,1]
	v_pk_fma_f32 v[14:15], v[88:89], v[38:39], v[14:15] op_sel_hi:[0,1,1]
	v_pk_fma_f32 v[16:17], v[88:89], v[46:47], v[16:17] op_sel_hi:[0,1,1]
	v_pk_fma_f32 v[18:19], v[88:89], v[54:55], v[18:19] op_sel_hi:[0,1,1]
	v_fmac_f32_e32 v8, v88, v59
	v_pk_fma_f32 v[12:13], v[90:91], v[26:27], v[12:13] op_sel_hi:[0,1,1]
	v_pk_fma_f32 v[14:15], v[90:91], v[34:35], v[14:15] op_sel_hi:[0,1,1]
	v_pk_fma_f32 v[16:17], v[90:91], v[42:43], v[16:17] op_sel_hi:[0,1,1]
	v_pk_fma_f32 v[18:19], v[90:91], v[50:51], v[18:19] op_sel_hi:[0,1,1]
	v_fmac_f32_e32 v8, v90, v60
	v_pk_fma_f32 v[12:13], v[92:93], v[32:33], v[12:13] op_sel_hi:[0,1,1]
	v_pk_fma_f32 v[14:15], v[92:93], v[40:41], v[14:15] op_sel_hi:[0,1,1]
	v_pk_fma_f32 v[16:17], v[92:93], v[48:49], v[16:17] op_sel_hi:[0,1,1]
	v_pk_fma_f32 v[18:19], v[92:93], v[56:57], v[18:19] op_sel_hi:[0,1,1]
	v_fmac_f32_e32 v8, v92, v61
	global_load_dword v86, v200, s[24:25]
	s_add_u32 s24, s24, 0x6000
	s_addc_u32 s25, s25, 0
	global_load_dword v88, v200, s[24:25]
	s_add_u32 s24, s24, 0x6000
	s_addc_u32 s25, s25, 0
	global_load_dword v90, v200, s[24:25]
	s_add_u32 s24, s24, 0x6000
	s_addc_u32 s25, s25, 0
	global_load_dword v92, v200, s[24:25]
	s_add_u32 s24, s24, 0x6000
	s_addc_u32 s25, s25, 0
	s_waitcnt vmcnt(56)
	v_add_u32_e32 v25, s20, v23
	ds_read_b128 v[26:29], v25
	ds_read_b128 v[30:33], v25 offset:8192
	ds_read_b128 v[34:37], v25 offset:16384
	ds_read_b128 v[38:41], v25 offset:24576
	ds_read_b128 v[42:45], v25 offset:32768
	ds_read_b128 v[46:49], v25 offset:40960
	ds_read_b128 v[50:53], v25 offset:49152
	ds_read_b128 v[54:57], v25 offset:57344
	v_add_u32_e32 v25, 0x10000, v25
	ds_read_b128 v[58:61], v25
	s_waitcnt lgkmcnt(6)
	v_mov_b32_e32 v70, v34
	v_mov_b32_e32 v71, v30
	v_mov_b32_e32 v72, v26
	s_waitcnt lgkmcnt(5)
	v_mov_b32_e32 v73, v38
	s_waitcnt lgkmcnt(4)
	v_mov_b32_e32 v74, v42
	s_waitcnt lgkmcnt(3)
	v_mov_b32_e32 v75, v46
	s_waitcnt lgkmcnt(2)
	v_mov_b32_e32 v76, v50
	s_waitcnt lgkmcnt(1)
	v_mov_b32_e32 v77, v54
	v_mov_b32_e32 v30, v35
	v_mov_b32_e32 v38, v27
	v_mov_b32_e32 v46, v43
	v_mov_b32_e32 v54, v51
	v_mov_b32_e32 v26, v36
	v_mov_b32_e32 v27, v32
	v_mov_b32_e32 v34, v28
	v_mov_b32_e32 v35, v40
	v_mov_b32_e32 v42, v44
	v_mov_b32_e32 v43, v48
	v_mov_b32_e32 v50, v52
	v_mov_b32_e32 v51, v56
	s_add_i32 s20, s20, 16
	v_mov_b32_e32 v32, v37
	v_mov_b32_e32 v40, v29
	v_mov_b32_e32 v48, v45
	v_mov_b32_e32 v56, v53
	v_pk_fma_f32 v[12:13], v[94:95], v[70:71], v[12:13] op_sel_hi:[0,1,1]
	v_pk_fma_f32 v[14:15], v[94:95], v[72:73], v[14:15] op_sel_hi:[0,1,1]
	v_pk_fma_f32 v[16:17], v[94:95], v[74:75], v[16:17] op_sel_hi:[0,1,1]
	v_pk_fma_f32 v[18:19], v[94:95], v[76:77], v[18:19] op_sel_hi:[0,1,1]
	s_waitcnt lgkmcnt(0)
	v_fmac_f32_e32 v8, v94, v58
	v_pk_fma_f32 v[12:13], v[96:97], v[30:31], v[12:13] op_sel_hi:[0,1,1]
	v_pk_fma_f32 v[14:15], v[96:97], v[38:39], v[14:15] op_sel_hi:[0,1,1]
	v_pk_fma_f32 v[16:17], v[96:97], v[46:47], v[16:17] op_sel_hi:[0,1,1]
	v_pk_fma_f32 v[18:19], v[96:97], v[54:55], v[18:19] op_sel_hi:[0,1,1]
	v_fmac_f32_e32 v8, v96, v59
	v_pk_fma_f32 v[12:13], v[98:99], v[26:27], v[12:13] op_sel_hi:[0,1,1]
	v_pk_fma_f32 v[14:15], v[98:99], v[34:35], v[14:15] op_sel_hi:[0,1,1]
	v_pk_fma_f32 v[16:17], v[98:99], v[42:43], v[16:17] op_sel_hi:[0,1,1]
	v_pk_fma_f32 v[18:19], v[98:99], v[50:51], v[18:19] op_sel_hi:[0,1,1]
	v_fmac_f32_e32 v8, v98, v60
	v_pk_fma_f32 v[12:13], v[100:101], v[32:33], v[12:13] op_sel_hi:[0,1,1]
	v_pk_fma_f32 v[14:15], v[100:101], v[40:41], v[14:15] op_sel_hi:[0,1,1]
	v_pk_fma_f32 v[16:17], v[100:101], v[48:49], v[16:17] op_sel_hi:[0,1,1]
	v_pk_fma_f32 v[18:19], v[100:101], v[56:57], v[18:19] op_sel_hi:[0,1,1]
	v_fmac_f32_e32 v8, v100, v61
	global_load_dword v94, v200, s[24:25]
	s_add_u32 s24, s24, 0x6000
	s_addc_u32 s25, s25, 0
	global_load_dword v96, v200, s[24:25]
	s_add_u32 s24, s24, 0x6000
	s_addc_u32 s25, s25, 0
	global_load_dword v98, v200, s[24:25]
	s_add_u32 s24, s24, 0x6000
	s_addc_u32 s25, s25, 0
	global_load_dword v100, v200, s[24:25]
	s_add_u32 s24, s24, 0x6000
	s_addc_u32 s25, s25, 0
	s_waitcnt vmcnt(56)
	v_add_u32_e32 v25, s20, v23
	ds_read_b128 v[26:29], v25
	ds_read_b128 v[30:33], v25 offset:8192
	ds_read_b128 v[34:37], v25 offset:16384
	ds_read_b128 v[38:41], v25 offset:24576
	ds_read_b128 v[42:45], v25 offset:32768
	ds_read_b128 v[46:49], v25 offset:40960
	ds_read_b128 v[50:53], v25 offset:49152
	ds_read_b128 v[54:57], v25 offset:57344
	v_add_u32_e32 v25, 0x10000, v25
	ds_read_b128 v[58:61], v25
	s_waitcnt lgkmcnt(6)
	v_mov_b32_e32 v70, v34
	v_mov_b32_e32 v71, v30
	v_mov_b32_e32 v72, v26
	s_waitcnt lgkmcnt(5)
	v_mov_b32_e32 v73, v38
	s_waitcnt lgkmcnt(4)
	v_mov_b32_e32 v74, v42
	s_waitcnt lgkmcnt(3)
	v_mov_b32_e32 v75, v46
	s_waitcnt lgkmcnt(2)
	v_mov_b32_e32 v76, v50
	s_waitcnt lgkmcnt(1)
	v_mov_b32_e32 v77, v54
	v_mov_b32_e32 v30, v35
	v_mov_b32_e32 v38, v27
	v_mov_b32_e32 v46, v43
	v_mov_b32_e32 v54, v51
	v_mov_b32_e32 v26, v36
	v_mov_b32_e32 v27, v32
	v_mov_b32_e32 v34, v28
	v_mov_b32_e32 v35, v40
	v_mov_b32_e32 v42, v44
	v_mov_b32_e32 v43, v48
	v_mov_b32_e32 v50, v52
	v_mov_b32_e32 v51, v56
	s_add_i32 s20, s20, 16
	v_mov_b32_e32 v32, v37
	v_mov_b32_e32 v40, v29
	v_mov_b32_e32 v48, v45
	v_mov_b32_e32 v56, v53
	v_pk_fma_f32 v[12:13], v[102:103], v[70:71], v[12:13] op_sel_hi:[0,1,1]
	v_pk_fma_f32 v[14:15], v[102:103], v[72:73], v[14:15] op_sel_hi:[0,1,1]
	v_pk_fma_f32 v[16:17], v[102:103], v[74:75], v[16:17] op_sel_hi:[0,1,1]
	v_pk_fma_f32 v[18:19], v[102:103], v[76:77], v[18:19] op_sel_hi:[0,1,1]
	s_waitcnt lgkmcnt(0)
	v_fmac_f32_e32 v8, v102, v58
	v_pk_fma_f32 v[12:13], v[104:105], v[30:31], v[12:13] op_sel_hi:[0,1,1]
	v_pk_fma_f32 v[14:15], v[104:105], v[38:39], v[14:15] op_sel_hi:[0,1,1]
	v_pk_fma_f32 v[16:17], v[104:105], v[46:47], v[16:17] op_sel_hi:[0,1,1]
	v_pk_fma_f32 v[18:19], v[104:105], v[54:55], v[18:19] op_sel_hi:[0,1,1]
	v_fmac_f32_e32 v8, v104, v59
	v_pk_fma_f32 v[12:13], v[106:107], v[26:27], v[12:13] op_sel_hi:[0,1,1]
	v_pk_fma_f32 v[14:15], v[106:107], v[34:35], v[14:15] op_sel_hi:[0,1,1]
	v_pk_fma_f32 v[16:17], v[106:107], v[42:43], v[16:17] op_sel_hi:[0,1,1]
	v_pk_fma_f32 v[18:19], v[106:107], v[50:51], v[18:19] op_sel_hi:[0,1,1]
	v_fmac_f32_e32 v8, v106, v60
	v_pk_fma_f32 v[12:13], v[108:109], v[32:33], v[12:13] op_sel_hi:[0,1,1]
	v_pk_fma_f32 v[14:15], v[108:109], v[40:41], v[14:15] op_sel_hi:[0,1,1]
	v_pk_fma_f32 v[16:17], v[108:109], v[48:49], v[16:17] op_sel_hi:[0,1,1]
	v_pk_fma_f32 v[18:19], v[108:109], v[56:57], v[18:19] op_sel_hi:[0,1,1]
	v_fmac_f32_e32 v8, v108, v61
	global_load_dword v102, v200, s[24:25]
	s_add_u32 s24, s24, 0x6000
	s_addc_u32 s25, s25, 0
	global_load_dword v104, v200, s[24:25]
	s_add_u32 s24, s24, 0x6000
	s_addc_u32 s25, s25, 0
	global_load_dword v106, v200, s[24:25]
	s_add_u32 s24, s24, 0x6000
	s_addc_u32 s25, s25, 0
	global_load_dword v108, v200, s[24:25]
	s_add_u32 s24, s24, 0x6000
	s_addc_u32 s25, s25, 0
	s_waitcnt vmcnt(56)
	v_add_u32_e32 v25, s20, v23
	ds_read_b128 v[26:29], v25
	ds_read_b128 v[30:33], v25 offset:8192
	ds_read_b128 v[34:37], v25 offset:16384
	ds_read_b128 v[38:41], v25 offset:24576
	ds_read_b128 v[42:45], v25 offset:32768
	ds_read_b128 v[46:49], v25 offset:40960
	ds_read_b128 v[50:53], v25 offset:49152
	ds_read_b128 v[54:57], v25 offset:57344
	v_add_u32_e32 v25, 0x10000, v25
	ds_read_b128 v[58:61], v25
	s_waitcnt lgkmcnt(6)
	v_mov_b32_e32 v70, v34
	v_mov_b32_e32 v71, v30
	v_mov_b32_e32 v72, v26
	s_waitcnt lgkmcnt(5)
	v_mov_b32_e32 v73, v38
	s_waitcnt lgkmcnt(4)
	v_mov_b32_e32 v74, v42
	s_waitcnt lgkmcnt(3)
	v_mov_b32_e32 v75, v46
	s_waitcnt lgkmcnt(2)
	v_mov_b32_e32 v76, v50
	s_waitcnt lgkmcnt(1)
	v_mov_b32_e32 v77, v54
	v_mov_b32_e32 v30, v35
	v_mov_b32_e32 v38, v27
	v_mov_b32_e32 v46, v43
	v_mov_b32_e32 v54, v51
	v_mov_b32_e32 v26, v36
	v_mov_b32_e32 v27, v32
	v_mov_b32_e32 v34, v28
	v_mov_b32_e32 v35, v40
	v_mov_b32_e32 v42, v44
	v_mov_b32_e32 v43, v48
	v_mov_b32_e32 v50, v52
	v_mov_b32_e32 v51, v56
	s_add_i32 s20, s20, 16
	v_mov_b32_e32 v32, v37
	v_mov_b32_e32 v40, v29
	v_mov_b32_e32 v48, v45
	v_mov_b32_e32 v56, v53
	v_pk_fma_f32 v[12:13], v[110:111], v[70:71], v[12:13] op_sel_hi:[0,1,1]
	v_pk_fma_f32 v[14:15], v[110:111], v[72:73], v[14:15] op_sel_hi:[0,1,1]
	v_pk_fma_f32 v[16:17], v[110:111], v[74:75], v[16:17] op_sel_hi:[0,1,1]
	v_pk_fma_f32 v[18:19], v[110:111], v[76:77], v[18:19] op_sel_hi:[0,1,1]
	s_waitcnt lgkmcnt(0)
	v_fmac_f32_e32 v8, v110, v58
	v_pk_fma_f32 v[12:13], v[112:113], v[30:31], v[12:13] op_sel_hi:[0,1,1]
	v_pk_fma_f32 v[14:15], v[112:113], v[38:39], v[14:15] op_sel_hi:[0,1,1]
	v_pk_fma_f32 v[16:17], v[112:113], v[46:47], v[16:17] op_sel_hi:[0,1,1]
	v_pk_fma_f32 v[18:19], v[112:113], v[54:55], v[18:19] op_sel_hi:[0,1,1]
	v_fmac_f32_e32 v8, v112, v59
	v_pk_fma_f32 v[12:13], v[114:115], v[26:27], v[12:13] op_sel_hi:[0,1,1]
	v_pk_fma_f32 v[14:15], v[114:115], v[34:35], v[14:15] op_sel_hi:[0,1,1]
	v_pk_fma_f32 v[16:17], v[114:115], v[42:43], v[16:17] op_sel_hi:[0,1,1]
	v_pk_fma_f32 v[18:19], v[114:115], v[50:51], v[18:19] op_sel_hi:[0,1,1]
	v_fmac_f32_e32 v8, v114, v60
	v_pk_fma_f32 v[12:13], v[116:117], v[32:33], v[12:13] op_sel_hi:[0,1,1]
	v_pk_fma_f32 v[14:15], v[116:117], v[40:41], v[14:15] op_sel_hi:[0,1,1]
	v_pk_fma_f32 v[16:17], v[116:117], v[48:49], v[16:17] op_sel_hi:[0,1,1]
	v_pk_fma_f32 v[18:19], v[116:117], v[56:57], v[18:19] op_sel_hi:[0,1,1]
	v_fmac_f32_e32 v8, v116, v61
	s_waitcnt vmcnt(52)
	v_add_u32_e32 v25, s20, v23
	ds_read_b128 v[26:29], v25
	ds_read_b128 v[30:33], v25 offset:8192
	ds_read_b128 v[34:37], v25 offset:16384
	ds_read_b128 v[38:41], v25 offset:24576
	ds_read_b128 v[42:45], v25 offset:32768
	ds_read_b128 v[46:49], v25 offset:40960
	ds_read_b128 v[50:53], v25 offset:49152
	ds_read_b128 v[54:57], v25 offset:57344
	v_add_u32_e32 v25, 0x10000, v25
	ds_read_b128 v[58:61], v25
	s_waitcnt lgkmcnt(6)
	v_mov_b32_e32 v70, v34
	v_mov_b32_e32 v71, v30
	v_mov_b32_e32 v72, v26
	s_waitcnt lgkmcnt(5)
	v_mov_b32_e32 v73, v38
	s_waitcnt lgkmcnt(4)
	v_mov_b32_e32 v74, v42
	s_waitcnt lgkmcnt(3)
	v_mov_b32_e32 v75, v46
	s_waitcnt lgkmcnt(2)
	v_mov_b32_e32 v76, v50
	s_waitcnt lgkmcnt(1)
	v_mov_b32_e32 v77, v54
	v_mov_b32_e32 v30, v35
	v_mov_b32_e32 v38, v27
	v_mov_b32_e32 v46, v43
	v_mov_b32_e32 v54, v51
	v_mov_b32_e32 v26, v36
	v_mov_b32_e32 v27, v32
	v_mov_b32_e32 v34, v28
	v_mov_b32_e32 v35, v40
	v_mov_b32_e32 v42, v44
	v_mov_b32_e32 v43, v48
	v_mov_b32_e32 v50, v52
	v_mov_b32_e32 v51, v56
	s_add_i32 s20, s20, 16
	v_mov_b32_e32 v32, v37
	v_mov_b32_e32 v40, v29
	v_mov_b32_e32 v48, v45
	v_mov_b32_e32 v56, v53
	v_pk_fma_f32 v[12:13], v[118:119], v[70:71], v[12:13] op_sel_hi:[0,1,1]
	v_pk_fma_f32 v[14:15], v[118:119], v[72:73], v[14:15] op_sel_hi:[0,1,1]
	v_pk_fma_f32 v[16:17], v[118:119], v[74:75], v[16:17] op_sel_hi:[0,1,1]
	v_pk_fma_f32 v[18:19], v[118:119], v[76:77], v[18:19] op_sel_hi:[0,1,1]
	s_waitcnt lgkmcnt(0)
	v_fmac_f32_e32 v8, v118, v58
	v_pk_fma_f32 v[12:13], v[120:121], v[30:31], v[12:13] op_sel_hi:[0,1,1]
	v_pk_fma_f32 v[14:15], v[120:121], v[38:39], v[14:15] op_sel_hi:[0,1,1]
	v_pk_fma_f32 v[16:17], v[120:121], v[46:47], v[16:17] op_sel_hi:[0,1,1]
	v_pk_fma_f32 v[18:19], v[120:121], v[54:55], v[18:19] op_sel_hi:[0,1,1]
	v_fmac_f32_e32 v8, v120, v59
	v_pk_fma_f32 v[12:13], v[122:123], v[26:27], v[12:13] op_sel_hi:[0,1,1]
	v_pk_fma_f32 v[14:15], v[122:123], v[34:35], v[14:15] op_sel_hi:[0,1,1]
	v_pk_fma_f32 v[16:17], v[122:123], v[42:43], v[16:17] op_sel_hi:[0,1,1]
	v_pk_fma_f32 v[18:19], v[122:123], v[50:51], v[18:19] op_sel_hi:[0,1,1]
	v_fmac_f32_e32 v8, v122, v60
	v_pk_fma_f32 v[12:13], v[124:125], v[32:33], v[12:13] op_sel_hi:[0,1,1]
	v_pk_fma_f32 v[14:15], v[124:125], v[40:41], v[14:15] op_sel_hi:[0,1,1]
	v_pk_fma_f32 v[16:17], v[124:125], v[48:49], v[16:17] op_sel_hi:[0,1,1]
	v_pk_fma_f32 v[18:19], v[124:125], v[56:57], v[18:19] op_sel_hi:[0,1,1]
	v_fmac_f32_e32 v8, v124, v61
	s_waitcnt vmcnt(48)
	v_add_u32_e32 v25, s20, v23
	ds_read_b128 v[26:29], v25
	ds_read_b128 v[30:33], v25 offset:8192
	ds_read_b128 v[34:37], v25 offset:16384
	ds_read_b128 v[38:41], v25 offset:24576
	ds_read_b128 v[42:45], v25 offset:32768
	ds_read_b128 v[46:49], v25 offset:40960
	ds_read_b128 v[50:53], v25 offset:49152
	ds_read_b128 v[54:57], v25 offset:57344
	v_add_u32_e32 v25, 0x10000, v25
	ds_read_b128 v[58:61], v25
	s_waitcnt lgkmcnt(6)
	v_mov_b32_e32 v70, v34
	v_mov_b32_e32 v71, v30
	v_mov_b32_e32 v72, v26
	s_waitcnt lgkmcnt(5)
	v_mov_b32_e32 v73, v38
	s_waitcnt lgkmcnt(4)
	v_mov_b32_e32 v74, v42
	s_waitcnt lgkmcnt(3)
	v_mov_b32_e32 v75, v46
	s_waitcnt lgkmcnt(2)
	v_mov_b32_e32 v76, v50
	s_waitcnt lgkmcnt(1)
	v_mov_b32_e32 v77, v54
	v_mov_b32_e32 v30, v35
	v_mov_b32_e32 v38, v27
	v_mov_b32_e32 v46, v43
	v_mov_b32_e32 v54, v51
	v_mov_b32_e32 v26, v36
	v_mov_b32_e32 v27, v32
	v_mov_b32_e32 v34, v28
	v_mov_b32_e32 v35, v40
	v_mov_b32_e32 v42, v44
	v_mov_b32_e32 v43, v48
	v_mov_b32_e32 v50, v52
	v_mov_b32_e32 v51, v56
	s_add_i32 s20, s20, 16
	v_mov_b32_e32 v32, v37
	v_mov_b32_e32 v40, v29
	v_mov_b32_e32 v48, v45
	v_mov_b32_e32 v56, v53
	v_pk_fma_f32 v[12:13], v[126:127], v[70:71], v[12:13] op_sel_hi:[0,1,1]
	v_pk_fma_f32 v[14:15], v[126:127], v[72:73], v[14:15] op_sel_hi:[0,1,1]
	v_pk_fma_f32 v[16:17], v[126:127], v[74:75], v[16:17] op_sel_hi:[0,1,1]
	v_pk_fma_f32 v[18:19], v[126:127], v[76:77], v[18:19] op_sel_hi:[0,1,1]
	s_waitcnt lgkmcnt(0)
	v_fmac_f32_e32 v8, v126, v58
	v_pk_fma_f32 v[12:13], v[128:129], v[30:31], v[12:13] op_sel_hi:[0,1,1]
	v_pk_fma_f32 v[14:15], v[128:129], v[38:39], v[14:15] op_sel_hi:[0,1,1]
	v_pk_fma_f32 v[16:17], v[128:129], v[46:47], v[16:17] op_sel_hi:[0,1,1]
	v_pk_fma_f32 v[18:19], v[128:129], v[54:55], v[18:19] op_sel_hi:[0,1,1]
	v_fmac_f32_e32 v8, v128, v59
	v_pk_fma_f32 v[12:13], v[130:131], v[26:27], v[12:13] op_sel_hi:[0,1,1]
	v_pk_fma_f32 v[14:15], v[130:131], v[34:35], v[14:15] op_sel_hi:[0,1,1]
	v_pk_fma_f32 v[16:17], v[130:131], v[42:43], v[16:17] op_sel_hi:[0,1,1]
	v_pk_fma_f32 v[18:19], v[130:131], v[50:51], v[18:19] op_sel_hi:[0,1,1]
	v_fmac_f32_e32 v8, v130, v60
	v_pk_fma_f32 v[12:13], v[132:133], v[32:33], v[12:13] op_sel_hi:[0,1,1]
	v_pk_fma_f32 v[14:15], v[132:133], v[40:41], v[14:15] op_sel_hi:[0,1,1]
	v_pk_fma_f32 v[16:17], v[132:133], v[48:49], v[16:17] op_sel_hi:[0,1,1]
	v_pk_fma_f32 v[18:19], v[132:133], v[56:57], v[18:19] op_sel_hi:[0,1,1]
	v_fmac_f32_e32 v8, v132, v61
	s_waitcnt vmcnt(44)
	v_add_u32_e32 v25, s20, v23
	ds_read_b128 v[26:29], v25
	ds_read_b128 v[30:33], v25 offset:8192
	ds_read_b128 v[34:37], v25 offset:16384
	ds_read_b128 v[38:41], v25 offset:24576
	ds_read_b128 v[42:45], v25 offset:32768
	ds_read_b128 v[46:49], v25 offset:40960
	ds_read_b128 v[50:53], v25 offset:49152
	ds_read_b128 v[54:57], v25 offset:57344
	v_add_u32_e32 v25, 0x10000, v25
	ds_read_b128 v[58:61], v25
	s_waitcnt lgkmcnt(6)
	v_mov_b32_e32 v70, v34
	v_mov_b32_e32 v71, v30
	v_mov_b32_e32 v72, v26
	s_waitcnt lgkmcnt(5)
	v_mov_b32_e32 v73, v38
	s_waitcnt lgkmcnt(4)
	v_mov_b32_e32 v74, v42
	s_waitcnt lgkmcnt(3)
	v_mov_b32_e32 v75, v46
	s_waitcnt lgkmcnt(2)
	v_mov_b32_e32 v76, v50
	s_waitcnt lgkmcnt(1)
	v_mov_b32_e32 v77, v54
	v_mov_b32_e32 v30, v35
	v_mov_b32_e32 v38, v27
	v_mov_b32_e32 v46, v43
	v_mov_b32_e32 v54, v51
	v_mov_b32_e32 v26, v36
	v_mov_b32_e32 v27, v32
	v_mov_b32_e32 v34, v28
	v_mov_b32_e32 v35, v40
	v_mov_b32_e32 v42, v44
	v_mov_b32_e32 v43, v48
	v_mov_b32_e32 v50, v52
	v_mov_b32_e32 v51, v56
	s_add_i32 s20, s20, 16
	v_mov_b32_e32 v32, v37
	v_mov_b32_e32 v40, v29
	v_mov_b32_e32 v48, v45
	v_mov_b32_e32 v56, v53
	v_pk_fma_f32 v[12:13], v[134:135], v[70:71], v[12:13] op_sel_hi:[0,1,1]
	v_pk_fma_f32 v[14:15], v[134:135], v[72:73], v[14:15] op_sel_hi:[0,1,1]
	v_pk_fma_f32 v[16:17], v[134:135], v[74:75], v[16:17] op_sel_hi:[0,1,1]
	v_pk_fma_f32 v[18:19], v[134:135], v[76:77], v[18:19] op_sel_hi:[0,1,1]
	s_waitcnt lgkmcnt(0)
	v_fmac_f32_e32 v8, v134, v58
	v_pk_fma_f32 v[12:13], v[136:137], v[30:31], v[12:13] op_sel_hi:[0,1,1]
	v_pk_fma_f32 v[14:15], v[136:137], v[38:39], v[14:15] op_sel_hi:[0,1,1]
	v_pk_fma_f32 v[16:17], v[136:137], v[46:47], v[16:17] op_sel_hi:[0,1,1]
	v_pk_fma_f32 v[18:19], v[136:137], v[54:55], v[18:19] op_sel_hi:[0,1,1]
	v_fmac_f32_e32 v8, v136, v59
	v_pk_fma_f32 v[12:13], v[138:139], v[26:27], v[12:13] op_sel_hi:[0,1,1]
	v_pk_fma_f32 v[14:15], v[138:139], v[34:35], v[14:15] op_sel_hi:[0,1,1]
	v_pk_fma_f32 v[16:17], v[138:139], v[42:43], v[16:17] op_sel_hi:[0,1,1]
	v_pk_fma_f32 v[18:19], v[138:139], v[50:51], v[18:19] op_sel_hi:[0,1,1]
	v_fmac_f32_e32 v8, v138, v60
	v_pk_fma_f32 v[12:13], v[140:141], v[32:33], v[12:13] op_sel_hi:[0,1,1]
	v_pk_fma_f32 v[14:15], v[140:141], v[40:41], v[14:15] op_sel_hi:[0,1,1]
	v_pk_fma_f32 v[16:17], v[140:141], v[48:49], v[16:17] op_sel_hi:[0,1,1]
	v_pk_fma_f32 v[18:19], v[140:141], v[56:57], v[18:19] op_sel_hi:[0,1,1]
	v_fmac_f32_e32 v8, v140, v61
	s_waitcnt vmcnt(40)
	v_add_u32_e32 v25, s20, v23
	ds_read_b128 v[26:29], v25
	ds_read_b128 v[30:33], v25 offset:8192
	ds_read_b128 v[34:37], v25 offset:16384
	ds_read_b128 v[38:41], v25 offset:24576
	ds_read_b128 v[42:45], v25 offset:32768
	ds_read_b128 v[46:49], v25 offset:40960
	ds_read_b128 v[50:53], v25 offset:49152
	ds_read_b128 v[54:57], v25 offset:57344
	v_add_u32_e32 v25, 0x10000, v25
	ds_read_b128 v[58:61], v25
	s_waitcnt lgkmcnt(6)
	v_mov_b32_e32 v70, v34
	v_mov_b32_e32 v71, v30
	v_mov_b32_e32 v72, v26
	s_waitcnt lgkmcnt(5)
	v_mov_b32_e32 v73, v38
	s_waitcnt lgkmcnt(4)
	v_mov_b32_e32 v74, v42
	s_waitcnt lgkmcnt(3)
	v_mov_b32_e32 v75, v46
	s_waitcnt lgkmcnt(2)
	v_mov_b32_e32 v76, v50
	s_waitcnt lgkmcnt(1)
	v_mov_b32_e32 v77, v54
	v_mov_b32_e32 v30, v35
	v_mov_b32_e32 v38, v27
	v_mov_b32_e32 v46, v43
	v_mov_b32_e32 v54, v51
	v_mov_b32_e32 v26, v36
	v_mov_b32_e32 v27, v32
	v_mov_b32_e32 v34, v28
	v_mov_b32_e32 v35, v40
	v_mov_b32_e32 v42, v44
	v_mov_b32_e32 v43, v48
	v_mov_b32_e32 v50, v52
	v_mov_b32_e32 v51, v56
	s_add_i32 s20, s20, 16
	v_mov_b32_e32 v32, v37
	v_mov_b32_e32 v40, v29
	v_mov_b32_e32 v48, v45
	v_mov_b32_e32 v56, v53
	v_pk_fma_f32 v[12:13], v[142:143], v[70:71], v[12:13] op_sel_hi:[0,1,1]
	v_pk_fma_f32 v[14:15], v[142:143], v[72:73], v[14:15] op_sel_hi:[0,1,1]
	v_pk_fma_f32 v[16:17], v[142:143], v[74:75], v[16:17] op_sel_hi:[0,1,1]
	v_pk_fma_f32 v[18:19], v[142:143], v[76:77], v[18:19] op_sel_hi:[0,1,1]
	s_waitcnt lgkmcnt(0)
	v_fmac_f32_e32 v8, v142, v58
	v_pk_fma_f32 v[12:13], v[144:145], v[30:31], v[12:13] op_sel_hi:[0,1,1]
	v_pk_fma_f32 v[14:15], v[144:145], v[38:39], v[14:15] op_sel_hi:[0,1,1]
	v_pk_fma_f32 v[16:17], v[144:145], v[46:47], v[16:17] op_sel_hi:[0,1,1]
	v_pk_fma_f32 v[18:19], v[144:145], v[54:55], v[18:19] op_sel_hi:[0,1,1]
	v_fmac_f32_e32 v8, v144, v59
	v_pk_fma_f32 v[12:13], v[146:147], v[26:27], v[12:13] op_sel_hi:[0,1,1]
	v_pk_fma_f32 v[14:15], v[146:147], v[34:35], v[14:15] op_sel_hi:[0,1,1]
	v_pk_fma_f32 v[16:17], v[146:147], v[42:43], v[16:17] op_sel_hi:[0,1,1]
	v_pk_fma_f32 v[18:19], v[146:147], v[50:51], v[18:19] op_sel_hi:[0,1,1]
	v_fmac_f32_e32 v8, v146, v60
	v_pk_fma_f32 v[12:13], v[148:149], v[32:33], v[12:13] op_sel_hi:[0,1,1]
	v_pk_fma_f32 v[14:15], v[148:149], v[40:41], v[14:15] op_sel_hi:[0,1,1]
	v_pk_fma_f32 v[16:17], v[148:149], v[48:49], v[16:17] op_sel_hi:[0,1,1]
	v_pk_fma_f32 v[18:19], v[148:149], v[56:57], v[18:19] op_sel_hi:[0,1,1]
	v_fmac_f32_e32 v8, v148, v61
	s_waitcnt vmcnt(36)
	v_add_u32_e32 v25, s20, v23
	ds_read_b128 v[26:29], v25
	ds_read_b128 v[30:33], v25 offset:8192
	ds_read_b128 v[34:37], v25 offset:16384
	ds_read_b128 v[38:41], v25 offset:24576
	ds_read_b128 v[42:45], v25 offset:32768
	ds_read_b128 v[46:49], v25 offset:40960
	ds_read_b128 v[50:53], v25 offset:49152
	ds_read_b128 v[54:57], v25 offset:57344
	v_add_u32_e32 v25, 0x10000, v25
	ds_read_b128 v[58:61], v25
	s_waitcnt lgkmcnt(6)
	v_mov_b32_e32 v70, v34
	v_mov_b32_e32 v71, v30
	v_mov_b32_e32 v72, v26
	s_waitcnt lgkmcnt(5)
	v_mov_b32_e32 v73, v38
	s_waitcnt lgkmcnt(4)
	v_mov_b32_e32 v74, v42
	s_waitcnt lgkmcnt(3)
	v_mov_b32_e32 v75, v46
	s_waitcnt lgkmcnt(2)
	v_mov_b32_e32 v76, v50
	s_waitcnt lgkmcnt(1)
	v_mov_b32_e32 v77, v54
	v_mov_b32_e32 v30, v35
	v_mov_b32_e32 v38, v27
	v_mov_b32_e32 v46, v43
	v_mov_b32_e32 v54, v51
	v_mov_b32_e32 v26, v36
	v_mov_b32_e32 v27, v32
	v_mov_b32_e32 v34, v28
	v_mov_b32_e32 v35, v40
	v_mov_b32_e32 v42, v44
	v_mov_b32_e32 v43, v48
	v_mov_b32_e32 v50, v52
	v_mov_b32_e32 v51, v56
	s_add_i32 s20, s20, 16
	v_mov_b32_e32 v32, v37
	v_mov_b32_e32 v40, v29
	v_mov_b32_e32 v48, v45
	v_mov_b32_e32 v56, v53
	v_pk_fma_f32 v[12:13], v[150:151], v[70:71], v[12:13] op_sel_hi:[0,1,1]
	v_pk_fma_f32 v[14:15], v[150:151], v[72:73], v[14:15] op_sel_hi:[0,1,1]
	v_pk_fma_f32 v[16:17], v[150:151], v[74:75], v[16:17] op_sel_hi:[0,1,1]
	v_pk_fma_f32 v[18:19], v[150:151], v[76:77], v[18:19] op_sel_hi:[0,1,1]
	s_waitcnt lgkmcnt(0)
	v_fmac_f32_e32 v8, v150, v58
	v_pk_fma_f32 v[12:13], v[152:153], v[30:31], v[12:13] op_sel_hi:[0,1,1]
	v_pk_fma_f32 v[14:15], v[152:153], v[38:39], v[14:15] op_sel_hi:[0,1,1]
	v_pk_fma_f32 v[16:17], v[152:153], v[46:47], v[16:17] op_sel_hi:[0,1,1]
	v_pk_fma_f32 v[18:19], v[152:153], v[54:55], v[18:19] op_sel_hi:[0,1,1]
	v_fmac_f32_e32 v8, v152, v59
	v_pk_fma_f32 v[12:13], v[154:155], v[26:27], v[12:13] op_sel_hi:[0,1,1]
	v_pk_fma_f32 v[14:15], v[154:155], v[34:35], v[14:15] op_sel_hi:[0,1,1]
	v_pk_fma_f32 v[16:17], v[154:155], v[42:43], v[16:17] op_sel_hi:[0,1,1]
	v_pk_fma_f32 v[18:19], v[154:155], v[50:51], v[18:19] op_sel_hi:[0,1,1]
	v_fmac_f32_e32 v8, v154, v60
	v_pk_fma_f32 v[12:13], v[156:157], v[32:33], v[12:13] op_sel_hi:[0,1,1]
	v_pk_fma_f32 v[14:15], v[156:157], v[40:41], v[14:15] op_sel_hi:[0,1,1]
	v_pk_fma_f32 v[16:17], v[156:157], v[48:49], v[16:17] op_sel_hi:[0,1,1]
	v_pk_fma_f32 v[18:19], v[156:157], v[56:57], v[18:19] op_sel_hi:[0,1,1]
	v_fmac_f32_e32 v8, v156, v61
	s_waitcnt vmcnt(32)
	v_add_u32_e32 v25, s20, v23
	ds_read_b128 v[26:29], v25
	ds_read_b128 v[30:33], v25 offset:8192
	ds_read_b128 v[34:37], v25 offset:16384
	ds_read_b128 v[38:41], v25 offset:24576
	ds_read_b128 v[42:45], v25 offset:32768
	ds_read_b128 v[46:49], v25 offset:40960
	ds_read_b128 v[50:53], v25 offset:49152
	ds_read_b128 v[54:57], v25 offset:57344
	v_add_u32_e32 v25, 0x10000, v25
	ds_read_b128 v[58:61], v25
	s_waitcnt lgkmcnt(6)
	v_mov_b32_e32 v70, v34
	v_mov_b32_e32 v71, v30
	v_mov_b32_e32 v72, v26
	s_waitcnt lgkmcnt(5)
	v_mov_b32_e32 v73, v38
	s_waitcnt lgkmcnt(4)
	v_mov_b32_e32 v74, v42
	s_waitcnt lgkmcnt(3)
	v_mov_b32_e32 v75, v46
	s_waitcnt lgkmcnt(2)
	v_mov_b32_e32 v76, v50
	s_waitcnt lgkmcnt(1)
	v_mov_b32_e32 v77, v54
	v_mov_b32_e32 v30, v35
	v_mov_b32_e32 v38, v27
	v_mov_b32_e32 v46, v43
	v_mov_b32_e32 v54, v51
	v_mov_b32_e32 v26, v36
	v_mov_b32_e32 v27, v32
	v_mov_b32_e32 v34, v28
	v_mov_b32_e32 v35, v40
	v_mov_b32_e32 v42, v44
	v_mov_b32_e32 v43, v48
	v_mov_b32_e32 v50, v52
	v_mov_b32_e32 v51, v56
	s_add_i32 s20, s20, 16
	v_mov_b32_e32 v32, v37
	v_mov_b32_e32 v40, v29
	v_mov_b32_e32 v48, v45
	v_mov_b32_e32 v56, v53
	v_pk_fma_f32 v[12:13], v[158:159], v[70:71], v[12:13] op_sel_hi:[0,1,1]
	v_pk_fma_f32 v[14:15], v[158:159], v[72:73], v[14:15] op_sel_hi:[0,1,1]
	v_pk_fma_f32 v[16:17], v[158:159], v[74:75], v[16:17] op_sel_hi:[0,1,1]
	v_pk_fma_f32 v[18:19], v[158:159], v[76:77], v[18:19] op_sel_hi:[0,1,1]
	s_waitcnt lgkmcnt(0)
	v_fmac_f32_e32 v8, v158, v58
	v_pk_fma_f32 v[12:13], v[160:161], v[30:31], v[12:13] op_sel_hi:[0,1,1]
	v_pk_fma_f32 v[14:15], v[160:161], v[38:39], v[14:15] op_sel_hi:[0,1,1]
	v_pk_fma_f32 v[16:17], v[160:161], v[46:47], v[16:17] op_sel_hi:[0,1,1]
	v_pk_fma_f32 v[18:19], v[160:161], v[54:55], v[18:19] op_sel_hi:[0,1,1]
	v_fmac_f32_e32 v8, v160, v59
	v_pk_fma_f32 v[12:13], v[162:163], v[26:27], v[12:13] op_sel_hi:[0,1,1]
	v_pk_fma_f32 v[14:15], v[162:163], v[34:35], v[14:15] op_sel_hi:[0,1,1]
	v_pk_fma_f32 v[16:17], v[162:163], v[42:43], v[16:17] op_sel_hi:[0,1,1]
	v_pk_fma_f32 v[18:19], v[162:163], v[50:51], v[18:19] op_sel_hi:[0,1,1]
	v_fmac_f32_e32 v8, v162, v60
	v_pk_fma_f32 v[12:13], v[164:165], v[32:33], v[12:13] op_sel_hi:[0,1,1]
	v_pk_fma_f32 v[14:15], v[164:165], v[40:41], v[14:15] op_sel_hi:[0,1,1]
	v_pk_fma_f32 v[16:17], v[164:165], v[48:49], v[16:17] op_sel_hi:[0,1,1]
	v_pk_fma_f32 v[18:19], v[164:165], v[56:57], v[18:19] op_sel_hi:[0,1,1]
	v_fmac_f32_e32 v8, v164, v61
	s_waitcnt vmcnt(28)
	v_add_u32_e32 v25, s20, v23
	ds_read_b128 v[26:29], v25
	ds_read_b128 v[30:33], v25 offset:8192
	ds_read_b128 v[34:37], v25 offset:16384
	ds_read_b128 v[38:41], v25 offset:24576
	ds_read_b128 v[42:45], v25 offset:32768
	ds_read_b128 v[46:49], v25 offset:40960
	ds_read_b128 v[50:53], v25 offset:49152
	ds_read_b128 v[54:57], v25 offset:57344
	v_add_u32_e32 v25, 0x10000, v25
	ds_read_b128 v[58:61], v25
	s_waitcnt lgkmcnt(6)
	v_mov_b32_e32 v70, v34
	v_mov_b32_e32 v71, v30
	v_mov_b32_e32 v72, v26
	s_waitcnt lgkmcnt(5)
	v_mov_b32_e32 v73, v38
	s_waitcnt lgkmcnt(4)
	v_mov_b32_e32 v74, v42
	s_waitcnt lgkmcnt(3)
	v_mov_b32_e32 v75, v46
	s_waitcnt lgkmcnt(2)
	v_mov_b32_e32 v76, v50
	s_waitcnt lgkmcnt(1)
	v_mov_b32_e32 v77, v54
	v_mov_b32_e32 v30, v35
	v_mov_b32_e32 v38, v27
	v_mov_b32_e32 v46, v43
	v_mov_b32_e32 v54, v51
	v_mov_b32_e32 v26, v36
	v_mov_b32_e32 v27, v32
	v_mov_b32_e32 v34, v28
	v_mov_b32_e32 v35, v40
	v_mov_b32_e32 v42, v44
	v_mov_b32_e32 v43, v48
	v_mov_b32_e32 v50, v52
	v_mov_b32_e32 v51, v56
	s_add_i32 s20, s20, 16
	v_mov_b32_e32 v32, v37
	v_mov_b32_e32 v40, v29
	v_mov_b32_e32 v48, v45
	v_mov_b32_e32 v56, v53
	v_pk_fma_f32 v[12:13], v[166:167], v[70:71], v[12:13] op_sel_hi:[0,1,1]
	v_pk_fma_f32 v[14:15], v[166:167], v[72:73], v[14:15] op_sel_hi:[0,1,1]
	v_pk_fma_f32 v[16:17], v[166:167], v[74:75], v[16:17] op_sel_hi:[0,1,1]
	v_pk_fma_f32 v[18:19], v[166:167], v[76:77], v[18:19] op_sel_hi:[0,1,1]
	s_waitcnt lgkmcnt(0)
	v_fmac_f32_e32 v8, v166, v58
	v_pk_fma_f32 v[12:13], v[168:169], v[30:31], v[12:13] op_sel_hi:[0,1,1]
	v_pk_fma_f32 v[14:15], v[168:169], v[38:39], v[14:15] op_sel_hi:[0,1,1]
	v_pk_fma_f32 v[16:17], v[168:169], v[46:47], v[16:17] op_sel_hi:[0,1,1]
	v_pk_fma_f32 v[18:19], v[168:169], v[54:55], v[18:19] op_sel_hi:[0,1,1]
	v_fmac_f32_e32 v8, v168, v59
	v_pk_fma_f32 v[12:13], v[170:171], v[26:27], v[12:13] op_sel_hi:[0,1,1]
	v_pk_fma_f32 v[14:15], v[170:171], v[34:35], v[14:15] op_sel_hi:[0,1,1]
	v_pk_fma_f32 v[16:17], v[170:171], v[42:43], v[16:17] op_sel_hi:[0,1,1]
	v_pk_fma_f32 v[18:19], v[170:171], v[50:51], v[18:19] op_sel_hi:[0,1,1]
	v_fmac_f32_e32 v8, v170, v60
	v_pk_fma_f32 v[12:13], v[172:173], v[32:33], v[12:13] op_sel_hi:[0,1,1]
	v_pk_fma_f32 v[14:15], v[172:173], v[40:41], v[14:15] op_sel_hi:[0,1,1]
	v_pk_fma_f32 v[16:17], v[172:173], v[48:49], v[16:17] op_sel_hi:[0,1,1]
	v_pk_fma_f32 v[18:19], v[172:173], v[56:57], v[18:19] op_sel_hi:[0,1,1]
	v_fmac_f32_e32 v8, v172, v61
	s_waitcnt vmcnt(24)
	v_add_u32_e32 v25, s20, v23
	ds_read_b128 v[26:29], v25
	ds_read_b128 v[30:33], v25 offset:8192
	ds_read_b128 v[34:37], v25 offset:16384
	ds_read_b128 v[38:41], v25 offset:24576
	ds_read_b128 v[42:45], v25 offset:32768
	ds_read_b128 v[46:49], v25 offset:40960
	ds_read_b128 v[50:53], v25 offset:49152
	ds_read_b128 v[54:57], v25 offset:57344
	v_add_u32_e32 v25, 0x10000, v25
	ds_read_b128 v[58:61], v25
	s_waitcnt lgkmcnt(6)
	v_mov_b32_e32 v70, v34
	v_mov_b32_e32 v71, v30
	v_mov_b32_e32 v72, v26
	s_waitcnt lgkmcnt(5)
	v_mov_b32_e32 v73, v38
	s_waitcnt lgkmcnt(4)
	v_mov_b32_e32 v74, v42
	s_waitcnt lgkmcnt(3)
	v_mov_b32_e32 v75, v46
	s_waitcnt lgkmcnt(2)
	v_mov_b32_e32 v76, v50
	s_waitcnt lgkmcnt(1)
	v_mov_b32_e32 v77, v54
	v_mov_b32_e32 v30, v35
	v_mov_b32_e32 v38, v27
	v_mov_b32_e32 v46, v43
	v_mov_b32_e32 v54, v51
	v_mov_b32_e32 v26, v36
	v_mov_b32_e32 v27, v32
	v_mov_b32_e32 v34, v28
	v_mov_b32_e32 v35, v40
	v_mov_b32_e32 v42, v44
	v_mov_b32_e32 v43, v48
	v_mov_b32_e32 v50, v52
	v_mov_b32_e32 v51, v56
	s_add_i32 s20, s20, 16
	v_mov_b32_e32 v32, v37
	v_mov_b32_e32 v40, v29
	v_mov_b32_e32 v48, v45
	v_mov_b32_e32 v56, v53
	v_pk_fma_f32 v[12:13], v[174:175], v[70:71], v[12:13] op_sel_hi:[0,1,1]
	v_pk_fma_f32 v[14:15], v[174:175], v[72:73], v[14:15] op_sel_hi:[0,1,1]
	v_pk_fma_f32 v[16:17], v[174:175], v[74:75], v[16:17] op_sel_hi:[0,1,1]
	v_pk_fma_f32 v[18:19], v[174:175], v[76:77], v[18:19] op_sel_hi:[0,1,1]
	s_waitcnt lgkmcnt(0)
	v_fmac_f32_e32 v8, v174, v58
	v_pk_fma_f32 v[12:13], v[176:177], v[30:31], v[12:13] op_sel_hi:[0,1,1]
	v_pk_fma_f32 v[14:15], v[176:177], v[38:39], v[14:15] op_sel_hi:[0,1,1]
	v_pk_fma_f32 v[16:17], v[176:177], v[46:47], v[16:17] op_sel_hi:[0,1,1]
	v_pk_fma_f32 v[18:19], v[176:177], v[54:55], v[18:19] op_sel_hi:[0,1,1]
	v_fmac_f32_e32 v8, v176, v59
	v_pk_fma_f32 v[12:13], v[178:179], v[26:27], v[12:13] op_sel_hi:[0,1,1]
	v_pk_fma_f32 v[14:15], v[178:179], v[34:35], v[14:15] op_sel_hi:[0,1,1]
	v_pk_fma_f32 v[16:17], v[178:179], v[42:43], v[16:17] op_sel_hi:[0,1,1]
	v_pk_fma_f32 v[18:19], v[178:179], v[50:51], v[18:19] op_sel_hi:[0,1,1]
	v_fmac_f32_e32 v8, v178, v60
	v_pk_fma_f32 v[12:13], v[180:181], v[32:33], v[12:13] op_sel_hi:[0,1,1]
	v_pk_fma_f32 v[14:15], v[180:181], v[40:41], v[14:15] op_sel_hi:[0,1,1]
	v_pk_fma_f32 v[16:17], v[180:181], v[48:49], v[16:17] op_sel_hi:[0,1,1]
	v_pk_fma_f32 v[18:19], v[180:181], v[56:57], v[18:19] op_sel_hi:[0,1,1]
	v_fmac_f32_e32 v8, v180, v61
	s_waitcnt vmcnt(20)
	v_add_u32_e32 v25, s20, v23
	ds_read_b128 v[26:29], v25
	ds_read_b128 v[30:33], v25 offset:8192
	ds_read_b128 v[34:37], v25 offset:16384
	ds_read_b128 v[38:41], v25 offset:24576
	ds_read_b128 v[42:45], v25 offset:32768
	ds_read_b128 v[46:49], v25 offset:40960
	ds_read_b128 v[50:53], v25 offset:49152
	ds_read_b128 v[54:57], v25 offset:57344
	v_add_u32_e32 v25, 0x10000, v25
	ds_read_b128 v[58:61], v25
	s_waitcnt lgkmcnt(6)
	v_mov_b32_e32 v70, v34
	v_mov_b32_e32 v71, v30
	v_mov_b32_e32 v72, v26
	s_waitcnt lgkmcnt(5)
	v_mov_b32_e32 v73, v38
	s_waitcnt lgkmcnt(4)
	v_mov_b32_e32 v74, v42
	s_waitcnt lgkmcnt(3)
	v_mov_b32_e32 v75, v46
	s_waitcnt lgkmcnt(2)
	v_mov_b32_e32 v76, v50
	s_waitcnt lgkmcnt(1)
	v_mov_b32_e32 v77, v54
	v_mov_b32_e32 v30, v35
	v_mov_b32_e32 v38, v27
	v_mov_b32_e32 v46, v43
	v_mov_b32_e32 v54, v51
	v_mov_b32_e32 v26, v36
	v_mov_b32_e32 v27, v32
	v_mov_b32_e32 v34, v28
	v_mov_b32_e32 v35, v40
	v_mov_b32_e32 v42, v44
	v_mov_b32_e32 v43, v48
	v_mov_b32_e32 v50, v52
	v_mov_b32_e32 v51, v56
	s_add_i32 s20, s20, 16
	v_mov_b32_e32 v32, v37
	v_mov_b32_e32 v40, v29
	v_mov_b32_e32 v48, v45
	v_mov_b32_e32 v56, v53
	v_pk_fma_f32 v[12:13], v[182:183], v[70:71], v[12:13] op_sel_hi:[0,1,1]
	v_pk_fma_f32 v[14:15], v[182:183], v[72:73], v[14:15] op_sel_hi:[0,1,1]
	v_pk_fma_f32 v[16:17], v[182:183], v[74:75], v[16:17] op_sel_hi:[0,1,1]
	v_pk_fma_f32 v[18:19], v[182:183], v[76:77], v[18:19] op_sel_hi:[0,1,1]
	s_waitcnt lgkmcnt(0)
	v_fmac_f32_e32 v8, v182, v58
	v_pk_fma_f32 v[12:13], v[184:185], v[30:31], v[12:13] op_sel_hi:[0,1,1]
	v_pk_fma_f32 v[14:15], v[184:185], v[38:39], v[14:15] op_sel_hi:[0,1,1]
	v_pk_fma_f32 v[16:17], v[184:185], v[46:47], v[16:17] op_sel_hi:[0,1,1]
	v_pk_fma_f32 v[18:19], v[184:185], v[54:55], v[18:19] op_sel_hi:[0,1,1]
	v_fmac_f32_e32 v8, v184, v59
	v_pk_fma_f32 v[12:13], v[186:187], v[26:27], v[12:13] op_sel_hi:[0,1,1]
	v_pk_fma_f32 v[14:15], v[186:187], v[34:35], v[14:15] op_sel_hi:[0,1,1]
	v_pk_fma_f32 v[16:17], v[186:187], v[42:43], v[16:17] op_sel_hi:[0,1,1]
	v_pk_fma_f32 v[18:19], v[186:187], v[50:51], v[18:19] op_sel_hi:[0,1,1]
	v_fmac_f32_e32 v8, v186, v60
	v_pk_fma_f32 v[12:13], v[188:189], v[32:33], v[12:13] op_sel_hi:[0,1,1]
	v_pk_fma_f32 v[14:15], v[188:189], v[40:41], v[14:15] op_sel_hi:[0,1,1]
	v_pk_fma_f32 v[16:17], v[188:189], v[48:49], v[16:17] op_sel_hi:[0,1,1]
	v_pk_fma_f32 v[18:19], v[188:189], v[56:57], v[18:19] op_sel_hi:[0,1,1]
	v_fmac_f32_e32 v8, v188, v61
	s_waitcnt vmcnt(16)
	v_add_u32_e32 v25, s20, v23
	ds_read_b128 v[26:29], v25
	ds_read_b128 v[30:33], v25 offset:8192
	ds_read_b128 v[34:37], v25 offset:16384
	ds_read_b128 v[38:41], v25 offset:24576
	ds_read_b128 v[42:45], v25 offset:32768
	ds_read_b128 v[46:49], v25 offset:40960
	ds_read_b128 v[50:53], v25 offset:49152
	ds_read_b128 v[54:57], v25 offset:57344
	v_add_u32_e32 v25, 0x10000, v25
	ds_read_b128 v[58:61], v25
	s_waitcnt lgkmcnt(6)
	v_mov_b32_e32 v70, v34
	v_mov_b32_e32 v71, v30
	v_mov_b32_e32 v72, v26
	s_waitcnt lgkmcnt(5)
	v_mov_b32_e32 v73, v38
	s_waitcnt lgkmcnt(4)
	v_mov_b32_e32 v74, v42
	s_waitcnt lgkmcnt(3)
	v_mov_b32_e32 v75, v46
	s_waitcnt lgkmcnt(2)
	v_mov_b32_e32 v76, v50
	s_waitcnt lgkmcnt(1)
	v_mov_b32_e32 v77, v54
	v_mov_b32_e32 v30, v35
	v_mov_b32_e32 v38, v27
	v_mov_b32_e32 v46, v43
	v_mov_b32_e32 v54, v51
	v_mov_b32_e32 v26, v36
	v_mov_b32_e32 v27, v32
	v_mov_b32_e32 v34, v28
	v_mov_b32_e32 v35, v40
	v_mov_b32_e32 v42, v44
	v_mov_b32_e32 v43, v48
	v_mov_b32_e32 v50, v52
	v_mov_b32_e32 v51, v56
	s_add_i32 s20, s20, 16
	v_mov_b32_e32 v32, v37
	v_mov_b32_e32 v40, v29
	v_mov_b32_e32 v48, v45
	v_mov_b32_e32 v56, v53
	v_pk_fma_f32 v[12:13], v[190:191], v[70:71], v[12:13] op_sel_hi:[0,1,1]
	v_pk_fma_f32 v[14:15], v[190:191], v[72:73], v[14:15] op_sel_hi:[0,1,1]
	v_pk_fma_f32 v[16:17], v[190:191], v[74:75], v[16:17] op_sel_hi:[0,1,1]
	v_pk_fma_f32 v[18:19], v[190:191], v[76:77], v[18:19] op_sel_hi:[0,1,1]
	s_waitcnt lgkmcnt(0)
	v_fmac_f32_e32 v8, v190, v58
	v_pk_fma_f32 v[12:13], v[192:193], v[30:31], v[12:13] op_sel_hi:[0,1,1]
	v_pk_fma_f32 v[14:15], v[192:193], v[38:39], v[14:15] op_sel_hi:[0,1,1]
	v_pk_fma_f32 v[16:17], v[192:193], v[46:47], v[16:17] op_sel_hi:[0,1,1]
	v_pk_fma_f32 v[18:19], v[192:193], v[54:55], v[18:19] op_sel_hi:[0,1,1]
	v_fmac_f32_e32 v8, v192, v59
	v_pk_fma_f32 v[12:13], v[194:195], v[26:27], v[12:13] op_sel_hi:[0,1,1]
	v_pk_fma_f32 v[14:15], v[194:195], v[34:35], v[14:15] op_sel_hi:[0,1,1]
	v_pk_fma_f32 v[16:17], v[194:195], v[42:43], v[16:17] op_sel_hi:[0,1,1]
	v_pk_fma_f32 v[18:19], v[194:195], v[50:51], v[18:19] op_sel_hi:[0,1,1]
	v_fmac_f32_e32 v8, v194, v60
	v_pk_fma_f32 v[12:13], v[196:197], v[32:33], v[12:13] op_sel_hi:[0,1,1]
	v_pk_fma_f32 v[14:15], v[196:197], v[40:41], v[14:15] op_sel_hi:[0,1,1]
	v_pk_fma_f32 v[16:17], v[196:197], v[48:49], v[16:17] op_sel_hi:[0,1,1]
	v_pk_fma_f32 v[18:19], v[196:197], v[56:57], v[18:19] op_sel_hi:[0,1,1]
	v_fmac_f32_e32 v8, v196, v61
	s_waitcnt vmcnt(12)
	v_add_u32_e32 v25, s20, v23
	ds_read_b128 v[26:29], v25
	ds_read_b128 v[30:33], v25 offset:8192
	ds_read_b128 v[34:37], v25 offset:16384
	ds_read_b128 v[38:41], v25 offset:24576
	ds_read_b128 v[42:45], v25 offset:32768
	ds_read_b128 v[46:49], v25 offset:40960
	ds_read_b128 v[50:53], v25 offset:49152
	ds_read_b128 v[54:57], v25 offset:57344
	v_add_u32_e32 v25, 0x10000, v25
	ds_read_b128 v[58:61], v25
	s_waitcnt lgkmcnt(6)
	v_mov_b32_e32 v70, v34
	v_mov_b32_e32 v71, v30
	v_mov_b32_e32 v72, v26
	s_waitcnt lgkmcnt(5)
	v_mov_b32_e32 v73, v38
	s_waitcnt lgkmcnt(4)
	v_mov_b32_e32 v74, v42
	s_waitcnt lgkmcnt(3)
	v_mov_b32_e32 v75, v46
	s_waitcnt lgkmcnt(2)
	v_mov_b32_e32 v76, v50
	s_waitcnt lgkmcnt(1)
	v_mov_b32_e32 v77, v54
	v_mov_b32_e32 v30, v35
	v_mov_b32_e32 v38, v27
	v_mov_b32_e32 v46, v43
	v_mov_b32_e32 v54, v51
	v_mov_b32_e32 v26, v36
	v_mov_b32_e32 v27, v32
	v_mov_b32_e32 v34, v28
	v_mov_b32_e32 v35, v40
	v_mov_b32_e32 v42, v44
	v_mov_b32_e32 v43, v48
	v_mov_b32_e32 v50, v52
	v_mov_b32_e32 v51, v56
	s_add_i32 s20, s20, 16
	v_mov_b32_e32 v32, v37
	v_mov_b32_e32 v40, v29
	v_mov_b32_e32 v48, v45
	v_mov_b32_e32 v56, v53
	v_pk_fma_f32 v[12:13], v[78:79], v[70:71], v[12:13] op_sel_hi:[0,1,1]
	v_pk_fma_f32 v[14:15], v[78:79], v[72:73], v[14:15] op_sel_hi:[0,1,1]
	v_pk_fma_f32 v[16:17], v[78:79], v[74:75], v[16:17] op_sel_hi:[0,1,1]
	v_pk_fma_f32 v[18:19], v[78:79], v[76:77], v[18:19] op_sel_hi:[0,1,1]
	s_waitcnt lgkmcnt(0)
	v_fmac_f32_e32 v8, v78, v58
	v_pk_fma_f32 v[12:13], v[80:81], v[30:31], v[12:13] op_sel_hi:[0,1,1]
	v_pk_fma_f32 v[14:15], v[80:81], v[38:39], v[14:15] op_sel_hi:[0,1,1]
	v_pk_fma_f32 v[16:17], v[80:81], v[46:47], v[16:17] op_sel_hi:[0,1,1]
	v_pk_fma_f32 v[18:19], v[80:81], v[54:55], v[18:19] op_sel_hi:[0,1,1]
	v_fmac_f32_e32 v8, v80, v59
	v_pk_fma_f32 v[12:13], v[82:83], v[26:27], v[12:13] op_sel_hi:[0,1,1]
	v_pk_fma_f32 v[14:15], v[82:83], v[34:35], v[14:15] op_sel_hi:[0,1,1]
	v_pk_fma_f32 v[16:17], v[82:83], v[42:43], v[16:17] op_sel_hi:[0,1,1]
	v_pk_fma_f32 v[18:19], v[82:83], v[50:51], v[18:19] op_sel_hi:[0,1,1]
	v_fmac_f32_e32 v8, v82, v60
	v_pk_fma_f32 v[12:13], v[84:85], v[32:33], v[12:13] op_sel_hi:[0,1,1]
	v_pk_fma_f32 v[14:15], v[84:85], v[40:41], v[14:15] op_sel_hi:[0,1,1]
	v_pk_fma_f32 v[16:17], v[84:85], v[48:49], v[16:17] op_sel_hi:[0,1,1]
	v_pk_fma_f32 v[18:19], v[84:85], v[56:57], v[18:19] op_sel_hi:[0,1,1]
	v_fmac_f32_e32 v8, v84, v61
	s_waitcnt vmcnt(8)
	v_add_u32_e32 v25, s20, v23
	ds_read_b128 v[26:29], v25
	ds_read_b128 v[30:33], v25 offset:8192
	ds_read_b128 v[34:37], v25 offset:16384
	ds_read_b128 v[38:41], v25 offset:24576
	ds_read_b128 v[42:45], v25 offset:32768
	ds_read_b128 v[46:49], v25 offset:40960
	ds_read_b128 v[50:53], v25 offset:49152
	ds_read_b128 v[54:57], v25 offset:57344
	v_add_u32_e32 v25, 0x10000, v25
	ds_read_b128 v[58:61], v25
	s_waitcnt lgkmcnt(6)
	v_mov_b32_e32 v70, v34
	v_mov_b32_e32 v71, v30
	v_mov_b32_e32 v72, v26
	s_waitcnt lgkmcnt(5)
	v_mov_b32_e32 v73, v38
	s_waitcnt lgkmcnt(4)
	v_mov_b32_e32 v74, v42
	s_waitcnt lgkmcnt(3)
	v_mov_b32_e32 v75, v46
	s_waitcnt lgkmcnt(2)
	v_mov_b32_e32 v76, v50
	s_waitcnt lgkmcnt(1)
	v_mov_b32_e32 v77, v54
	v_mov_b32_e32 v30, v35
	v_mov_b32_e32 v38, v27
	v_mov_b32_e32 v46, v43
	v_mov_b32_e32 v54, v51
	v_mov_b32_e32 v26, v36
	v_mov_b32_e32 v27, v32
	v_mov_b32_e32 v34, v28
	v_mov_b32_e32 v35, v40
	v_mov_b32_e32 v42, v44
	v_mov_b32_e32 v43, v48
	v_mov_b32_e32 v50, v52
	v_mov_b32_e32 v51, v56
	s_add_i32 s20, s20, 16
	v_mov_b32_e32 v32, v37
	v_mov_b32_e32 v40, v29
	v_mov_b32_e32 v48, v45
	v_mov_b32_e32 v56, v53
	v_pk_fma_f32 v[12:13], v[86:87], v[70:71], v[12:13] op_sel_hi:[0,1,1]
	v_pk_fma_f32 v[14:15], v[86:87], v[72:73], v[14:15] op_sel_hi:[0,1,1]
	v_pk_fma_f32 v[16:17], v[86:87], v[74:75], v[16:17] op_sel_hi:[0,1,1]
	v_pk_fma_f32 v[18:19], v[86:87], v[76:77], v[18:19] op_sel_hi:[0,1,1]
	s_waitcnt lgkmcnt(0)
	v_fmac_f32_e32 v8, v86, v58
	v_pk_fma_f32 v[12:13], v[88:89], v[30:31], v[12:13] op_sel_hi:[0,1,1]
	v_pk_fma_f32 v[14:15], v[88:89], v[38:39], v[14:15] op_sel_hi:[0,1,1]
	v_pk_fma_f32 v[16:17], v[88:89], v[46:47], v[16:17] op_sel_hi:[0,1,1]
	v_pk_fma_f32 v[18:19], v[88:89], v[54:55], v[18:19] op_sel_hi:[0,1,1]
	v_fmac_f32_e32 v8, v88, v59
	v_pk_fma_f32 v[12:13], v[90:91], v[26:27], v[12:13] op_sel_hi:[0,1,1]
	v_pk_fma_f32 v[14:15], v[90:91], v[34:35], v[14:15] op_sel_hi:[0,1,1]
	v_pk_fma_f32 v[16:17], v[90:91], v[42:43], v[16:17] op_sel_hi:[0,1,1]
	v_pk_fma_f32 v[18:19], v[90:91], v[50:51], v[18:19] op_sel_hi:[0,1,1]
	v_fmac_f32_e32 v8, v90, v60
	v_pk_fma_f32 v[12:13], v[92:93], v[32:33], v[12:13] op_sel_hi:[0,1,1]
	v_pk_fma_f32 v[14:15], v[92:93], v[40:41], v[14:15] op_sel_hi:[0,1,1]
	v_pk_fma_f32 v[16:17], v[92:93], v[48:49], v[16:17] op_sel_hi:[0,1,1]
	v_pk_fma_f32 v[18:19], v[92:93], v[56:57], v[18:19] op_sel_hi:[0,1,1]
	v_fmac_f32_e32 v8, v92, v61
	s_waitcnt vmcnt(4)
	v_add_u32_e32 v25, s20, v23
	ds_read_b128 v[26:29], v25
	ds_read_b128 v[30:33], v25 offset:8192
	ds_read_b128 v[34:37], v25 offset:16384
	ds_read_b128 v[38:41], v25 offset:24576
	ds_read_b128 v[42:45], v25 offset:32768
	ds_read_b128 v[46:49], v25 offset:40960
	ds_read_b128 v[50:53], v25 offset:49152
	ds_read_b128 v[54:57], v25 offset:57344
	v_add_u32_e32 v25, 0x10000, v25
	ds_read_b128 v[58:61], v25
	s_waitcnt lgkmcnt(6)
	v_mov_b32_e32 v70, v34
	v_mov_b32_e32 v71, v30
	v_mov_b32_e32 v72, v26
	s_waitcnt lgkmcnt(5)
	v_mov_b32_e32 v73, v38
	s_waitcnt lgkmcnt(4)
	v_mov_b32_e32 v74, v42
	s_waitcnt lgkmcnt(3)
	v_mov_b32_e32 v75, v46
	s_waitcnt lgkmcnt(2)
	v_mov_b32_e32 v76, v50
	s_waitcnt lgkmcnt(1)
	v_mov_b32_e32 v77, v54
	v_mov_b32_e32 v30, v35
	v_mov_b32_e32 v38, v27
	v_mov_b32_e32 v46, v43
	v_mov_b32_e32 v54, v51
	v_mov_b32_e32 v26, v36
	v_mov_b32_e32 v27, v32
	v_mov_b32_e32 v34, v28
	v_mov_b32_e32 v35, v40
	v_mov_b32_e32 v42, v44
	v_mov_b32_e32 v43, v48
	v_mov_b32_e32 v50, v52
	v_mov_b32_e32 v51, v56
	s_add_i32 s20, s20, 16
	v_mov_b32_e32 v32, v37
	v_mov_b32_e32 v40, v29
	v_mov_b32_e32 v48, v45
	v_mov_b32_e32 v56, v53
	v_pk_fma_f32 v[12:13], v[94:95], v[70:71], v[12:13] op_sel_hi:[0,1,1]
	v_pk_fma_f32 v[14:15], v[94:95], v[72:73], v[14:15] op_sel_hi:[0,1,1]
	v_pk_fma_f32 v[16:17], v[94:95], v[74:75], v[16:17] op_sel_hi:[0,1,1]
	v_pk_fma_f32 v[18:19], v[94:95], v[76:77], v[18:19] op_sel_hi:[0,1,1]
	s_waitcnt lgkmcnt(0)
	v_fmac_f32_e32 v8, v94, v58
	v_pk_fma_f32 v[12:13], v[96:97], v[30:31], v[12:13] op_sel_hi:[0,1,1]
	v_pk_fma_f32 v[14:15], v[96:97], v[38:39], v[14:15] op_sel_hi:[0,1,1]
	v_pk_fma_f32 v[16:17], v[96:97], v[46:47], v[16:17] op_sel_hi:[0,1,1]
	v_pk_fma_f32 v[18:19], v[96:97], v[54:55], v[18:19] op_sel_hi:[0,1,1]
	v_fmac_f32_e32 v8, v96, v59
	v_pk_fma_f32 v[12:13], v[98:99], v[26:27], v[12:13] op_sel_hi:[0,1,1]
	v_pk_fma_f32 v[14:15], v[98:99], v[34:35], v[14:15] op_sel_hi:[0,1,1]
	v_pk_fma_f32 v[16:17], v[98:99], v[42:43], v[16:17] op_sel_hi:[0,1,1]
	v_pk_fma_f32 v[18:19], v[98:99], v[50:51], v[18:19] op_sel_hi:[0,1,1]
	v_fmac_f32_e32 v8, v98, v60
	v_pk_fma_f32 v[12:13], v[100:101], v[32:33], v[12:13] op_sel_hi:[0,1,1]
	v_pk_fma_f32 v[14:15], v[100:101], v[40:41], v[14:15] op_sel_hi:[0,1,1]
	v_pk_fma_f32 v[16:17], v[100:101], v[48:49], v[16:17] op_sel_hi:[0,1,1]
	v_pk_fma_f32 v[18:19], v[100:101], v[56:57], v[18:19] op_sel_hi:[0,1,1]
	v_fmac_f32_e32 v8, v100, v61
	s_waitcnt vmcnt(0)
	v_add_u32_e32 v25, s20, v23
	ds_read_b128 v[26:29], v25
	ds_read_b128 v[30:33], v25 offset:8192
	ds_read_b128 v[34:37], v25 offset:16384
	ds_read_b128 v[38:41], v25 offset:24576
	ds_read_b128 v[42:45], v25 offset:32768
	ds_read_b128 v[46:49], v25 offset:40960
	ds_read_b128 v[50:53], v25 offset:49152
	ds_read_b128 v[54:57], v25 offset:57344
	v_add_u32_e32 v25, 0x10000, v25
	ds_read_b128 v[58:61], v25
	s_waitcnt lgkmcnt(6)
	v_mov_b32_e32 v70, v34
	v_mov_b32_e32 v71, v30
	v_mov_b32_e32 v72, v26
	s_waitcnt lgkmcnt(5)
	v_mov_b32_e32 v73, v38
	s_waitcnt lgkmcnt(4)
	v_mov_b32_e32 v74, v42
	s_waitcnt lgkmcnt(3)
	v_mov_b32_e32 v75, v46
	s_waitcnt lgkmcnt(2)
	v_mov_b32_e32 v76, v50
	s_waitcnt lgkmcnt(1)
	v_mov_b32_e32 v77, v54
	v_mov_b32_e32 v30, v35
	v_mov_b32_e32 v38, v27
	v_mov_b32_e32 v46, v43
	v_mov_b32_e32 v54, v51
	v_mov_b32_e32 v26, v36
	v_mov_b32_e32 v27, v32
	v_mov_b32_e32 v34, v28
	v_mov_b32_e32 v35, v40
	v_mov_b32_e32 v42, v44
	v_mov_b32_e32 v43, v48
	v_mov_b32_e32 v50, v52
	v_mov_b32_e32 v51, v56
	s_add_i32 s20, s20, 16
	v_mov_b32_e32 v32, v37
	v_mov_b32_e32 v40, v29
	v_mov_b32_e32 v48, v45
	v_mov_b32_e32 v56, v53
	v_pk_fma_f32 v[12:13], v[102:103], v[70:71], v[12:13] op_sel_hi:[0,1,1]
	v_pk_fma_f32 v[14:15], v[102:103], v[72:73], v[14:15] op_sel_hi:[0,1,1]
	v_pk_fma_f32 v[16:17], v[102:103], v[74:75], v[16:17] op_sel_hi:[0,1,1]
	v_pk_fma_f32 v[18:19], v[102:103], v[76:77], v[18:19] op_sel_hi:[0,1,1]
	s_waitcnt lgkmcnt(0)
	v_fmac_f32_e32 v8, v102, v58
	v_pk_fma_f32 v[12:13], v[104:105], v[30:31], v[12:13] op_sel_hi:[0,1,1]
	v_pk_fma_f32 v[14:15], v[104:105], v[38:39], v[14:15] op_sel_hi:[0,1,1]
	v_pk_fma_f32 v[16:17], v[104:105], v[46:47], v[16:17] op_sel_hi:[0,1,1]
	v_pk_fma_f32 v[18:19], v[104:105], v[54:55], v[18:19] op_sel_hi:[0,1,1]
	v_fmac_f32_e32 v8, v104, v59
	v_pk_fma_f32 v[12:13], v[106:107], v[26:27], v[12:13] op_sel_hi:[0,1,1]
	v_pk_fma_f32 v[14:15], v[106:107], v[34:35], v[14:15] op_sel_hi:[0,1,1]
	v_pk_fma_f32 v[16:17], v[106:107], v[42:43], v[16:17] op_sel_hi:[0,1,1]
	v_pk_fma_f32 v[18:19], v[106:107], v[50:51], v[18:19] op_sel_hi:[0,1,1]
	v_fmac_f32_e32 v8, v106, v60
	v_pk_fma_f32 v[12:13], v[108:109], v[32:33], v[12:13] op_sel_hi:[0,1,1]
	v_pk_fma_f32 v[14:15], v[108:109], v[40:41], v[14:15] op_sel_hi:[0,1,1]
	v_pk_fma_f32 v[16:17], v[108:109], v[48:49], v[16:17] op_sel_hi:[0,1,1]
	v_pk_fma_f32 v[18:19], v[108:109], v[56:57], v[18:19] op_sel_hi:[0,1,1]
	v_fmac_f32_e32 v8, v108, v61
	ds_write2st64_b32 v24, v14, v13 offset1:1
	ds_write2st64_b32 v24, v12, v15 offset0:2 offset1:3
	ds_write2st64_b32 v24, v16, v17 offset0:4 offset1:5
	ds_write2st64_b32 v24, v18, v19 offset0:6 offset1:7
	ds_write_b32 v24, v8 offset:2048
	s_waitcnt lgkmcnt(0)
	s_barrier
	s_and_saveexec_b64 s[6:7], s[4:5]
	s_cbranch_execz .LBB0_10
	s_mul_i32 s20, s19, 0x1800
	s_add_i32 s20, s20, s22
	v_or_b32_e32 v10, s20, v20
	v_ashrrev_i32_e32 v11, 31, v10
	s_mul_i32 s19, s19, 9
	v_lshl_add_u64 v[10:11], v[10:11], 2, s[72:73]
	v_or_b32_e32 v8, s22, v20
	s_mov_b64 s[22:23], 0
	v_mov_b32_e32 v12, v2
